# speedup vs baseline: 1.0268x; 1.0037x over previous
; DEV bf16_t f2bf(float f) { unsigned u = __float_as_uint(f); u += 0x7fffu + ((u >> 16) & 1u); return (bf16_t)(u >> 16); }
; DEV int lv(int x) { asm volatile("" : "+v"(x)); return x; }
; DEV int crow(int r, int hi) { return (r & 3) + 8 * (r >> 2) + 4 * hi; }
; template <bool SPREAD>
; DEV void attn_store(f32x16 (&o)[4], const float* __restrict__ gain, float oscale, bf16_t* __restrict__ mix, int q0, int colbase) {
;   const int tid = lv(threadIdx.x), wid = tid >> 6, lane = tid & 63, r32 = lane & 31, hi = lane >> 5;
;   unsigned char* sc = shm_raw + wid * 8704;
;   float gn[4];
; #pragma unroll
;   for (int d = 0; d < 4; ++d) gn[d] = gain[d * 32 + r32] * oscale;
; #pragma unroll
;   for (int r = 0; r < 16; ++r) {
;     float ss = o[0][r] * o[0][r] + o[1][r] * o[1][r] + o[2][r] * o[2][r] + o[3][r] * o[3][r];
;     ss += __shfl_xor(ss, 1); ss += __shfl_xor(ss, 2); ss += __shfl_xor(ss, 4); ss += __shfl_xor(ss, 8); ss += __shfl_xor(ss, 16);
;     const float rn = rsqrtf(ss * (1.f / 128.f) + EPS);
;     const int cr = crow(r, hi);
; #pragma unroll
;     for (int d = 0; d < 4; ++d) *reinterpret_cast<bf16_t*>(sc + cr * 272 + (d * 32 + r32) * 2) = f2bf(o[d][r] * rn * gn[d]);
;   }
.LBB0_366:
	v_mov_b32_e32 v66, v210
	s_xor_b64 s[8:9], s[0:1], -1
	s_barrier
	s_movk_i32 s0, 0x2200
	v_ashrrev_i32_e32 v67, 6, v66
	v_and_b32_e32 v64, 31, v66
	v_mul_lo_u32 v65, v67, s0
	v_readlane_b32 s0, v255, 59
	v_lshlrev_b32_e32 v68, 2, v64
	v_readlane_b32 s1, v255, 60
	s_nop 4
	global_load_dword v72, v68, s[0:1]
	global_load_dword v71, v68, s[0:1] offset:128
	global_load_dword v70, v68, s[0:1] offset:256
	global_load_dword v69, v68, s[0:1] offset:384
	v_add_u32_e32 v68, 0, v65
	v_lshrrev_b32_e32 v65, 3, v66
	v_and_b32_e32 v73, 4, v65
	v_lshlrev_b32_e32 v76, 1, v64
	v_mul_u32_u24_e32 v73, 0x110, v73
	v_mov_b32_e32 v64, v32
	v_mov_b32_e32 v65, v48
	v_add3_u32 v73, v68, v76, v73
	v_mov_b32_e32 v76, v33
	v_mov_b32_e32 v77, v49
	v_pk_mul_f32 v[64:65], v[64:65], v[64:65]
	v_mov_b32_e32 v74, v16
	v_mov_b32_e32 v75, v0
	v_pk_mul_f32 v[76:77], v[76:77], v[76:77]
	v_mov_b32_e32 v78, v17
	v_mov_b32_e32 v79, v1
	v_pk_mul_f32 v[74:75], v[74:75], v[74:75]
	v_pk_mul_f32 v[78:79], v[78:79], v[78:79]
	v_mov_b32_e32 v80, v76
	v_mov_b32_e32 v81, v64
	v_mov_b32_e32 v64, v77
	v_pk_add_f32 v[64:65], v[80:81], v[64:65]
	v_mov_b32_e32 v76, v79
	v_mov_b32_e32 v77, v75
	v_pk_add_f32 v[64:65], v[76:77], v[64:65]
	v_mov_b32_e32 v79, v74
	v_pk_add_f32 v[64:65], v[78:79], v[64:65]
	ds_bpermute_b32 v75, v221, v65
	ds_bpermute_b32 v74, v221, v64
	s_mov_b32 s0, 0x358637bd
	s_brev_b32 s4, 60
	s_add_i32 s16, 0, 0x18000
	s_add_i32 s15, 0, 0x10000
	s_waitcnt lgkmcnt(0)
	v_pk_add_f32 v[64:65], v[64:65], v[74:75]
	ds_bpermute_b32 v75, v220, v65
	ds_bpermute_b32 v74, v220, v64
	s_add_i32 s14, s75, 4
	s_waitcnt lgkmcnt(0)
	v_pk_add_f32 v[64:65], v[64:65], v[74:75]
	ds_bpermute_b32 v75, v219, v65
	ds_bpermute_b32 v74, v219, v64
	s_waitcnt lgkmcnt(0)
	v_pk_add_f32 v[64:65], v[64:65], v[74:75]
	ds_bpermute_b32 v75, v218, v65
	ds_bpermute_b32 v74, v218, v64
	s_waitcnt lgkmcnt(0)
	v_pk_add_f32 v[64:65], v[64:65], v[74:75]
	ds_bpermute_b32 v75, v217, v65
	ds_bpermute_b32 v74, v217, v64
	s_waitcnt lgkmcnt(0)
	v_pk_add_f32 v[74:75], v[64:65], v[74:75]
	v_mov_b64_e32 v[64:65], s[0:1]
	v_pk_fma_f32 v[74:75], v[74:75], s[4:5], v[64:65] op_sel_hi:[1,0,0]
	s_nop 0
	v_mul_f32_e32 v76, 0x4b800000, v75
	v_cmp_gt_f32_e64 s[0:1], s33, v75
	v_cmp_gt_f32_e32 vcc, s33, v74
	s_nop 0
	v_cndmask_b32_e64 v75, v75, v76, s[0:1]
	v_rsq_f32_e32 v75, v75
	s_nop 0
	v_mul_f32_e32 v76, 0x45800000, v75
	v_cndmask_b32_e64 v75, v75, v76, s[0:1]
	v_mul_f32_e32 v48, v48, v75
	s_waitcnt vmcnt(3)
	v_mul_f32_e32 v48, v72, v48
	v_bfe_u32 v76, v48, 16, 1
	v_mul_f32_e32 v32, v32, v75
	v_add3_u32 v48, v48, v76, s2
	s_waitcnt vmcnt(2)
	v_mul_f32_e32 v32, v71, v32
	ds_write_b16_d16_hi v73, v48
	v_bfe_u32 v48, v32, 16, 1
	v_mul_f32_e32 v0, v0, v75
	v_add3_u32 v32, v32, v48, s2
	s_waitcnt vmcnt(1)
	v_mul_f32_e32 v0, v70, v0
	ds_write_b16_d16_hi v73, v32 offset:64
	v_bfe_u32 v32, v0, 16, 1
	v_add3_u32 v0, v0, v32, s2
	ds_write_b16_d16_hi v73, v0 offset:128
	v_mul_f32_e32 v0, v16, v75
	s_waitcnt vmcnt(0)
	v_mul_f32_e32 v0, v69, v0
	v_bfe_u32 v16, v0, 16, 1
	v_add3_u32 v0, v0, v16, s2
	ds_write_b16_d16_hi v73, v0 offset:192
	v_mul_f32_e32 v0, 0x4b800000, v74
	v_cndmask_b32_e32 v0, v74, v0, vcc
	v_rsq_f32_e32 v0, v0
	v_mov_b32_e32 v48, v19
	v_mul_f32_e32 v16, 0x45800000, v0
	v_cndmask_b32_e32 v0, v0, v16, vcc
	v_mul_f32_e32 v16, v49, v0
	v_mul_f32_e32 v16, v72, v16
	v_bfe_u32 v32, v16, 16, 1
	v_add3_u32 v16, v16, v32, s2
	ds_write_b16_d16_hi v73, v16 offset:272
	v_mul_f32_e32 v16, v33, v0
	v_mul_f32_e32 v16, v71, v16
	v_bfe_u32 v32, v16, 16, 1
	v_mul_f32_e32 v1, v1, v0
	v_add3_u32 v16, v16, v32, s2
	v_mul_f32_e32 v1, v70, v1
	ds_write_b16_d16_hi v73, v16 offset:336
	v_bfe_u32 v16, v1, 16, 1
	v_mul_f32_e32 v0, v17, v0
	v_add3_u32 v1, v1, v16, s2
	v_mul_f32_e32 v0, v69, v0
	ds_write_b16_d16_hi v73, v1 offset:400
	v_bfe_u32 v1, v0, 16, 1
	v_add3_u32 v0, v0, v1, s2
	ds_write_b16_d16_hi v73, v0 offset:464
	v_mov_b32_e32 v0, v34
	v_mov_b32_e32 v1, v50
	v_mov_b32_e32 v32, v35
	v_mov_b32_e32 v33, v51
	v_pk_mul_f32 v[0:1], v[0:1], v[0:1]
	v_mov_b32_e32 v16, v18
	v_mov_b32_e32 v17, v2
	v_pk_mul_f32 v[32:33], v[32:33], v[32:33]
	v_mov_b32_e32 v49, v3
	v_pk_mul_f32 v[16:17], v[16:17], v[16:17]
	v_pk_mul_f32 v[48:49], v[48:49], v[48:49]
	v_mov_b32_e32 v74, v32
	v_mov_b32_e32 v75, v0
	v_mov_b32_e32 v0, v33
	v_pk_add_f32 v[0:1], v[74:75], v[0:1]
	v_mov_b32_e32 v32, v49
	v_mov_b32_e32 v33, v17
	v_pk_add_f32 v[0:1], v[32:33], v[0:1]
	v_mov_b32_e32 v49, v16
	v_pk_add_f32 v[0:1], v[48:49], v[0:1]
	ds_bpermute_b32 v17, v221, v1
	ds_bpermute_b32 v16, v221, v0
	s_waitcnt lgkmcnt(0)
	v_pk_add_f32 v[0:1], v[0:1], v[16:17]
	ds_bpermute_b32 v17, v220, v1
	ds_bpermute_b32 v16, v220, v0
	s_waitcnt lgkmcnt(0)
	v_pk_add_f32 v[0:1], v[0:1], v[16:17]
	ds_bpermute_b32 v17, v219, v1
	ds_bpermute_b32 v16, v219, v0
	s_waitcnt lgkmcnt(0)
	v_pk_add_f32 v[0:1], v[0:1], v[16:17]
	ds_bpermute_b32 v17, v218, v1
	ds_bpermute_b32 v16, v218, v0
	s_waitcnt lgkmcnt(0)
	v_pk_add_f32 v[0:1], v[0:1], v[16:17]
	ds_bpermute_b32 v17, v217, v1
	ds_bpermute_b32 v16, v217, v0
	s_waitcnt lgkmcnt(0)
; DEV bf16_t f2bf(float f) { unsigned u = __float_as_uint(f); u += 0x7fffu + ((u >> 16) & 1u); return (bf16_t)(u >> 16); }
; DEV int crow(int r, int hi) { return (r & 3) + 8 * (r >> 2) + 4 * hi; }
; template <bool SPREAD>
; DEV void attn_store(f32x16 (&o)[4], const float* __restrict__ gain, float oscale, bf16_t* __restrict__ mix, int q0, int colbase) {
;     ...
;   for (int r = 0; r < 16; ++r) {
;     float ss = o[0][r] * o[0][r] + o[1][r] * o[1][r] + o[2][r] * o[2][r] + o[3][r] * o[3][r];
;     ss += __shfl_xor(ss, 1); ss += __shfl_xor(ss, 2); ss += __shfl_xor(ss, 4); ss += __shfl_xor(ss, 8); ss += __shfl_xor(ss, 16);
;     const float rn = rsqrtf(ss * (1.f / 128.f) + EPS);
;     const int cr = crow(r, hi);
; #pragma unroll
;     for (int d = 0; d < 4; ++d) *reinterpret_cast<bf16_t*>(sc + cr * 272 + (d * 32 + r32) * 2) = f2bf(o[d][r] * rn * gn[d]);
;   }
	v_pk_add_f32 v[0:1], v[0:1], v[16:17]
	s_nop 0
	v_pk_fma_f32 v[0:1], v[0:1], s[4:5], v[64:65] op_sel_hi:[1,0,0]
	s_nop 0
	v_mul_f32_e32 v16, 0x4b800000, v1
	v_cmp_gt_f32_e64 s[0:1], s33, v1
	v_cmp_gt_f32_e32 vcc, s33, v0
	s_nop 0
	v_cndmask_b32_e64 v1, v1, v16, s[0:1]
	v_rsq_f32_e32 v1, v1
	s_nop 0
	v_mul_f32_e32 v16, 0x45800000, v1
	v_cndmask_b32_e64 v1, v1, v16, s[0:1]
	v_mul_f32_e32 v16, v50, v1
	v_mul_f32_e32 v16, v72, v16
	v_bfe_u32 v17, v16, 16, 1
	v_add3_u32 v16, v16, v17, s2
	ds_write_b16_d16_hi v73, v16 offset:544
	v_mul_f32_e32 v16, v34, v1
	v_mul_f32_e32 v16, v71, v16
	v_bfe_u32 v17, v16, 16, 1
	v_mul_f32_e32 v2, v2, v1
	v_add3_u32 v16, v16, v17, s2
	v_mul_f32_e32 v2, v70, v2
	ds_write_b16_d16_hi v73, v16 offset:608
	v_bfe_u32 v16, v2, 16, 1
	v_mul_f32_e32 v1, v18, v1
	v_add3_u32 v2, v2, v16, s2
	v_mul_f32_e32 v1, v69, v1
	ds_write_b16_d16_hi v73, v2 offset:672
	v_bfe_u32 v2, v1, 16, 1
	v_add3_u32 v1, v1, v2, s2
	ds_write_b16_d16_hi v73, v1 offset:736
	v_mul_f32_e32 v1, 0x4b800000, v0
	v_cndmask_b32_e32 v0, v0, v1, vcc
	v_rsq_f32_e32 v0, v0
	v_mov_b32_e32 v16, v37
	v_mov_b32_e32 v17, v53
	v_pk_mul_f32 v[16:17], v[16:17], v[16:17]
	v_mul_f32_e32 v1, 0x45800000, v0
	v_cndmask_b32_e32 v0, v0, v1, vcc
	v_mul_f32_e32 v1, v51, v0
	v_mul_f32_e32 v1, v72, v1
	v_bfe_u32 v2, v1, 16, 1
	v_add3_u32 v1, v1, v2, s2
	ds_write_b16_d16_hi v73, v1 offset:816
	v_mul_f32_e32 v1, v35, v0
	v_mul_f32_e32 v1, v71, v1
	v_bfe_u32 v2, v1, 16, 1
	v_add3_u32 v1, v1, v2, s2
	ds_write_b16_d16_hi v73, v1 offset:880
	v_mul_f32_e32 v1, v3, v0
	v_mul_f32_e32 v1, v70, v1
	v_bfe_u32 v2, v1, 16, 1
	v_mul_f32_e32 v0, v19, v0
	v_add3_u32 v1, v1, v2, s2
	v_mul_f32_e32 v0, v69, v0
	ds_write_b16_d16_hi v73, v1 offset:944
	v_bfe_u32 v1, v0, 16, 1
	v_add3_u32 v0, v0, v1, s2
	ds_write_b16_d16_hi v73, v0 offset:1008
	v_mov_b32_e32 v0, v36
	v_mov_b32_e32 v1, v52
	v_pk_mul_f32 v[0:1], v[0:1], v[0:1]
	v_mov_b32_e32 v2, v20
	v_mov_b32_e32 v3, v4
	v_mov_b32_e32 v18, v21
	v_mov_b32_e32 v19, v5
	v_pk_mul_f32 v[2:3], v[2:3], v[2:3]
	v_pk_mul_f32 v[18:19], v[18:19], v[18:19]
	v_mov_b32_e32 v32, v16
	v_mov_b32_e32 v33, v0
	v_mov_b32_e32 v0, v17
	v_pk_add_f32 v[0:1], v[32:33], v[0:1]
	v_mov_b32_e32 v16, v19
	v_mov_b32_e32 v17, v3
	v_pk_add_f32 v[0:1], v[16:17], v[0:1]
	v_mov_b32_e32 v19, v2
	v_pk_add_f32 v[0:1], v[18:19], v[0:1]
	ds_bpermute_b32 v3, v221, v1
	ds_bpermute_b32 v2, v221, v0
	v_mov_b32_e32 v16, v23
	v_mov_b32_e32 v17, v7
	v_pk_mul_f32 v[16:17], v[16:17], v[16:17]
	s_waitcnt lgkmcnt(0)
	v_pk_add_f32 v[0:1], v[0:1], v[2:3]
	ds_bpermute_b32 v3, v220, v1
	ds_bpermute_b32 v2, v220, v0
	s_waitcnt lgkmcnt(0)
	v_pk_add_f32 v[0:1], v[0:1], v[2:3]
	ds_bpermute_b32 v3, v219, v1
	ds_bpermute_b32 v2, v219, v0
	s_waitcnt lgkmcnt(0)
	v_pk_add_f32 v[0:1], v[0:1], v[2:3]
	ds_bpermute_b32 v3, v218, v1
	ds_bpermute_b32 v2, v218, v0
	s_waitcnt lgkmcnt(0)
	v_pk_add_f32 v[0:1], v[0:1], v[2:3]
	ds_bpermute_b32 v3, v217, v1
	ds_bpermute_b32 v2, v217, v0
	s_waitcnt lgkmcnt(0)
	v_pk_add_f32 v[0:1], v[0:1], v[2:3]
	s_nop 0
	v_pk_fma_f32 v[0:1], v[0:1], s[4:5], v[64:65] op_sel_hi:[1,0,0]
	s_nop 0
	v_mul_f32_e32 v2, 0x4b800000, v1
	v_cmp_gt_f32_e64 s[0:1], s33, v1
	v_cmp_gt_f32_e32 vcc, s33, v0
	s_nop 0
	v_cndmask_b32_e64 v1, v1, v2, s[0:1]
	v_rsq_f32_e32 v1, v1
	s_nop 0
	v_mul_f32_e32 v2, 0x45800000, v1
	v_cndmask_b32_e64 v1, v1, v2, s[0:1]
	v_mul_f32_e32 v2, v52, v1
	v_mul_f32_e32 v2, v72, v2
	v_bfe_u32 v3, v2, 16, 1
	v_add3_u32 v2, v2, v3, s2
	ds_write_b16_d16_hi v73, v2 offset:2176
	v_mul_f32_e32 v2, v36, v1
	v_mul_f32_e32 v2, v71, v2
	v_bfe_u32 v3, v2, 16, 1
	v_add3_u32 v2, v2, v3, s2
	ds_write_b16_d16_hi v73, v2 offset:2240
	v_mul_f32_e32 v2, v4, v1
	v_mul_f32_e32 v2, v70, v2
	v_bfe_u32 v3, v2, 16, 1
	v_mul_f32_e32 v1, v20, v1
	v_add3_u32 v2, v2, v3, s2
	v_mul_f32_e32 v1, v69, v1
	ds_write_b16_d16_hi v73, v2 offset:2304
	v_bfe_u32 v2, v1, 16, 1
	v_add3_u32 v1, v1, v2, s2
	ds_write_b16_d16_hi v73, v1 offset:2368
	v_mul_f32_e32 v1, 0x4b800000, v0
	v_cndmask_b32_e32 v0, v0, v1, vcc
	v_rsq_f32_e32 v0, v0
	v_mov_b32_e32 v4, v39
	v_mov_b32_e32 v3, v6
	v_mul_f32_e32 v1, 0x45800000, v0
	v_cndmask_b32_e32 v0, v0, v1, vcc
	v_mul_f32_e32 v1, v53, v0
	v_mul_f32_e32 v1, v72, v1
	v_bfe_u32 v2, v1, 16, 1
	v_add3_u32 v1, v1, v2, s2
	ds_write_b16_d16_hi v73, v1 offset:2448
	v_mul_f32_e32 v1, v37, v0
	v_mul_f32_e32 v1, v71, v1
	v_bfe_u32 v2, v1, 16, 1
	v_add3_u32 v1, v1, v2, s2
	ds_write_b16_d16_hi v73, v1 offset:2512
	v_mul_f32_e32 v1, v5, v0
	v_mul_f32_e32 v1, v70, v1
	v_bfe_u32 v2, v1, 16, 1
	v_mul_f32_e32 v0, v21, v0
	v_add3_u32 v1, v1, v2, s2
	v_mul_f32_e32 v0, v69, v0
	ds_write_b16_d16_hi v73, v1 offset:2576
	v_bfe_u32 v1, v0, 16, 1
	v_add3_u32 v0, v0, v1, s2
	ds_write_b16_d16_hi v73, v0 offset:2640
	v_mov_b32_e32 v0, v38
	v_mov_b32_e32 v1, v54
	v_mov_b32_e32 v5, v55
	v_pk_mul_f32 v[0:1], v[0:1], v[0:1]
	v_mov_b32_e32 v2, v22
	v_pk_mul_f32 v[4:5], v[4:5], v[4:5]
	v_pk_mul_f32 v[2:3], v[2:3], v[2:3]
	v_mov_b32_e32 v18, v4
	v_mov_b32_e32 v19, v0
	v_mov_b32_e32 v0, v5
	v_pk_add_f32 v[0:1], v[18:19], v[0:1]
	v_mov_b32_e32 v4, v17
	v_mov_b32_e32 v5, v3
	v_pk_add_f32 v[0:1], v[4:5], v[0:1]
	v_mov_b32_e32 v17, v2
	v_pk_add_f32 v[0:1], v[16:17], v[0:1]
	ds_bpermute_b32 v3, v221, v1
	ds_bpermute_b32 v2, v221, v0
	v_mov_b32_e32 v4, v41
	v_mov_b32_e32 v5, v57
	v_pk_mul_f32 v[4:5], v[4:5], v[4:5]
	s_waitcnt lgkmcnt(0)
	v_pk_add_f32 v[0:1], v[0:1], v[2:3]
	ds_bpermute_b32 v3, v220, v1
	ds_bpermute_b32 v2, v220, v0
	v_mov_b32_e32 v16, v4
	s_waitcnt lgkmcnt(0)
	v_pk_add_f32 v[0:1], v[0:1], v[2:3]
	ds_bpermute_b32 v3, v219, v1
	ds_bpermute_b32 v2, v219, v0
	s_waitcnt lgkmcnt(0)
; DEV bf16_t f2bf(float f) { unsigned u = __float_as_uint(f); u += 0x7fffu + ((u >> 16) & 1u); return (bf16_t)(u >> 16); }
; DEV int crow(int r, int hi) { return (r & 3) + 8 * (r >> 2) + 4 * hi; }
; template <bool SPREAD>
; DEV void attn_store(f32x16 (&o)[4], const float* __restrict__ gain, float oscale, bf16_t* __restrict__ mix, int q0, int colbase) {
;     ...
;   for (int r = 0; r < 16; ++r) {
;     float ss = o[0][r] * o[0][r] + o[1][r] * o[1][r] + o[2][r] * o[2][r] + o[3][r] * o[3][r];
;     ss += __shfl_xor(ss, 1); ss += __shfl_xor(ss, 2); ss += __shfl_xor(ss, 4); ss += __shfl_xor(ss, 8); ss += __shfl_xor(ss, 16);
;     const float rn = rsqrtf(ss * (1.f / 128.f) + EPS);
;     const int cr = crow(r, hi);
; #pragma unroll
;     for (int d = 0; d < 4; ++d) *reinterpret_cast<bf16_t*>(sc + cr * 272 + (d * 32 + r32) * 2) = f2bf(o[d][r] * rn * gn[d]);
;   }
	v_pk_add_f32 v[0:1], v[0:1], v[2:3]
	ds_bpermute_b32 v3, v218, v1
	ds_bpermute_b32 v2, v218, v0
	s_waitcnt lgkmcnt(0)
	v_pk_add_f32 v[0:1], v[0:1], v[2:3]
	ds_bpermute_b32 v3, v217, v1
	ds_bpermute_b32 v2, v217, v0
	s_waitcnt lgkmcnt(0)
	v_pk_add_f32 v[0:1], v[0:1], v[2:3]
	s_nop 0
	v_pk_fma_f32 v[0:1], v[0:1], s[4:5], v[64:65] op_sel_hi:[1,0,0]
	s_nop 0
	v_mul_f32_e32 v2, 0x4b800000, v1
	v_cmp_gt_f32_e64 s[0:1], s33, v1
	v_cmp_gt_f32_e32 vcc, s33, v0
	s_nop 0
	v_cndmask_b32_e64 v1, v1, v2, s[0:1]
	v_rsq_f32_e32 v1, v1
	s_nop 0
	v_mul_f32_e32 v2, 0x45800000, v1
	v_cndmask_b32_e64 v1, v1, v2, s[0:1]
	v_mul_f32_e32 v2, v54, v1
	v_mul_f32_e32 v2, v72, v2
	v_bfe_u32 v3, v2, 16, 1
	v_add3_u32 v2, v2, v3, s2
	ds_write_b16_d16_hi v73, v2 offset:2720
	v_mul_f32_e32 v2, v38, v1
	v_mul_f32_e32 v2, v71, v2
	v_bfe_u32 v3, v2, 16, 1
	v_add3_u32 v2, v2, v3, s2
	ds_write_b16_d16_hi v73, v2 offset:2784
	v_mul_f32_e32 v2, v6, v1
	v_mul_f32_e32 v2, v70, v2
	v_bfe_u32 v3, v2, 16, 1
	v_mul_f32_e32 v1, v22, v1
	v_add3_u32 v2, v2, v3, s2
	v_mul_f32_e32 v1, v69, v1
	ds_write_b16_d16_hi v73, v2 offset:2848
	v_bfe_u32 v2, v1, 16, 1
	v_add3_u32 v1, v1, v2, s2
	ds_write_b16_d16_hi v73, v1 offset:2912
	v_mul_f32_e32 v1, 0x4b800000, v0
	v_cndmask_b32_e32 v0, v0, v1, vcc
	v_rsq_f32_e32 v0, v0
	v_mov_b32_e32 v3, v8
	v_mov_b32_e32 v6, v25
	v_mul_f32_e32 v1, 0x45800000, v0
	v_cndmask_b32_e32 v0, v0, v1, vcc
	v_mul_f32_e32 v1, v55, v0
	v_mul_f32_e32 v1, v72, v1
	v_bfe_u32 v2, v1, 16, 1
	v_add3_u32 v1, v1, v2, s2
	ds_write_b16_d16_hi v73, v1 offset:2992
	v_mul_f32_e32 v1, v39, v0
	v_mul_f32_e32 v1, v71, v1
	v_bfe_u32 v2, v1, 16, 1
	v_add3_u32 v1, v1, v2, s2
	ds_write_b16_d16_hi v73, v1 offset:3056
	v_mul_f32_e32 v1, v7, v0
	v_mul_f32_e32 v1, v70, v1
	v_bfe_u32 v2, v1, 16, 1
	v_mul_f32_e32 v0, v23, v0
	v_add3_u32 v1, v1, v2, s2
	v_mul_f32_e32 v0, v69, v0
	ds_write_b16_d16_hi v73, v1 offset:3120
	v_bfe_u32 v1, v0, 16, 1
	v_add3_u32 v0, v0, v1, s2
	ds_write_b16_d16_hi v73, v0 offset:3184
	v_mov_b32_e32 v0, v40
	v_mov_b32_e32 v1, v56
	v_pk_mul_f32 v[0:1], v[0:1], v[0:1]
	v_mov_b32_e32 v2, v24
	v_mov_b32_e32 v7, v9
	v_pk_mul_f32 v[2:3], v[2:3], v[2:3]
	v_pk_mul_f32 v[6:7], v[6:7], v[6:7]
	v_mov_b32_e32 v17, v0
	v_mov_b32_e32 v0, v5
	v_pk_add_f32 v[0:1], v[16:17], v[0:1]
	v_mov_b32_e32 v4, v7
	v_mov_b32_e32 v5, v3
	v_pk_add_f32 v[0:1], v[4:5], v[0:1]
	v_mov_b32_e32 v7, v2
	v_pk_add_f32 v[0:1], v[6:7], v[0:1]
	ds_bpermute_b32 v3, v221, v1
	ds_bpermute_b32 v2, v221, v0
	v_mov_b32_e32 v4, v43
	v_mov_b32_e32 v5, v59
	v_pk_mul_f32 v[4:5], v[4:5], v[4:5]
	v_mov_b32_e32 v6, v27
	s_waitcnt lgkmcnt(0)
	v_pk_add_f32 v[0:1], v[0:1], v[2:3]
	ds_bpermute_b32 v3, v220, v1
	ds_bpermute_b32 v2, v220, v0
	v_mov_b32_e32 v7, v11
	v_pk_mul_f32 v[6:7], v[6:7], v[6:7]
	v_mov_b32_e32 v17, 0x2000
	s_waitcnt lgkmcnt(0)
	v_pk_add_f32 v[0:1], v[0:1], v[2:3]
	ds_bpermute_b32 v3, v219, v1
	ds_bpermute_b32 v2, v219, v0
	s_waitcnt lgkmcnt(0)
	v_pk_add_f32 v[0:1], v[0:1], v[2:3]
	ds_bpermute_b32 v3, v218, v1
	ds_bpermute_b32 v2, v218, v0
	s_waitcnt lgkmcnt(0)
	v_pk_add_f32 v[0:1], v[0:1], v[2:3]
	ds_bpermute_b32 v3, v217, v1
	ds_bpermute_b32 v2, v217, v0
	s_waitcnt lgkmcnt(0)
	v_pk_add_f32 v[0:1], v[0:1], v[2:3]
	s_nop 0
	v_pk_fma_f32 v[0:1], v[0:1], s[4:5], v[64:65] op_sel_hi:[1,0,0]
	s_nop 0
	v_mul_f32_e32 v2, 0x4b800000, v1
	v_cmp_gt_f32_e64 s[0:1], s33, v1
	v_cmp_gt_f32_e32 vcc, s33, v0
	s_nop 0
	v_cndmask_b32_e64 v1, v1, v2, s[0:1]
	v_rsq_f32_e32 v1, v1
	s_nop 0
	v_mul_f32_e32 v2, 0x45800000, v1
	v_cndmask_b32_e64 v1, v1, v2, s[0:1]
	v_mul_f32_e32 v2, v56, v1
	v_mul_f32_e32 v2, v72, v2
	v_bfe_u32 v3, v2, 16, 1
	v_add3_u32 v2, v2, v3, s2
	ds_write_b16_d16_hi v73, v2 offset:4352
	v_mul_f32_e32 v2, v40, v1
	v_mul_f32_e32 v2, v71, v2
	v_bfe_u32 v3, v2, 16, 1
	v_add3_u32 v2, v2, v3, s2
	ds_write_b16_d16_hi v73, v2 offset:4416
	v_mul_f32_e32 v2, v8, v1
	v_mul_f32_e32 v2, v70, v2
	v_bfe_u32 v3, v2, 16, 1
	v_mul_f32_e32 v1, v24, v1
	v_add3_u32 v2, v2, v3, s2
	v_mul_f32_e32 v1, v69, v1
	ds_write_b16_d16_hi v73, v2 offset:4480
	v_bfe_u32 v2, v1, 16, 1
	v_add3_u32 v1, v1, v2, s2
	ds_write_b16_d16_hi v73, v1 offset:4544
	v_mul_f32_e32 v1, 0x4b800000, v0
	v_cndmask_b32_e32 v0, v0, v1, vcc
	v_rsq_f32_e32 v0, v0
	v_mov_b32_e32 v3, v10
	v_mov_b32_e32 v8, v4
	v_mov_b32_e32 v4, v7
	v_mul_f32_e32 v1, 0x45800000, v0
	v_cndmask_b32_e32 v0, v0, v1, vcc
	v_mul_f32_e32 v1, v57, v0
	v_mul_f32_e32 v1, v72, v1
	v_bfe_u32 v2, v1, 16, 1
	v_add3_u32 v1, v1, v2, s2
	ds_write_b16_d16_hi v73, v1 offset:4624
	v_mul_f32_e32 v1, v41, v0
	v_mul_f32_e32 v1, v71, v1
	v_bfe_u32 v2, v1, 16, 1
	v_add3_u32 v1, v1, v2, s2
	ds_write_b16_d16_hi v73, v1 offset:4688
	v_mul_f32_e32 v1, v9, v0
	v_mul_f32_e32 v1, v70, v1
	v_bfe_u32 v2, v1, 16, 1
	v_mul_f32_e32 v0, v25, v0
	v_add3_u32 v1, v1, v2, s2
	v_mul_f32_e32 v0, v69, v0
	ds_write_b16_d16_hi v73, v1 offset:4752
	v_bfe_u32 v1, v0, 16, 1
	v_add3_u32 v0, v0, v1, s2
	ds_write_b16_d16_hi v73, v0 offset:4816
	v_mov_b32_e32 v0, v42
	v_mov_b32_e32 v1, v58
	v_pk_mul_f32 v[0:1], v[0:1], v[0:1]
	v_mov_b32_e32 v2, v26
	v_pk_mul_f32 v[2:3], v[2:3], v[2:3]
	v_mov_b32_e32 v9, v0
	v_mov_b32_e32 v0, v5
	v_pk_add_f32 v[0:1], v[8:9], v[0:1]
	v_mov_b32_e32 v5, v3
	v_pk_add_f32 v[0:1], v[4:5], v[0:1]
	v_mov_b32_e32 v7, v2
	v_pk_add_f32 v[0:1], v[6:7], v[0:1]
	ds_bpermute_b32 v3, v221, v1
	ds_bpermute_b32 v2, v221, v0
	v_mov_b32_e32 v4, v45
	v_mov_b32_e32 v5, v61
	v_pk_mul_f32 v[4:5], v[4:5], v[4:5]
	v_mov_b32_e32 v6, v29
	s_waitcnt lgkmcnt(0)
	v_pk_add_f32 v[0:1], v[0:1], v[2:3]
	ds_bpermute_b32 v3, v220, v1
	ds_bpermute_b32 v2, v220, v0
	v_mov_b32_e32 v7, v13
	v_pk_mul_f32 v[6:7], v[6:7], v[6:7]
	v_mov_b32_e32 v8, v4
	v_mov_b32_e32 v4, v7
	s_waitcnt lgkmcnt(0)
; DEV bf16_t f2bf(float f) { unsigned u = __float_as_uint(f); u += 0x7fffu + ((u >> 16) & 1u); return (bf16_t)(u >> 16); }
; DEV int crow(int r, int hi) { return (r & 3) + 8 * (r >> 2) + 4 * hi; }
; template <bool SPREAD>
; DEV void attn_store(f32x16 (&o)[4], const float* __restrict__ gain, float oscale, bf16_t* __restrict__ mix, int q0, int colbase) {
;     ...
;   for (int r = 0; r < 16; ++r) {
;     float ss = o[0][r] * o[0][r] + o[1][r] * o[1][r] + o[2][r] * o[2][r] + o[3][r] * o[3][r];
;     ss += __shfl_xor(ss, 1); ss += __shfl_xor(ss, 2); ss += __shfl_xor(ss, 4); ss += __shfl_xor(ss, 8); ss += __shfl_xor(ss, 16);
;     const float rn = rsqrtf(ss * (1.f / 128.f) + EPS);
;     const int cr = crow(r, hi);
; #pragma unroll
;     for (int d = 0; d < 4; ++d) *reinterpret_cast<bf16_t*>(sc + cr * 272 + (d * 32 + r32) * 2) = f2bf(o[d][r] * rn * gn[d]);
;   }
	v_pk_add_f32 v[0:1], v[0:1], v[2:3]
	ds_bpermute_b32 v3, v219, v1
	ds_bpermute_b32 v2, v219, v0
	s_waitcnt lgkmcnt(0)
	v_pk_add_f32 v[0:1], v[0:1], v[2:3]
	ds_bpermute_b32 v3, v218, v1
	ds_bpermute_b32 v2, v218, v0
	s_waitcnt lgkmcnt(0)
	v_pk_add_f32 v[0:1], v[0:1], v[2:3]
	ds_bpermute_b32 v3, v217, v1
	ds_bpermute_b32 v2, v217, v0
	s_waitcnt lgkmcnt(0)
	v_pk_add_f32 v[0:1], v[0:1], v[2:3]
	s_nop 0
	v_pk_fma_f32 v[0:1], v[0:1], s[4:5], v[64:65] op_sel_hi:[1,0,0]
	s_nop 0
	v_mul_f32_e32 v2, 0x4b800000, v1
	v_cmp_gt_f32_e64 s[0:1], s33, v1
	v_cmp_gt_f32_e32 vcc, s33, v0
	s_nop 0
	v_cndmask_b32_e64 v1, v1, v2, s[0:1]
	v_rsq_f32_e32 v1, v1
	s_nop 0
	v_mul_f32_e32 v2, 0x45800000, v1
	v_cndmask_b32_e64 v1, v1, v2, s[0:1]
	v_mul_f32_e32 v2, v58, v1
	v_mul_f32_e32 v2, v72, v2
	v_bfe_u32 v3, v2, 16, 1
	v_add3_u32 v2, v2, v3, s2
	ds_write_b16_d16_hi v73, v2 offset:4896
	v_mul_f32_e32 v2, v42, v1
	v_mul_f32_e32 v2, v71, v2
	v_bfe_u32 v3, v2, 16, 1
	v_add3_u32 v2, v2, v3, s2
	ds_write_b16_d16_hi v73, v2 offset:4960
	v_mul_f32_e32 v2, v10, v1
	v_mul_f32_e32 v2, v70, v2
	v_bfe_u32 v3, v2, 16, 1
	v_mul_f32_e32 v1, v26, v1
	v_add3_u32 v2, v2, v3, s2
	v_mul_f32_e32 v1, v69, v1
	ds_write_b16_d16_hi v73, v2 offset:5024
	v_bfe_u32 v2, v1, 16, 1
	v_add3_u32 v1, v1, v2, s2
	ds_write_b16_d16_hi v73, v1 offset:5088
	v_mul_f32_e32 v1, 0x4b800000, v0
	v_cndmask_b32_e32 v0, v0, v1, vcc
	v_rsq_f32_e32 v0, v0
	v_mov_b32_e32 v3, v12
	v_mul_f32_e32 v1, 0x45800000, v0
	v_cndmask_b32_e32 v0, v0, v1, vcc
	v_mul_f32_e32 v1, v59, v0
	v_mul_f32_e32 v1, v72, v1
	v_bfe_u32 v2, v1, 16, 1
	v_add3_u32 v1, v1, v2, s2
	ds_write_b16_d16_hi v73, v1 offset:5168
	v_mul_f32_e32 v1, v43, v0
	v_mul_f32_e32 v1, v71, v1
	v_bfe_u32 v2, v1, 16, 1
	v_add3_u32 v1, v1, v2, s2
	ds_write_b16_d16_hi v73, v1 offset:5232
	v_mul_f32_e32 v1, v11, v0
	v_mul_f32_e32 v1, v70, v1
	v_bfe_u32 v2, v1, 16, 1
	v_mul_f32_e32 v0, v27, v0
	v_add3_u32 v1, v1, v2, s2
	v_mul_f32_e32 v0, v69, v0
	ds_write_b16_d16_hi v73, v1 offset:5296
	v_bfe_u32 v1, v0, 16, 1
	v_add3_u32 v0, v0, v1, s2
	ds_write_b16_d16_hi v73, v0 offset:5360
	v_mov_b32_e32 v0, v44
	v_mov_b32_e32 v1, v60
	v_pk_mul_f32 v[0:1], v[0:1], v[0:1]
	v_mov_b32_e32 v2, v28
	v_pk_mul_f32 v[2:3], v[2:3], v[2:3]
	v_mov_b32_e32 v9, v0
	v_mov_b32_e32 v0, v5
	v_pk_add_f32 v[0:1], v[8:9], v[0:1]
	v_mov_b32_e32 v5, v3
	v_pk_add_f32 v[0:1], v[4:5], v[0:1]
	v_mov_b32_e32 v7, v2
	v_pk_add_f32 v[0:1], v[6:7], v[0:1]
	ds_bpermute_b32 v3, v221, v1
	ds_bpermute_b32 v2, v221, v0
	v_mov_b32_e32 v4, v47
	v_mov_b32_e32 v5, v63
	v_pk_mul_f32 v[4:5], v[4:5], v[4:5]
	v_mov_b32_e32 v6, v31
	s_waitcnt lgkmcnt(0)
	v_pk_add_f32 v[0:1], v[0:1], v[2:3]
	ds_bpermute_b32 v3, v220, v1
	ds_bpermute_b32 v2, v220, v0
	v_mov_b32_e32 v7, v15
	v_pk_mul_f32 v[6:7], v[6:7], v[6:7]
	v_mov_b32_e32 v8, v4
	v_mov_b32_e32 v4, v7
	s_waitcnt lgkmcnt(0)
	v_pk_add_f32 v[0:1], v[0:1], v[2:3]
	ds_bpermute_b32 v3, v219, v1
	ds_bpermute_b32 v2, v219, v0
	s_waitcnt lgkmcnt(0)
	v_pk_add_f32 v[0:1], v[0:1], v[2:3]
	ds_bpermute_b32 v3, v218, v1
	ds_bpermute_b32 v2, v218, v0
	s_waitcnt lgkmcnt(0)
	v_pk_add_f32 v[0:1], v[0:1], v[2:3]
	ds_bpermute_b32 v3, v217, v1
	ds_bpermute_b32 v2, v217, v0
	s_waitcnt lgkmcnt(0)
	v_pk_add_f32 v[0:1], v[0:1], v[2:3]
	s_nop 0
	v_pk_fma_f32 v[0:1], v[0:1], s[4:5], v[64:65] op_sel_hi:[1,0,0]
	s_nop 0
	v_mul_f32_e32 v2, 0x4b800000, v1
	v_cmp_gt_f32_e64 s[0:1], s33, v1
	v_cmp_gt_f32_e32 vcc, s33, v0
	s_nop 0
	v_cndmask_b32_e64 v1, v1, v2, s[0:1]
	v_rsq_f32_e32 v1, v1
	s_nop 0
	v_mul_f32_e32 v2, 0x45800000, v1
	v_cndmask_b32_e64 v1, v1, v2, s[0:1]
	v_mul_f32_e32 v2, v60, v1
	v_mul_f32_e32 v2, v72, v2
	v_bfe_u32 v3, v2, 16, 1
	v_add3_u32 v2, v2, v3, s2
	ds_write_b16_d16_hi v73, v2 offset:6528
	v_mul_f32_e32 v2, v44, v1
	v_mul_f32_e32 v2, v71, v2
	v_bfe_u32 v3, v2, 16, 1
	v_add3_u32 v2, v2, v3, s2
	ds_write_b16_d16_hi v73, v2 offset:6592
	v_mul_f32_e32 v2, v12, v1
	v_mul_f32_e32 v2, v70, v2
	v_bfe_u32 v3, v2, 16, 1
	v_mul_f32_e32 v1, v28, v1
	v_add3_u32 v2, v2, v3, s2
	v_mul_f32_e32 v1, v69, v1
	ds_write_b16_d16_hi v73, v2 offset:6656
	v_bfe_u32 v2, v1, 16, 1
	v_add3_u32 v1, v1, v2, s2
	ds_write_b16_d16_hi v73, v1 offset:6720
	v_mul_f32_e32 v1, 0x4b800000, v0
	v_cndmask_b32_e32 v0, v0, v1, vcc
	v_rsq_f32_e32 v0, v0
	v_mov_b32_e32 v3, v14
	v_mul_f32_e32 v1, 0x45800000, v0
	v_cndmask_b32_e32 v0, v0, v1, vcc
	v_mul_f32_e32 v1, v61, v0
	v_mul_f32_e32 v1, v72, v1
	v_bfe_u32 v2, v1, 16, 1
	v_add3_u32 v1, v1, v2, s2
	ds_write_b16_d16_hi v73, v1 offset:6800
	v_mul_f32_e32 v1, v45, v0
	v_mul_f32_e32 v1, v71, v1
	v_bfe_u32 v2, v1, 16, 1
	v_add3_u32 v1, v1, v2, s2
	ds_write_b16_d16_hi v73, v1 offset:6864
	v_mul_f32_e32 v1, v13, v0
	v_mul_f32_e32 v1, v70, v1
	v_bfe_u32 v2, v1, 16, 1
	v_mul_f32_e32 v0, v29, v0
	v_add3_u32 v1, v1, v2, s2
	v_mul_f32_e32 v0, v69, v0
	ds_write_b16_d16_hi v73, v1 offset:6928
	v_bfe_u32 v1, v0, 16, 1
	v_add3_u32 v0, v0, v1, s2
	ds_write_b16_d16_hi v73, v0 offset:6992
	v_mov_b32_e32 v0, v46
	v_mov_b32_e32 v1, v62
	v_pk_mul_f32 v[0:1], v[0:1], v[0:1]
	v_mov_b32_e32 v2, v30
	v_pk_mul_f32 v[2:3], v[2:3], v[2:3]
	v_mov_b32_e32 v9, v0
	v_mov_b32_e32 v0, v5
	v_pk_add_f32 v[0:1], v[8:9], v[0:1]
	v_mov_b32_e32 v5, v3
	v_pk_add_f32 v[0:1], v[4:5], v[0:1]
	v_mov_b32_e32 v7, v2
	v_pk_add_f32 v[0:1], v[6:7], v[0:1]
	ds_bpermute_b32 v3, v221, v1
	ds_bpermute_b32 v2, v221, v0
	v_bfe_u32 v6, v66, 4, 2
	v_lshl_add_u32 v7, v67, 5, s74
	s_waitcnt lgkmcnt(0)
	v_pk_add_f32 v[0:1], v[0:1], v[2:3]
	ds_bpermute_b32 v3, v220, v1
	ds_bpermute_b32 v2, v220, v0
	s_waitcnt lgkmcnt(0)
	v_pk_add_f32 v[0:1], v[0:1], v[2:3]
	ds_bpermute_b32 v3, v219, v1
	ds_bpermute_b32 v2, v219, v0
	s_waitcnt lgkmcnt(0)
; DEV void diff16_pass(const bf16_t* __restrict__ proj, int qcol, int kcol, int vcol, int q0, f32x4 (&o)[2][8], f32x4 (&l_out)[2], unsigned char* lds) {
;     ...
;   for (int g = 0; g < 2; ++g) { const int sl = 16 * g + fr; const bf16_t* Qw = proj + (size_t)(q0 + 64 * (sl >> 3) + 8 * wid + (sl & 7)) * INW + qcol + fq * 8;
;     *reinterpret_cast<bf16x8*>(lds + D_QOFF + wid * 4096 + (g * 2 + 0) * 1024 + lane * 16) = *reinterpret_cast<const bf16x8*>(Qw);
;     *reinterpret_cast<bf16x8*>(lds + D_QOFF + wid * 4096 + (g * 2 + 1) * 1024 + lane * 16) = *reinterpret_cast<const bf16x8*>(Qw + 32); }
; template <bool SPREAD>
; DEV void attn_store(f32x16 (&o)[4], const float* __restrict__ gain, float oscale, bf16_t* __restrict__ mix, int q0, int colbase) {
;     ...
; #pragma unroll
;   for (int i = 0; i < 8; ++i) { const int rs = 4 * i + (lane >> 4);
;     const u32x4 w = *reinterpret_cast<const u32x4*>(sc + rs * 272 + (lane & 15) * 16);
;     const size_t row = SPREAD ? (size_t)(q0 + 64 * (rs >> 3) + 8 * wid + (rs & 7)) : (size_t)(q0 + wid * 32 + rs);
;     *reinterpret_cast<u32x4*>(mix + row * DM + colbase + (lane & 15) * 8) = w; }
;   __syncthreads();
	v_pk_add_f32 v[0:1], v[0:1], v[2:3]
	ds_bpermute_b32 v3, v218, v1
	ds_bpermute_b32 v2, v218, v0
	s_waitcnt lgkmcnt(0)
	v_pk_add_f32 v[0:1], v[0:1], v[2:3]
	ds_bpermute_b32 v3, v217, v1
	ds_bpermute_b32 v2, v217, v0
	s_waitcnt lgkmcnt(0)
	v_pk_add_f32 v[0:1], v[0:1], v[2:3]
	s_nop 0
	v_pk_fma_f32 v[0:1], v[0:1], s[4:5], v[64:65] op_sel_hi:[1,0,0]
	s_nop 0
	v_mul_f32_e32 v2, 0x4b800000, v1
	v_cmp_gt_f32_e64 s[0:1], s33, v1
	v_cmp_gt_f32_e32 vcc, s33, v0
	s_nop 0
	v_cndmask_b32_e64 v1, v1, v2, s[0:1]
	v_rsq_f32_e32 v1, v1
	s_nop 0
	v_mul_f32_e32 v2, 0x45800000, v1
	v_cndmask_b32_e64 v1, v1, v2, s[0:1]
	v_mul_f32_e32 v2, v62, v1
	v_mul_f32_e32 v2, v72, v2
	v_bfe_u32 v3, v2, 16, 1
	v_add3_u32 v2, v2, v3, s2
	ds_write_b16_d16_hi v73, v2 offset:7072
	v_mul_f32_e32 v2, v46, v1
	v_mul_f32_e32 v2, v71, v2
	v_bfe_u32 v3, v2, 16, 1
	v_add3_u32 v2, v2, v3, s2
	ds_write_b16_d16_hi v73, v2 offset:7136
	v_mul_f32_e32 v2, v14, v1
	v_mul_f32_e32 v2, v70, v2
	v_bfe_u32 v3, v2, 16, 1
	v_mul_f32_e32 v1, v30, v1
	v_add3_u32 v2, v2, v3, s2
	v_mul_f32_e32 v1, v69, v1
	ds_write_b16_d16_hi v73, v2 offset:7200
	v_bfe_u32 v2, v1, 16, 1
	v_add3_u32 v1, v1, v2, s2
	ds_write_b16_d16_hi v73, v1 offset:7264
	v_mul_f32_e32 v1, 0x4b800000, v0
	v_cndmask_b32_e32 v0, v0, v1, vcc
	v_rsq_f32_e32 v0, v0
	v_readlane_b32 s0, v255, 47
	v_readlane_b32 s1, v255, 48
	v_mul_f32_e32 v1, 0x45800000, v0
	v_cndmask_b32_e32 v0, v0, v1, vcc
	v_mul_f32_e32 v1, v63, v0
	v_mul_f32_e32 v1, v72, v1
	v_bfe_u32 v2, v1, 16, 1
	v_add3_u32 v1, v1, v2, s2
	ds_write_b16_d16_hi v73, v1 offset:7344
	v_mul_f32_e32 v1, v47, v0
	v_mul_f32_e32 v1, v71, v1
	v_bfe_u32 v2, v1, 16, 1
	v_add3_u32 v1, v1, v2, s2
	ds_write_b16_d16_hi v73, v1 offset:7408
	v_mul_f32_e32 v1, v15, v0
	v_mul_f32_e32 v1, v70, v1
	v_bfe_u32 v2, v1, 16, 1
	v_mul_f32_e32 v0, v31, v0
	v_add3_u32 v1, v1, v2, s2
	v_mul_f32_e32 v0, v69, v0
	ds_write_b16_d16_hi v73, v1 offset:7472
	v_bfe_u32 v1, v0, 16, 1
	v_add3_u32 v0, v0, v1, s2
	ds_write_b16_d16_hi v73, v0 offset:7536
	v_lshlrev_b32_e32 v0, 4, v66
	v_and_b32_e32 v192, 0xf0, v0
	v_mul_u32_u24_e32 v0, 0x110, v6
	v_add3_u32 v10, v68, v192, v0
	ds_read_b128 v[0:3], v10
	v_or_b32_e32 v6, v7, v6
	v_ashrrev_i32_e32 v7, 31, v6
	v_lshl_add_u64 v[4:5], s[0:1], 0, v[192:193]
	v_lshlrev_b64 v[8:9], 12, v[6:7]
	v_lshl_add_u64 v[8:9], v[4:5], 0, v[8:9]
	s_waitcnt lgkmcnt(0)
	global_store_dwordx4 v[8:9], v[0:3], off
	ds_read_b128 v[0:3], v10 offset:1088
	v_or_b32_e32 v8, 4, v6
	v_ashrrev_i32_e32 v9, 31, v8
	v_lshlrev_b64 v[8:9], 12, v[8:9]
	v_lshl_add_u64 v[8:9], v[4:5], 0, v[8:9]
	s_waitcnt lgkmcnt(0)
	global_store_dwordx4 v[8:9], v[0:3], off
	ds_read_b128 v[0:3], v10 offset:2176
	v_or_b32_e32 v8, 8, v6
	v_ashrrev_i32_e32 v9, 31, v8
	v_lshlrev_b64 v[8:9], 12, v[8:9]
	v_lshl_add_u64 v[8:9], v[4:5], 0, v[8:9]
	s_waitcnt lgkmcnt(0)
	global_store_dwordx4 v[8:9], v[0:3], off
	ds_read_b128 v[0:3], v10 offset:3264
	v_or_b32_e32 v8, 12, v6
	v_ashrrev_i32_e32 v9, 31, v8
	v_lshlrev_b64 v[8:9], 12, v[8:9]
	v_lshl_add_u64 v[8:9], v[4:5], 0, v[8:9]
	s_waitcnt lgkmcnt(0)
	global_store_dwordx4 v[8:9], v[0:3], off
	ds_read_b128 v[0:3], v10 offset:4352
	v_or_b32_e32 v8, 16, v6
	v_ashrrev_i32_e32 v9, 31, v8
	v_lshlrev_b64 v[8:9], 12, v[8:9]
	v_lshl_add_u64 v[8:9], v[4:5], 0, v[8:9]
	s_waitcnt lgkmcnt(0)
	global_store_dwordx4 v[8:9], v[0:3], off
	ds_read_b128 v[0:3], v10 offset:5440
	v_or_b32_e32 v8, 20, v6
	v_ashrrev_i32_e32 v9, 31, v8
	v_lshlrev_b64 v[8:9], 12, v[8:9]
	v_lshl_add_u64 v[8:9], v[4:5], 0, v[8:9]
	s_waitcnt lgkmcnt(0)
	global_store_dwordx4 v[8:9], v[0:3], off
	ds_read_b128 v[0:3], v10 offset:6528
	v_or_b32_e32 v8, 24, v6
	v_ashrrev_i32_e32 v9, 31, v8
	v_lshlrev_b64 v[8:9], 12, v[8:9]
	v_lshl_add_u64 v[8:9], v[4:5], 0, v[8:9]
	s_waitcnt lgkmcnt(0)
	global_store_dwordx4 v[8:9], v[0:3], off
	ds_read_b128 v[0:3], v10 offset:7616
	v_or_b32_e32 v6, 28, v6
	v_ashrrev_i32_e32 v7, 31, v6
	v_lshlrev_b64 v[6:7], 12, v[6:7]
	v_lshl_add_u64 v[4:5], v[4:5], 0, v[6:7]
	v_mov_b32_e32 v8, v210
	s_waitcnt lgkmcnt(0)
	global_store_dwordx4 v[4:5], v[0:3], off
	s_barrier
	v_readlane_b32 s0, v255, 51
	v_ashrrev_i32_e32 v9, 6, v8
	v_and_b32_e32 v0, 0x3fffffc0, v8
	v_lshlrev_b32_e32 v12, 3, v8
	v_and_b32_e32 v13, 7, v8
	v_lshl_add_u32 v225, v0, 2, s16
	v_and_b32_e32 v0, 64, v12
	v_lshlrev_b32_e32 v1, 3, v9
	v_or_b32_e32 v2, s74, v13
	v_and_b32_e32 v192, 48, v8
	v_readlane_b32 s1, v255, 52
	v_add3_u32 v14, v2, v1, v0
	v_and_b32_e32 v227, 63, v8
	v_lshl_add_u64 v[4:5], s[0:1], 0, v[192:193]
	v_readlane_b32 s0, v255, 10
	v_lshlrev_b32_e32 v11, 4, v227
	v_bfe_u32 v10, v8, 4, 2
	v_lshl_add_u32 v15, v9, 12, s0
	v_mad_i64_i32 v[6:7], s[0:1], v14, s85, v[4:5]
	global_load_dwordx4 v[0:3], v[6:7], off
	global_load_dwordx4 v[96:99], v[6:7], off offset:64
	v_add_u32_e32 v108, 0x80, v14
	v_mad_i64_i32 v[4:5], s[0:1], v108, s85, v[4:5]
	global_load_dwordx4 v[100:103], v[4:5], off
	global_load_dwordx4 v[104:107], v[4:5], off offset:64
	v_add_u32_e32 v228, v15, v11
	v_lshrrev_b32_e32 v15, 6, v8
	v_and_b32_e32 v15, 4, v15
	v_lshl_add_u32 v17, v8, 4, v17
	v_lshrrev_b32_e32 v17, 8, v17
	v_and_b32_e32 v226, 15, v8
	s_waitcnt vmcnt(0)
; #define VWAIT(n) asm volatile("s_waitcnt vmcnt(" #n ")" ::: "memory")
; #define LBAR() do { asm volatile("s_waitcnt lgkmcnt(0)" ::: "memory"); __builtin_amdgcn_s_barrier(); } while (0)
; #define VWAIT(n) asm volatile("s_waitcnt vmcnt(" #n ")" ::: "memory")
; #define LBAR() do { asm volatile("s_waitcnt lgkmcnt(0)" ::: "memory"); __builtin_amdgcn_s_barrier(); } while (0)
; #define ROWMAXF16(S, pm) do { _Pragma("unroll") for (int g = 0; g < 2; ++g) { float m_ = S[g][0][0]; \
;       _Pragma("unroll") for (int kb = 0; kb < 4; ++kb) _Pragma("unroll") for (int j = 0; j < 4; ++j) m_ = fmaxf(m_, S[g][kb][j]); pm[g] = m_; } } while (0)
; DEV void diff16_pass(const bf16_t* __restrict__ proj, int qcol, int kcol, int vcol, int q0, f32x4 (&o)[2][8], f32x4 (&l_out)[2], unsigned char* lds) {
;     ...
;   for (int g = 0; g < 2; ++g) { const int sl = 16 * g + fr; const bf16_t* Qw = proj + (size_t)(q0 + 64 * (sl >> 3) + 8 * wid + (sl & 7)) * INW + qcol + fq * 8;
;     *reinterpret_cast<bf16x8*>(lds + D_QOFF + wid * 4096 + (g * 2 + 0) * 1024 + lane * 16) = *reinterpret_cast<const bf16x8*>(Qw);
;     *reinterpret_cast<bf16x8*>(lds + D_QOFF + wid * 4096 + (g * 2 + 1) * 1024 + lane * 16) = *reinterpret_cast<const bf16x8*>(Qw + 32); }
;   const int c0 = q0 >> 6, NT = c0 + 4, lim0 = c0 + (fr >> 3), lim1 = c0 + 2 + (fr >> 3);
;   const int kf = ((fr >> 1) & 1) | ((fr >> 2) << 1);
;   const lds_cptr krd = (lds_cptr)shm_raw + D_KOFF + (8 * (fr >> 2) + (fr & 3)) * 128;
;   const int kch0 = ((0 + fq) ^ kf) << 4, kch1 = ((4 + fq) ^ kf) << 4;
;   const int vlane = (fq >> 1) * 512 + (fq & 1) * 256 + (fr >> 2) * 64 + (fr & 3) * 8;
;   const lds_cptr vrdE = (lds_cptr)shm_raw + vlane + (fq & 1) * 32, vrdO = (lds_cptr)shm_raw + vlane + (1 - (fq & 1)) * 32;
;   typedef unsigned char __attribute__((address_space(3))) lds_u8w;
;   lds_u8w* ldsw = (lds_u8w*)shm_raw;
;   unsigned Kg, Vg0, Vg1;
;   { const int r = tid >> 3, fK = ((r >> 1) & 1) | (((r >> 3) & 3) << 1); Kg = (unsigned)(r * INW + kcol + (((tid & 7) ^ fK) * 8)) * 2u;
;     ...
;     VSRC(tid, Vg0); VSRC(512 + tid, Vg1);
;     ...
;   }
;   const unsigned dmaw = (unsigned)__builtin_amdgcn_readfirstlane(wid) * 1024u;
;     ...
;   DMA(0); DMA(1); DMA(2); VWAIT(3); LBAR();
;   { QKT16(SA, 0); float pm_[2]; ROWMAXF16(SA, pm_); RESCALE16(SA, pm_, alA, rfA, true); alA[0] = 1.f; alA[1] = 1.f; rfA = false; EXP16(SA); }
	ds_write_b128 v228, v[0:3]
	ds_write_b128 v228, v[96:99] offset:1024
	ds_write_b128 v228, v[100:103] offset:2048
	ds_write_b128 v228, v[104:107] offset:3072
	v_or_b32_e32 v6, 4, v10
	s_movk_i32 s0, 0x1800
	v_lshrrev_b32_e32 v14, 5, v8
	v_and_b32_e32 v14, 6, v14
	v_bfe_u32 v2, v8, 2, 2
	v_bfe_u32 v1, v8, 1, 1
	v_lshlrev_b32_e32 v3, 1, v2
	v_bitop3_b32 v5, v3, v10, v1 bitop3:0x36
	v_bitop3_b32 v1, v3, v6, v1 bitop3:0x36
	v_bfe_u32 v6, v227, 4, 1
	v_lshlrev_b32_e32 v7, 8, v6
	v_lshlrev_b32_e32 v48, 5, v6
	v_lshrrev_b32_e32 v6, 3, v8
	v_and_b32_e32 v3, 0x200, v11
	v_mul_lo_u32 v6, v6, s0
	v_readlane_b32 s0, v255, 49
	v_add3_u32 v3, 0, v3, v7
	v_lshrrev_b32_e32 v7, 4, v8
	v_bfe_u32 v11, v8, 4, 1
	v_add_lshl_u32 v6, s0, v6, 1
	s_mov_b32 s0, 0x1fffe0
	v_bitop3_b32 v11, v11, v13, v14 bitop3:0x36
	v_bfe_u32 v13, v8, 1, 27
	v_and_or_b32 v16, v7, s0, v15
	v_readlane_b32 s0, v255, 50
	v_xor_b32_e32 v7, v13, v7
	v_lshrrev_b32_e32 v0, 1, v8
	v_and_or_b32 v12, v12, 8, s0
	s_mov_b32 s0, 0xffffe0
	v_and_b32_e32 v14, 24, v13
	v_lshlrev_b32_e32 v7, 4, v7
	v_and_or_b32 v15, v17, s0, v15
	v_lshlrev_b32_e32 v4, 10, v2
	v_lshlrev_b32_e32 v10, 6, v2
	v_or3_b32 v16, v16, v2, v14
	v_and_b32_e32 v0, 0x60, v0
	v_and_b32_e32 v7, 16, v7
	v_or3_b32 v2, v15, v2, v14
	v_and_b32_e32 v13, 0x60, v13
	v_readfirstlane_b32 s0, v9
	v_mul_u32_u24_e32 v16, 0x1800, v16
	v_or3_b32 v0, v0, v7, v12
	v_mul_i32_i24_e32 v2, 0x1800, v2
	v_or3_b32 v7, v13, v7, v12
	v_and_b32_e32 v8, 3, v8
	s_lshl_b32 s0, s0, 10
	v_lshlrev_b32_e32 v231, 4, v1
	v_lshlrev_b32_e32 v1, 3, v8
	v_lshl_or_b32 v232, v11, 4, v6
	v_add_lshl_u32 v233, v0, v16, 1
	v_add_lshl_u32 v234, v7, v2, 1
	s_add_i32 s17, s15, s0
	v_add3_u32 v49, v3, v10, v1
	v_mov_b32_e32 v0, v233
	v_mov_b32_e32 v1, v232
	v_mov_b32_e32 v2, v234
	s_mov_b32 m0, s17
	s_add_i32 s18, s0, 0
	v_readlane_b32 s0, v253, 33
	global_load_lds_dwordx4 v1, s[86:87]
	s_mov_b32 m0, s18
	v_mov_b32_e32 v1, v232
	global_load_lds_dwordx4 v0, s[86:87]
	s_add_i32 m0, s18, 0x2000
	v_mov_b32_e32 v0, v233
	global_load_lds_dwordx4 v2, s[86:87]
	v_mov_b32_e32 v2, v234
	s_add_i32 m0, s18, 0x12000
	v_readlane_b32 s1, v253, 34
	v_lshlrev_b32_e32 v9, 7, v8
	v_add3_u32 v229, s15, v4, v9
	v_lshlrev_b32_e32 v230, 4, v5
	v_add_u32_e32 v50, v229, v230
	s_nop 0
	global_load_lds_dwordx4 v1, s[0:1]
	s_add_i32 m0, s18, 0x4000
	v_mov_b32_e32 v1, v232
	global_load_lds_dwordx4 v0, s[0:1]
	s_add_i32 m0, s18, 0x6000
	v_mov_b32_e32 v0, v233
	global_load_lds_dwordx4 v2, s[0:1]
	v_readlane_b32 s0, v253, 35
	v_mov_b32_e32 v2, v234
	s_add_i32 m0, s18, 0x14000
	v_readlane_b32 s1, v253, 36
	v_add_u32_e32 v51, v229, v231
	v_add_u32_e32 v223, v49, v48
	v_xad_u32 v224, v48, 32, v49
	s_nop 1
	global_load_lds_dwordx4 v1, s[0:1]
	s_add_i32 m0, s18, 0x8000
	s_nop 0
	global_load_lds_dwordx4 v0, s[0:1]
	s_add_i32 m0, s18, 0xa000
	s_cmp_gt_i32 s81, -1
	global_load_lds_dwordx4 v2, s[0:1]
	s_waitcnt vmcnt(3)
	s_waitcnt lgkmcnt(0)
	s_barrier
	ds_read_b128 v[24:27], v228
	ds_read_b128 v[28:31], v228 offset:1024
	ds_read_b128 v[32:35], v228 offset:2048
	ds_read_b128 v[36:39], v228 offset:3072
	ds_read_b128 v[0:3], v50
	ds_read_b128 v[4:7], v51
	s_waitcnt lgkmcnt(0)
	v_mfma_f32_16x16x32_bf16 v[8:11], v[0:3], v[24:27], 0
	s_cselect_b64 s[10:11], -1, 0
	s_cmp_lt_i32 s81, 0
	v_mfma_f32_16x16x32_bf16 v[12:15], v[0:3], v[32:35], 0
	v_mfma_f32_16x16x32_bf16 v[0:3], v[4:7], v[28:31], v[8:11]
	v_mfma_f32_16x16x32_bf16 v[4:7], v[4:7], v[36:39], v[12:15]
	s_nop 2
	ds_read_b128 v[8:11], v50 offset:512
	s_nop 1
	ds_read_b128 v[12:15], v51 offset:512
	s_waitcnt lgkmcnt(0)
	v_mfma_f32_16x16x32_bf16 v[16:19], v[8:11], v[24:27], 0
	v_mfma_f32_16x16x32_bf16 v[20:23], v[8:11], v[32:35], 0
	v_mfma_f32_16x16x32_bf16 v[8:11], v[12:15], v[28:31], v[16:19]
	v_mfma_f32_16x16x32_bf16 v[16:19], v[12:15], v[36:39], v[20:23]
	ds_read_b128 v[12:15], v50 offset:4096
	s_nop 4
	ds_read_b128 v[20:23], v51 offset:4096
	s_waitcnt lgkmcnt(0)
	v_mfma_f32_16x16x32_bf16 v[40:43], v[12:15], v[24:27], 0
	v_mfma_f32_16x16x32_bf16 v[44:47], v[12:15], v[32:35], 0
	v_mfma_f32_16x16x32_bf16 v[12:15], v[20:23], v[28:31], v[40:43]
	v_mfma_f32_16x16x32_bf16 v[20:23], v[20:23], v[36:39], v[44:47]
	s_nop 4
	ds_read_b128 v[40:43], v50 offset:4608
	ds_read_b128 v[44:47], v51 offset:4608
	s_waitcnt lgkmcnt(0)
	v_mfma_f32_16x16x32_bf16 v[24:27], v[40:43], v[24:27], 0
	v_mfma_f32_16x16x32_bf16 v[32:35], v[40:43], v[32:35], 0
	v_mfma_f32_16x16x32_bf16 v[24:27], v[44:47], v[28:31], v[24:27]
	v_mfma_f32_16x16x32_bf16 v[28:31], v[44:47], v[36:39], v[32:35]
	s_nop 5
	v_max_f32_e32 v32, v1, v1
	v_max_f32_e32 v33, v0, v0
	v_max_f32_e32 v32, v33, v32
	v_max_f32_e32 v33, v5, v5
	v_max_f32_e32 v34, v4, v4
	v_max_f32_e32 v33, v34, v33
	v_max3_f32 v32, v32, v2, v3
	v_max3_f32 v33, v33, v6, v7
	v_max3_f32 v32, v32, v8, v9
	v_max3_f32 v33, v33, v16, v17
	v_max3_f32 v32, v32, v10, v11
	v_max3_f32 v33, v33, v18, v19
	v_max3_f32 v32, v32, v12, v13
	v_max3_f32 v33, v33, v20, v21
	v_max3_f32 v32, v32, v14, v15
	v_max3_f32 v33, v33, v22, v23
	v_max3_f32 v32, v32, v24, v25
	v_max3_f32 v33, v33, v28, v29
	v_max3_f32 v32, v32, v26, v27
	v_max3_f32 v34, v33, v30, v31
	ds_bpermute_b32 v33, v217, v32
	ds_bpermute_b32 v35, v217, v34
	s_waitcnt lgkmcnt(0)
	v_max_f32_e32 v33, v33, v33
	v_max_f32_e32 v35, v35, v35
	v_max_f32_e32 v32, v32, v33
	v_max_f32_e32 v34, v34, v35
	ds_bpermute_b32 v33, v216, v32
	ds_bpermute_b32 v35, v216, v34
	s_cbranch_scc1 .LBB0_391
; #define VWAIT(n) asm volatile("s_waitcnt vmcnt(" #n ")" ::: "memory")
; #define LBAR() do { asm volatile("s_waitcnt lgkmcnt(0)" ::: "memory"); __builtin_amdgcn_s_barrier(); } while (0)
; #define VWAIT(n) asm volatile("s_waitcnt vmcnt(" #n ")" ::: "memory")
; #define LBAR() do { asm volatile("s_waitcnt lgkmcnt(0)" ::: "memory"); __builtin_amdgcn_s_barrier(); } while (0)
; #define ROWMAXF16(S, pm) do { _Pragma("unroll") for (int g = 0; g < 2; ++g) { float m_ = S[g][0][0]; \
;       _Pragma("unroll") for (int kb = 0; kb < 4; ++kb) _Pragma("unroll") for (int j = 0; j < 4; ++j) m_ = fmaxf(m_, S[g][kb][j]); pm[g] = m_; } } while (0)
; #define EXP16(S) do { _Pragma("unroll") for (int g = 0; g < 2; ++g) _Pragma("unroll") for (int kb = 0; kb < 4; ++kb) _Pragma("unroll") for (int j = 0; j < 4; ++j) S[g][kb][j] = __builtin_amdgcn_exp2f(S[g][kb][j]); } while (0)
; DEV void diff16_pass(const bf16_t* __restrict__ proj, int qcol, int kcol, int vcol, int q0, f32x4 (&o)[2][8], f32x4 (&l_out)[2], unsigned char* lds) {
;     ...
;   float m_reg[2] = {0.f, 0.f};
;   f32x4 ol[2] = {(f32x4){0.f, 0.f, 0.f, 0.f}, (f32x4){0.f, 0.f, 0.f, 0.f}};
;   const bf16x8 ones = {0x3F80, 0x3F80, 0x3F80, 0x3F80, 0x3F80, 0x3F80, 0x3F80, 0x3F80};
;   f32x4 negm[2] = {(f32x4){0.f, 0.f, 0.f, 0.f}, (f32x4){0.f, 0.f, 0.f, 0.f}};
; #pragma unroll
;   for (int g = 0; g < 2; ++g)
; #pragma unroll
;     for (int cb = 0; cb < 8; ++cb) o[g][cb] = (f32x4){0.f, 0.f, 0.f, 0.f};
;   f32x4 SA[2][4], SB2[2][4]; float alA[2], alB[2]; bool rfA = false, rfB = false; bf16x8 pa[2][2];
;   DMA(0); DMA(1); DMA(2); VWAIT(3); LBAR();
;   { QKT16(SA, 0); float pm_[2]; ROWMAXF16(SA, pm_); RESCALE16(SA, pm_, alA, rfA, true); alA[0] = 1.f; alA[1] = 1.f; rfA = false; EXP16(SA); }
	s_waitcnt lgkmcnt(0)
	v_max_f32_e32 v35, v35, v35
	v_max_f32_e32 v34, v34, v34
	v_max_f32_e32 v35, v34, v35
	v_sub_f32_e32 v5, v5, v35
	v_sub_f32_e32 v4, v4, v35
	v_exp_f32_e32 v137, v4
	v_exp_f32_e32 v148, v5
	v_max_f32_e32 v4, v33, v33
	v_max_f32_e32 v5, v32, v32
	v_sub_f32_e32 v7, v7, v35
	v_sub_f32_e32 v6, v6, v35
	v_max_f32_e32 v34, v5, v4
	v_exp_f32_e32 v149, v6
	v_exp_f32_e32 v151, v7
	v_sub_f32_e32 v4, v27, v34
	v_sub_f32_e32 v5, v26, v34
	v_sub_f32_e32 v6, v25, v34
	v_sub_f32_e32 v7, v24, v34
	v_exp_f32_e32 v152, v7
	v_exp_f32_e32 v154, v6
	v_exp_f32_e32 v155, v5
	v_exp_f32_e32 v157, v4
	v_sub_f32_e32 v4, v15, v34
	v_sub_f32_e32 v5, v14, v34
	v_sub_f32_e32 v6, v13, v34
	v_sub_f32_e32 v7, v12, v34
	v_sub_f32_e32 v31, v31, v35
	v_sub_f32_e32 v30, v30, v35
	v_sub_f32_e32 v29, v29, v35
	v_sub_f32_e32 v28, v28, v35
	v_sub_f32_e32 v23, v23, v35
	v_sub_f32_e32 v22, v22, v35
	v_sub_f32_e32 v21, v21, v35
	v_sub_f32_e32 v20, v20, v35
	v_sub_f32_e32 v19, v19, v35
	v_sub_f32_e32 v18, v18, v35
	v_sub_f32_e32 v17, v17, v35
	v_sub_f32_e32 v16, v16, v35
	v_exp_f32_e32 v153, v7
	v_exp_f32_e32 v156, v6
	v_exp_f32_e32 v158, v5
	v_exp_f32_e32 v159, v4
	v_sub_f32_e32 v4, v11, v34
	v_sub_f32_e32 v5, v10, v34
	v_sub_f32_e32 v6, v9, v34
	v_sub_f32_e32 v7, v8, v34
	v_sub_f32_e32 v3, v3, v34
	v_sub_f32_e32 v2, v2, v34
	v_sub_f32_e32 v1, v1, v34
	v_sub_f32_e32 v0, v0, v34
	v_exp_f32_e32 v128, v28
	v_exp_f32_e32 v130, v29
	v_exp_f32_e32 v131, v30
	v_exp_f32_e32 v133, v31
	v_exp_f32_e32 v129, v20
	v_exp_f32_e32 v134, v21
	v_exp_f32_e32 v135, v22
	v_exp_f32_e32 v138, v23
	v_exp_f32_e32 v132, v16
	v_exp_f32_e32 v136, v17
	v_exp_f32_e32 v139, v18
	v_exp_f32_e32 v150, v19
	v_exp_f32_e32 v240, v7
	v_exp_f32_e32 v242, v6
	v_exp_f32_e32 v243, v5
	v_exp_f32_e32 v246, v4
	v_exp_f32_e32 v241, v0
	v_exp_f32_e32 v244, v1
	v_exp_f32_e32 v245, v2
	v_exp_f32_e32 v247, v3
	v_lshrrev_b32_e32 v36, 3, v226
	v_pk_add_f32 v[208:209], v[34:35], 0 op_sel_hi:[1,0]
	v_mov_b32_e32 v2, v193
	v_mov_b32_e32 v3, v193
	v_or_b32_e32 v235, s75, v36
	v_xor_b32_e32 v76, 0x80000000, v209
	v_pk_add_f32 v[72:73], v[208:209], 0 neg_lo:[1,1] neg_hi:[1,1]
	v_mov_b32_e32 v0, v193
	v_mov_b32_e32 v1, v193
	v_mov_b64_e32 v[10:11], v[2:3]
	v_mov_b64_e32 v[26:27], v[2:3]
	v_mov_b64_e32 v[18:19], v[2:3]
	v_mov_b64_e32 v[38:39], v[2:3]
	v_mov_b64_e32 v[42:43], v[2:3]
	v_mov_b64_e32 v[50:51], v[2:3]
	v_mov_b64_e32 v[66:67], v[2:3]
	v_mov_b64_e32 v[6:7], v[2:3]
	v_mov_b64_e32 v[14:15], v[2:3]
	v_mov_b64_e32 v[30:31], v[2:3]
	v_mov_b64_e32 v[22:23], v[2:3]
	v_mov_b64_e32 v[34:35], v[2:3]
	v_mov_b64_e32 v[46:47], v[2:3]
	v_mov_b64_e32 v[54:55], v[2:3]
	v_mov_b64_e32 v[62:63], v[2:3]
	v_mov_b64_e32 v[70:71], v[2:3]
	v_mov_b64_e32 v[58:59], v[2:3]
	v_or_b32_e32 v236, 2, v235
	v_cmp_gt_u32_e64 s[4:5], 16, v227
	v_lshl_add_u32 v237, v226, 2, v225
	s_mov_b32 s23, 1
	s_mov_b64 s[6:7], 0
	v_mov_b32_e32 v249, 1.0
	s_mov_b32 s19, 0x10000
	s_movk_i32 s20, 0x4000
	v_mov_b64_e32 v[8:9], v[0:1]
	v_mov_b64_e32 v[24:25], v[0:1]
	v_mov_b64_e32 v[16:17], v[0:1]
	v_mov_b64_e32 v[36:37], v[0:1]
	v_mov_b64_e32 v[40:41], v[0:1]
	v_mov_b64_e32 v[48:49], v[0:1]
	v_mov_b64_e32 v[64:65], v[0:1]
	v_mov_b64_e32 v[4:5], v[0:1]
	v_mov_b64_e32 v[12:13], v[0:1]
	v_mov_b64_e32 v[28:29], v[0:1]
	v_mov_b64_e32 v[20:21], v[0:1]
	v_mov_b64_e32 v[32:33], v[0:1]
	v_mov_b64_e32 v[44:45], v[0:1]
	v_mov_b64_e32 v[52:53], v[0:1]
	v_mov_b64_e32 v[60:61], v[0:1]
	v_mov_b32_e32 v248, 1.0
	v_mov_b64_e32 v[68:69], v[0:1]
	v_mov_b64_e32 v[56:57], v[0:1]
	v_mov_b32_e32 v73, v72
	v_mov_b32_e32 v74, v72
	v_mov_b32_e32 v75, v72
	v_mov_b32_e32 v77, v76
	v_mov_b32_e32 v78, v76
	v_mov_b32_e32 v79, v76
	s_branch .LBB0_369

.LBB0_369:
	s_and_b32 s22, s23, 3
	v_lshl_add_u32 v84, s22, 13, v229
	v_add_u32_e32 v86, v84, v230
	v_add_u32_e32 v87, v84, v231
	ds_read_b128 v[176:179], v228
	ds_read_b128 v[160:163], v86
	ds_read_b128 v[180:183], v228 offset:2048
	ds_read_b128 v[164:167], v87
	ds_read_b128 v[184:187], v228 offset:1024
	ds_read_b128 v[188:191], v228 offset:3072
	ds_read_b128 v[168:171], v86 offset:512
	ds_read_b128 v[172:175], v87 offset:512
	ds_read_b128 v[140:143], v86 offset:4096
	ds_read_b128 v[144:147], v87 offset:4096
	s_and_b32 s0, s19, 0xc000
	v_add_u32_e32 v212, s0, v223
	v_add_u32_e32 v213, s0, v224
	v_cvt_pk_bf16_f32 v120, v241, v244
	v_cvt_pk_bf16_f32 v121, v245, v247
	v_cvt_pk_bf16_f32 v122, v240, v242
	v_cvt_pk_bf16_f32 v123, v243, v246
	v_cvt_pk_bf16_f32 v112, v153, v156
	v_cvt_pk_bf16_f32 v113, v158, v159
	v_cvt_pk_bf16_f32 v114, v152, v154
	v_cvt_pk_bf16_f32 v115, v155, v157
	v_cvt_pk_bf16_f32 v124, v137, v148
	v_cvt_pk_bf16_f32 v125, v149, v151
	v_cvt_pk_bf16_f32 v126, v132, v136
	v_cvt_pk_bf16_f32 v127, v139, v150
	v_cvt_pk_bf16_f32 v116, v129, v134
	v_cvt_pk_bf16_f32 v117, v135, v138
	v_cvt_pk_bf16_f32 v118, v128, v130
	v_cvt_pk_bf16_f32 v119, v131, v133
	s_andn2_b64 vcc, exec, s[6:7]
	s_cbranch_vccz .Lh1a_resc
.Lh1a_resc_ret:
	s_add_i32 s21, s23, 2
	s_min_i32 s12, s21, 0xff
	s_mul_i32 s0, s12, 0xc0000
	s_add_u32 s0, s86, s0
	s_addc_u32 s1, s87, 0
	s_and_b32 s12, s12, 3
	s_lshl_b32 s13, s12, 13
	s_lshl_b32 s12, s12, 14
	s_add_i32 s12, s18, s12
	s_mov_b32 s82, s80
	s_mov_b32 s83, s80
	s_mov_b32 s81, s80
	v_mov_b64_e32 v[154:155], s[82:83]
	v_mov_b64_e32 v[152:153], s[80:81]
	ds_read_b128 v[240:243], v86 offset:4608
	ds_read_b128 v[244:247], v87 offset:4608
	v_mfma_f32_16x16x32_bf16 v[68:71], v[120:123], v[152:155], v[68:71]
	v_mfma_f32_16x16x32_bf16 v[56:59], v[124:127], v[152:155], v[56:59]
	v_mfma_f32_16x16x32_bf16 v[68:71], v[112:115], v[152:155], v[68:71]
	v_mfma_f32_16x16x32_bf16 v[56:59], v[116:119], v[152:155], v[56:59]
	s_waitcnt lgkmcnt(6)
	ds_read_b64_tr_b16 v[128:129], v212
	ds_read_b64_tr_b16 v[130:131], v212 offset:4096
	ds_read_b64_tr_b16 v[132:133], v212 offset:8192
	ds_read_b64_tr_b16 v[134:135], v212 offset:12288
	v_mfma_f32_16x16x32_bf16 v[84:87], v[160:163], v[176:179], v[72:75]
	v_mfma_f32_16x16x32_bf16 v[80:83], v[160:163], v[180:183], v[76:79]
	v_mfma_f32_16x16x32_bf16 v[84:87], v[164:167], v[184:187], v[84:87]
	v_mfma_f32_16x16x32_bf16 v[80:83], v[164:167], v[188:191], v[80:83]
	s_add_i32 m0, s17, s13
	s_nop 0
	global_load_lds_dwordx4 v232, s[0:1]
	s_waitcnt lgkmcnt(8)
	ds_read_b64_tr_b16 v[136:137], v213
	ds_read_b64_tr_b16 v[138:139], v213 offset:4096
	ds_read_b64_tr_b16 v[148:149], v213 offset:8192
	ds_read_b64_tr_b16 v[150:151], v213 offset:12288
	v_mfma_f32_16x16x32_bf16 v[96:99], v[168:171], v[176:179], v[72:75]
	v_mfma_f32_16x16x32_bf16 v[88:91], v[168:171], v[180:183], v[76:79]
	v_mfma_f32_16x16x32_bf16 v[96:99], v[172:175], v[184:187], v[96:99]
	v_mfma_f32_16x16x32_bf16 v[88:91], v[172:175], v[188:191], v[88:91]
	s_mov_b32 m0, s12
	s_nop 0
	global_load_lds_dwordx4 v233, s[0:1]
	s_waitcnt lgkmcnt(10)
	ds_read_b64_tr_b16 v[152:153], v212 offset:1024
	ds_read_b64_tr_b16 v[154:155], v212 offset:5120
	ds_read_b64_tr_b16 v[156:157], v212 offset:9216
	ds_read_b64_tr_b16 v[158:159], v212 offset:13312
	v_mfma_f32_16x16x32_bf16 v[100:103], v[140:143], v[176:179], v[72:75]
	v_mfma_f32_16x16x32_bf16 v[92:95], v[140:143], v[180:183], v[76:79]
	v_mfma_f32_16x16x32_bf16 v[100:103], v[144:147], v[184:187], v[100:103]
	v_mfma_f32_16x16x32_bf16 v[92:95], v[144:147], v[188:191], v[92:95]
	s_add_i32 m0, s12, 0x2000
	s_nop 0
	global_load_lds_dwordx4 v234, s[0:1]
	s_waitcnt lgkmcnt(12)
	v_mfma_f32_16x16x32_bf16 v[108:111], v[240:243], v[176:179], v[72:75]
	v_mfma_f32_16x16x32_bf16 v[104:107], v[240:243], v[180:183], v[76:79]
	v_mfma_f32_16x16x32_bf16 v[108:111], v[244:247], v[184:187], v[108:111]
	v_mfma_f32_16x16x32_bf16 v[104:107], v[244:247], v[188:191], v[104:107]
	s_cmp_le_i32 s23, s75
	s_cbranch_scc0 .LBB0_379

.LBB0_373:
	s_waitcnt lgkmcnt(8)
	ds_read_b64_tr_b16 v[240:241], v212 offset:2048
	ds_read_b64_tr_b16 v[242:243], v212 offset:6144
	ds_read_b64_tr_b16 v[244:245], v212 offset:10240
	ds_read_b64_tr_b16 v[246:247], v212 offset:14336
	v_mfma_f32_16x16x32_bf16 v[52:55], v[120:123], v[136:139], v[52:55]
	v_exp_f32_e32 v162, v84
	v_mfma_f32_16x16x32_bf16 v[48:51], v[124:127], v[136:139], v[48:51]
	v_exp_f32_e32 v163, v85
	v_mfma_f32_16x16x32_bf16 v[52:55], v[112:115], v[148:151], v[52:55]
	v_exp_f32_e32 v161, v86
	v_mfma_f32_16x16x32_bf16 v[48:51], v[116:119], v[148:151], v[48:51]
	v_exp_f32_e32 v160, v87
	v_exp_f32_e32 v167, v96
	s_waitcnt lgkmcnt(8)
	ds_read_b64_tr_b16 v[128:129], v213 offset:2048
	ds_read_b64_tr_b16 v[130:131], v213 offset:6144
	ds_read_b64_tr_b16 v[132:133], v213 offset:10240
	ds_read_b64_tr_b16 v[134:135], v213 offset:14336
	v_mfma_f32_16x16x32_bf16 v[44:47], v[120:123], v[152:155], v[44:47]
	v_exp_f32_e32 v166, v97
	v_mfma_f32_16x16x32_bf16 v[40:43], v[124:127], v[152:155], v[40:43]
	v_exp_f32_e32 v164, v98
	v_mfma_f32_16x16x32_bf16 v[44:47], v[112:115], v[156:159], v[44:47]
	v_exp_f32_e32 v165, v99
	v_mfma_f32_16x16x32_bf16 v[40:43], v[116:119], v[156:159], v[40:43]
	v_exp_f32_e32 v171, v100
	v_exp_f32_e32 v170, v101
	s_waitcnt lgkmcnt(8)
	ds_read_b64_tr_b16 v[136:137], v212 offset:3072
	ds_read_b64_tr_b16 v[138:139], v212 offset:7168
	ds_read_b64_tr_b16 v[148:149], v212 offset:11264
	ds_read_b64_tr_b16 v[150:151], v212 offset:15360
	v_mfma_f32_16x16x32_bf16 v[32:35], v[120:123], v[140:143], v[32:35]
	v_exp_f32_e32 v169, v102
	v_mfma_f32_16x16x32_bf16 v[36:39], v[124:127], v[140:143], v[36:39]
	v_exp_f32_e32 v168, v103
	v_mfma_f32_16x16x32_bf16 v[32:35], v[112:115], v[144:147], v[32:35]
	v_exp_f32_e32 v178, v108
	v_mfma_f32_16x16x32_bf16 v[36:39], v[116:119], v[144:147], v[36:39]
	v_exp_f32_e32 v179, v109
	v_exp_f32_e32 v177, v110
	s_waitcnt lgkmcnt(8)
	ds_read_b64_tr_b16 v[152:153], v213 offset:3072
	ds_read_b64_tr_b16 v[154:155], v213 offset:7168
	ds_read_b64_tr_b16 v[156:157], v213 offset:11264
	ds_read_b64_tr_b16 v[158:159], v213 offset:15360
	v_mfma_f32_16x16x32_bf16 v[20:23], v[120:123], v[240:243], v[20:23]
	v_exp_f32_e32 v176, v111
	v_mfma_f32_16x16x32_bf16 v[16:19], v[124:127], v[240:243], v[16:19]
	v_exp_f32_e32 v175, v80
	v_mfma_f32_16x16x32_bf16 v[20:23], v[112:115], v[244:247], v[20:23]
	v_exp_f32_e32 v174, v81
	v_mfma_f32_16x16x32_bf16 v[16:19], v[116:119], v[244:247], v[16:19]
	v_exp_f32_e32 v172, v82
	v_exp_f32_e32 v173, v83
	s_waitcnt lgkmcnt(8)
	v_mfma_f32_16x16x32_bf16 v[28:31], v[120:123], v[128:131], v[28:31]
	v_exp_f32_e32 v183, v88
	v_mfma_f32_16x16x32_bf16 v[24:27], v[124:127], v[128:131], v[24:27]
	v_exp_f32_e32 v182, v89
	v_mfma_f32_16x16x32_bf16 v[28:31], v[112:115], v[132:135], v[28:31]
	v_exp_f32_e32 v181, v90
	v_mfma_f32_16x16x32_bf16 v[24:27], v[116:119], v[132:135], v[24:27]
	v_exp_f32_e32 v180, v91
	s_waitcnt lgkmcnt(4)
	v_mfma_f32_16x16x32_bf16 v[12:15], v[120:123], v[136:139], v[12:15]
	v_exp_f32_e32 v186, v92
	v_mfma_f32_16x16x32_bf16 v[8:11], v[124:127], v[136:139], v[8:11]
	v_exp_f32_e32 v187, v93
	v_mfma_f32_16x16x32_bf16 v[12:15], v[112:115], v[148:151], v[12:15]
	v_exp_f32_e32 v185, v94
	v_mfma_f32_16x16x32_bf16 v[8:11], v[116:119], v[148:151], v[8:11]
	v_exp_f32_e32 v184, v95
	s_waitcnt lgkmcnt(0)
	v_mfma_f32_16x16x32_bf16 v[4:7], v[120:123], v[152:155], v[4:7]
	v_exp_f32_e32 v191, v104
	v_mfma_f32_16x16x32_bf16 v[0:3], v[124:127], v[152:155], v[0:3]
	v_exp_f32_e32 v190, v105
	v_mfma_f32_16x16x32_bf16 v[4:7], v[112:115], v[156:159], v[4:7]
	v_exp_f32_e32 v189, v106
	v_mfma_f32_16x16x32_bf16 v[0:3], v[116:119], v[156:159], v[0:3]
	v_exp_f32_e32 v188, v107
	s_waitcnt vmcnt(3)
	s_waitcnt lgkmcnt(0)
	s_add_i32 s0, s23, 1
	s_cmp_ge_i32 s0, s14
	s_mov_b64 s[0:1], -1
	s_barrier
	s_cbranch_scc1 .LBB0_368
	s_and_b32 s0, s20, 0x6000
	v_add_u32_e32 v84, s0, v229
	v_add_u32_e32 v86, v84, v230
	v_add_u32_e32 v87, v84, v231
	ds_read_b128 v[240:243], v228
	ds_read_b128 v[128:131], v86
	ds_read_b128 v[244:247], v228 offset:2048
	ds_read_b128 v[132:135], v87
	ds_read_b128 v[152:155], v228 offset:1024
	ds_read_b128 v[156:159], v228 offset:3072
	ds_read_b128 v[136:139], v86 offset:512
	ds_read_b128 v[148:151], v87 offset:512
	ds_read_b128 v[140:143], v86 offset:4096
	ds_read_b128 v[144:147], v87 offset:4096
	s_lshl_b32 s0, s22, 14
	v_add_u32_e32 v214, s0, v223
	v_add_u32_e32 v215, s0, v224
	v_cvt_pk_bf16_f32 v120, v162, v163
	v_cvt_pk_bf16_f32 v121, v161, v160
	v_cvt_pk_bf16_f32 v122, v167, v166
	v_cvt_pk_bf16_f32 v123, v164, v165
	v_cvt_pk_bf16_f32 v112, v171, v170
	v_cvt_pk_bf16_f32 v113, v169, v168
	v_cvt_pk_bf16_f32 v114, v178, v179
	v_cvt_pk_bf16_f32 v115, v177, v176
	v_cvt_pk_bf16_f32 v124, v175, v174
	v_cvt_pk_bf16_f32 v125, v172, v173
	v_cvt_pk_bf16_f32 v126, v183, v182
	v_cvt_pk_bf16_f32 v127, v181, v180
	v_cvt_pk_bf16_f32 v116, v186, v187
	v_cvt_pk_bf16_f32 v117, v185, v184
	v_cvt_pk_bf16_f32 v118, v191, v190
	v_cvt_pk_bf16_f32 v119, v189, v188
	s_andn2_b64 vcc, exec, s[12:13]
	s_cbranch_vccz .Lh2a_resc
.Lh2a_resc_ret:
	s_min_i32 s0, s23, 0xfc
	s_add_i32 s6, s0, 3
	s_mul_i32 s0, s6, 0xc0000
	s_add_u32 s0, s86, s0
	s_addc_u32 s1, s87, 0
	s_and_b32 s6, s6, 3
	s_lshl_b32 s7, s6, 13
	s_lshl_b32 s6, s6, 14
	s_add_i32 s6, s18, s6
	s_mov_b32 s82, s80
	s_mov_b32 s83, s80
	s_mov_b32 s81, s80
	v_mov_b64_e32 v[186:187], s[82:83]
	v_mov_b64_e32 v[184:185], s[80:81]
	ds_read_b128 v[160:163], v86 offset:4608
	ds_read_b128 v[164:167], v87 offset:4608
	v_mfma_f32_16x16x32_bf16 v[68:71], v[120:123], v[184:187], v[68:71]
	v_mfma_f32_16x16x32_bf16 v[56:59], v[124:127], v[184:187], v[56:59]
	v_mfma_f32_16x16x32_bf16 v[68:71], v[112:115], v[184:187], v[68:71]
	v_mfma_f32_16x16x32_bf16 v[56:59], v[116:119], v[184:187], v[56:59]
	s_waitcnt lgkmcnt(6)
	ds_read_b64_tr_b16 v[168:169], v214
	ds_read_b64_tr_b16 v[170:171], v214 offset:4096
	ds_read_b64_tr_b16 v[172:173], v214 offset:8192
	ds_read_b64_tr_b16 v[174:175], v214 offset:12288
	v_mfma_f32_16x16x32_bf16 v[84:87], v[128:131], v[240:243], v[72:75]
	v_mfma_f32_16x16x32_bf16 v[80:83], v[128:131], v[244:247], v[76:79]
	v_mfma_f32_16x16x32_bf16 v[84:87], v[132:135], v[152:155], v[84:87]
	v_mfma_f32_16x16x32_bf16 v[80:83], v[132:135], v[156:159], v[80:83]
	s_add_i32 m0, s17, s7
	s_nop 0
	global_load_lds_dwordx4 v232, s[0:1]
	s_waitcnt lgkmcnt(8)
	ds_read_b64_tr_b16 v[176:177], v215
	ds_read_b64_tr_b16 v[178:179], v215 offset:4096
	ds_read_b64_tr_b16 v[180:181], v215 offset:8192
	ds_read_b64_tr_b16 v[182:183], v215 offset:12288
	v_mfma_f32_16x16x32_bf16 v[96:99], v[136:139], v[240:243], v[72:75]
	v_mfma_f32_16x16x32_bf16 v[88:91], v[136:139], v[244:247], v[76:79]
	v_mfma_f32_16x16x32_bf16 v[96:99], v[148:151], v[152:155], v[96:99]
	v_mfma_f32_16x16x32_bf16 v[88:91], v[148:151], v[156:159], v[88:91]
	s_mov_b32 m0, s6
	s_nop 0
	global_load_lds_dwordx4 v233, s[0:1]
	s_waitcnt lgkmcnt(10)
	ds_read_b64_tr_b16 v[184:185], v214 offset:1024
	ds_read_b64_tr_b16 v[186:187], v214 offset:5120
	ds_read_b64_tr_b16 v[188:189], v214 offset:9216
	ds_read_b64_tr_b16 v[190:191], v214 offset:13312
	v_mfma_f32_16x16x32_bf16 v[100:103], v[140:143], v[240:243], v[72:75]
	v_mfma_f32_16x16x32_bf16 v[92:95], v[140:143], v[244:247], v[76:79]
	v_mfma_f32_16x16x32_bf16 v[100:103], v[144:147], v[152:155], v[100:103]
	v_mfma_f32_16x16x32_bf16 v[92:95], v[144:147], v[156:159], v[92:95]
	s_add_i32 m0, s6, 0x2000
	s_nop 0
	global_load_lds_dwordx4 v234, s[0:1]
	s_waitcnt lgkmcnt(12)
	v_mfma_f32_16x16x32_bf16 v[108:111], v[160:163], v[240:243], v[72:75]
	v_mfma_f32_16x16x32_bf16 v[104:107], v[160:163], v[244:247], v[76:79]
	v_mfma_f32_16x16x32_bf16 v[108:111], v[164:167], v[152:155], v[108:111]
	v_mfma_f32_16x16x32_bf16 v[104:107], v[164:167], v[156:159], v[104:107]
	s_cmp_lt_i32 s23, s75
	s_cbranch_scc0 .LBB0_384

; DEV unsigned cvtpk(float lo, float hi) { f32x2_t v = {lo, hi}; bf16x2_t b = __builtin_convertvector(v, bf16x2_t); return __builtin_bit_cast(unsigned, b); }
; #define VWAIT(n) asm volatile("s_waitcnt vmcnt(" #n ")" ::: "memory")
; #define LBAR() do { asm volatile("s_waitcnt lgkmcnt(0)" ::: "memory"); __builtin_amdgcn_s_barrier(); } while (0)
; #define VWAIT(n) asm volatile("s_waitcnt vmcnt(" #n ")" ::: "memory")
; #define LBAR() do { asm volatile("s_waitcnt lgkmcnt(0)" ::: "memory"); __builtin_amdgcn_s_barrier(); } while (0)
; #define SUMPACK16(S, al) do { _Pragma("unroll") for (int g = 0; g < 2; ++g) { pa[g][0] = PKS(S, g, 0); pa[g][1] = PKS(S, g, 1); } } while (0)
; #define PVL() do { ol[0] = MF16(pa[0][0], ones, ol[0]); ol[1] = MF16(pa[1][0], ones, ol[1]); ol[0] = MF16(pa[0][1], ones, ol[0]); ol[1] = MF16(pa[1][1], ones, ol[1]); } while (0)
; DEV void diff16_pass(const bf16_t* __restrict__ proj, int qcol, int kcol, int vcol, int q0, f32x4 (&o)[2][8], f32x4 (&l_out)[2], unsigned char* lds) {
;     ...
;   { SUMPACK16(SB2, alB); DRESC16(alB, rfB); PVL(); const lds_cptr vE_ = vrdE + ((NT - 1) & 3) * D_VSLOT, vO_ = vrdO + ((NT - 1) & 3) * D_VSLOT;
;     PV16(0, vE_, vO_); PV16(1, vE_, vO_); PV16(2, vE_, vO_); PV16(3, vE_, vO_); PV16(4, vE_, vO_); PV16(5, vE_, vO_); PV16(6, vE_, vO_); PV16(7, vE_, vO_); }
;   VWAIT(0); LBAR();
;   l_out[0] = ol[0]; l_out[1] = ol[1];
; DEV void attn_phase(const Params& p, int layer) {
;     ...
;         for (int g = 0; g < 2; ++g) { const f32x4 l4 = ld[g];
;           const f32x4 il = {__builtin_amdgcn_rcpf(l4[0]), __builtin_amdgcn_rcpf(l4[1]), __builtin_amdgcn_rcpf(l4[2]), __builtin_amdgcn_rcpf(l4[3])};
; #pragma unroll
;           for (int cb = 0; cb < 8; cb += 2) { const f32x4 a4 = od[g][cb] * il, b4 = od[g][cb + 1] * il;
;             const u32x4 w = {cvtpk(a4[0], a4[1]), cvtpk(a4[2], a4[3]), cvtpk(b4[0], b4[1]), cvtpk(b4[2], b4[3])};
;             *reinterpret_cast<u32x4*>((bf16_t*)o1s + (wid * 8 + g * 4 + (cb >> 1)) * 512 + lane * 8) = w; } }
.LBB0_393:
	v_cvt_pk_bf16_f32 v72, v162, v163
	v_cvt_pk_bf16_f32 v73, v161, v160
	v_cvt_pk_bf16_f32 v74, v167, v166
	v_cvt_pk_bf16_f32 v75, v164, v165
	v_cvt_pk_bf16_f32 v84, v175, v174
	v_cvt_pk_bf16_f32 v85, v172, v173
	v_cvt_pk_bf16_f32 v86, v183, v182
	v_cvt_pk_bf16_f32 v87, v181, v180
	s_mov_b32 s82, s80
	s_mov_b32 s83, s80
	s_mov_b32 s81, s80
	v_mov_b64_e32 v[94:95], s[82:83]
	v_cvt_pk_bf16_f32 v76, v171, v170
	v_cvt_pk_bf16_f32 v77, v169, v168
	v_cvt_pk_bf16_f32 v78, v178, v179
	v_cvt_pk_bf16_f32 v79, v177, v176
	v_cvt_pk_bf16_f32 v88, v186, v187
	v_cvt_pk_bf16_f32 v89, v185, v184
	v_cvt_pk_bf16_f32 v90, v191, v190
	v_cvt_pk_bf16_f32 v91, v189, v188
	v_mov_b64_e32 v[92:93], s[80:81]
	v_readlane_b32 s0, v255, 57
	v_readlane_b32 s1, v255, 58
	v_mfma_f32_16x16x32_bf16 v[68:71], v[72:75], v[92:95], v[68:71]
	s_andn2_b64 vcc, exec, s[10:11]
	v_mfma_f32_16x16x32_bf16 v[56:59], v[84:87], v[92:95], v[56:59]
	v_mfma_f32_16x16x32_bf16 v[80:83], v[76:79], v[92:95], v[68:71]
	v_mfma_f32_16x16x32_bf16 v[68:71], v[88:91], v[92:95], v[56:59]
	s_nop 5
	ds_read_b64_tr_b16 v[56:57], v223 offset:49152
	ds_read_b64_tr_b16 v[58:59], v223 offset:53248
	ds_read_b64_tr_b16 v[92:93], v223 offset:57344
	ds_read_b64_tr_b16 v[94:95], v223 offset:61440
	s_waitcnt lgkmcnt(0)
	v_mfma_f32_16x16x32_bf16 v[60:63], v[72:75], v[56:59], v[60:63]
	v_mfma_f32_16x16x32_bf16 v[56:59], v[84:87], v[56:59], v[64:67]
	v_mfma_f32_16x16x32_bf16 v[60:63], v[76:79], v[92:95], v[60:63]
	v_mfma_f32_16x16x32_bf16 v[56:59], v[88:91], v[92:95], v[56:59]
	s_nop 0
	ds_read_b64_tr_b16 v[64:65], v224 offset:49152
	ds_read_b64_tr_b16 v[66:67], v224 offset:53248
	ds_read_b64_tr_b16 v[92:93], v224 offset:57344
	ds_read_b64_tr_b16 v[94:95], v224 offset:61440
	s_waitcnt lgkmcnt(0)
	v_mfma_f32_16x16x32_bf16 v[52:55], v[72:75], v[64:67], v[52:55]
	v_mfma_f32_16x16x32_bf16 v[48:51], v[84:87], v[64:67], v[48:51]
	v_mfma_f32_16x16x32_bf16 v[52:55], v[76:79], v[92:95], v[52:55]
	v_mfma_f32_16x16x32_bf16 v[48:51], v[88:91], v[92:95], v[48:51]
	ds_read_b64_tr_b16 v[64:65], v223 offset:50176
	ds_read_b64_tr_b16 v[66:67], v223 offset:54272
	ds_read_b64_tr_b16 v[92:93], v223 offset:58368
	ds_read_b64_tr_b16 v[94:95], v223 offset:62464
	s_waitcnt lgkmcnt(0)
	v_mfma_f32_16x16x32_bf16 v[44:47], v[72:75], v[64:67], v[44:47]
	v_mfma_f32_16x16x32_bf16 v[40:43], v[84:87], v[64:67], v[40:43]
	v_mfma_f32_16x16x32_bf16 v[44:47], v[76:79], v[92:95], v[44:47]
	v_mfma_f32_16x16x32_bf16 v[40:43], v[88:91], v[92:95], v[40:43]
	ds_read_b64_tr_b16 v[64:65], v224 offset:50176
	ds_read_b64_tr_b16 v[66:67], v224 offset:54272
	ds_read_b64_tr_b16 v[92:93], v224 offset:58368
	ds_read_b64_tr_b16 v[94:95], v224 offset:62464
	s_waitcnt lgkmcnt(0)
	v_mfma_f32_16x16x32_bf16 v[32:35], v[72:75], v[64:67], v[32:35]
	v_mfma_f32_16x16x32_bf16 v[64:67], v[84:87], v[64:67], v[36:39]
	v_mfma_f32_16x16x32_bf16 v[36:39], v[76:79], v[92:95], v[32:35]
	v_mfma_f32_16x16x32_bf16 v[32:35], v[88:91], v[92:95], v[64:67]
	s_nop 5
	ds_read_b64_tr_b16 v[64:65], v223 offset:51200
	ds_read_b64_tr_b16 v[66:67], v223 offset:55296
	ds_read_b64_tr_b16 v[92:93], v223 offset:59392
	ds_read_b64_tr_b16 v[94:95], v223 offset:63488
	s_waitcnt lgkmcnt(0)
	v_mfma_f32_16x16x32_bf16 v[20:23], v[72:75], v[64:67], v[20:23]
	v_mfma_f32_16x16x32_bf16 v[16:19], v[84:87], v[64:67], v[16:19]
	v_mfma_f32_16x16x32_bf16 v[64:67], v[76:79], v[92:95], v[20:23]
	v_mfma_f32_16x16x32_bf16 v[16:19], v[88:91], v[92:95], v[16:19]
	s_nop 4
	ds_read_b64_tr_b16 v[20:21], v224 offset:51200
	ds_read_b64_tr_b16 v[22:23], v224 offset:55296
	ds_read_b64_tr_b16 v[92:93], v224 offset:59392
	ds_read_b64_tr_b16 v[94:95], v224 offset:63488
	s_waitcnt lgkmcnt(0)
	v_mfma_f32_16x16x32_bf16 v[28:31], v[72:75], v[20:23], v[28:31]
	v_mfma_f32_16x16x32_bf16 v[20:23], v[84:87], v[20:23], v[24:27]
	v_mfma_f32_16x16x32_bf16 v[24:27], v[76:79], v[92:95], v[28:31]
	v_mfma_f32_16x16x32_bf16 v[20:23], v[88:91], v[92:95], v[20:23]
	s_nop 4
	ds_read_b64_tr_b16 v[28:29], v223 offset:52224
	ds_read_b64_tr_b16 v[30:31], v223 offset:56320
	ds_read_b64_tr_b16 v[92:93], v223 offset:60416
	ds_read_b64_tr_b16 v[94:95], v223 offset:64512
	s_waitcnt lgkmcnt(0)
	v_mfma_f32_16x16x32_bf16 v[12:15], v[72:75], v[28:31], v[12:15]
	v_mfma_f32_16x16x32_bf16 v[8:11], v[84:87], v[28:31], v[8:11]
	v_mfma_f32_16x16x32_bf16 v[12:15], v[76:79], v[92:95], v[12:15]
	v_mfma_f32_16x16x32_bf16 v[8:11], v[88:91], v[92:95], v[8:11]
	ds_read_b64_tr_b16 v[28:29], v224 offset:52224
	ds_read_b64_tr_b16 v[30:31], v224 offset:56320
	ds_read_b64_tr_b16 v[92:93], v224 offset:60416
	ds_read_b64_tr_b16 v[94:95], v224 offset:64512
	s_waitcnt vmcnt(0)
	s_waitcnt lgkmcnt(0)
	s_waitcnt lgkmcnt(0)
	v_mfma_f32_16x16x32_bf16 v[4:7], v[72:75], v[28:31], v[4:7]
	v_rcp_f32_e32 v72, v80
	v_rcp_f32_e32 v73, v81
	v_rcp_f32_e32 v74, v82
	v_rcp_f32_e32 v75, v83
	v_mfma_f32_16x16x32_bf16 v[0:3], v[84:87], v[28:31], v[0:3]
	v_mul_f32_e64 v28, v72, v60
	v_mul_f32_e64 v29, v73, v61
	v_pk_mul_f32 v[52:53], v[72:73], v[52:53]
	v_pk_mul_f32 v[30:31], v[74:75], v[62:63]
	v_pk_mul_f32 v[54:55], v[74:75], v[54:55]
	v_cvt_pk_bf16_f32 v28, v28, v29
	v_cvt_pk_bf16_f32 v29, v30, v31
	v_cvt_pk_bf16_f32 v30, v52, v53
	v_cvt_pk_bf16_f32 v31, v54, v55
	v_mfma_f32_16x16x32_bf16 v[4:7], v[76:79], v[92:95], v[4:7]
	s_barrier
; DEV unsigned cvtpk(float lo, float hi) { f32x2_t v = {lo, hi}; bf16x2_t b = __builtin_convertvector(v, bf16x2_t); return __builtin_bit_cast(unsigned, b); }
; DEV void diff16_pass(const bf16_t* __restrict__ proj, int qcol, int kcol, int vcol, int q0, f32x4 (&o)[2][8], f32x4 (&l_out)[2], unsigned char* lds) {
;     ...
;   for (int g = 0; g < 2; ++g) { const int sl = 16 * g + fr; const bf16_t* Qw = proj + (size_t)(q0 + 64 * (sl >> 3) + 8 * wid + (sl & 7)) * INW + qcol + fq * 8;
;     *reinterpret_cast<bf16x8*>(lds + D_QOFF + wid * 4096 + (g * 2 + 0) * 1024 + lane * 16) = *reinterpret_cast<const bf16x8*>(Qw);
;     *reinterpret_cast<bf16x8*>(lds + D_QOFF + wid * 4096 + (g * 2 + 1) * 1024 + lane * 16) = *reinterpret_cast<const bf16x8*>(Qw + 32); }
;   const int c0 = q0 >> 6, NT = c0 + 4, lim0 = c0 + (fr >> 3), lim1 = c0 + 2 + (fr >> 3);
;   const int kf = ((fr >> 1) & 1) | ((fr >> 2) << 1);
;   const lds_cptr krd = (lds_cptr)shm_raw + D_KOFF + (8 * (fr >> 2) + (fr & 3)) * 128;
;   const int kch0 = ((0 + fq) ^ kf) << 4, kch1 = ((4 + fq) ^ kf) << 4;
;   const int vlane = (fq >> 1) * 512 + (fq & 1) * 256 + (fr >> 2) * 64 + (fr & 3) * 8;
;   const lds_cptr vrdE = (lds_cptr)shm_raw + vlane + (fq & 1) * 32, vrdO = (lds_cptr)shm_raw + vlane + (1 - (fq & 1)) * 32;
;   typedef unsigned char __attribute__((address_space(3))) lds_u8w;
;   lds_u8w* ldsw = (lds_u8w*)shm_raw;
;   unsigned Kg, Vg0, Vg1;
;   { const int r = tid >> 3, fK = ((r >> 1) & 1) | (((r >> 3) & 3) << 1); Kg = (unsigned)(r * INW + kcol + (((tid & 7) ^ fK) * 8)) * 2u;
;     ...
;     VSRC(tid, Vg0); VSRC(512 + tid, Vg1);
;     ...
;   }
;   const unsigned dmaw = (unsigned)__builtin_amdgcn_readfirstlane(wid) * 1024u;
; DEV void attn_phase(const Params& p, int layer) {
;     ...
;         for (int g = 0; g < 2; ++g) { const f32x4 l4 = ld[g];
;           const f32x4 il = {__builtin_amdgcn_rcpf(l4[0]), __builtin_amdgcn_rcpf(l4[1]), __builtin_amdgcn_rcpf(l4[2]), __builtin_amdgcn_rcpf(l4[3])};
; #pragma unroll
;           for (int cb = 0; cb < 8; cb += 2) { const f32x4 a4 = od[g][cb] * il, b4 = od[g][cb + 1] * il;
;             const u32x4 w = {cvtpk(a4[0], a4[1]), cvtpk(a4[2], a4[3]), cvtpk(b4[0], b4[1]), cvtpk(b4[2], b4[3])};
;             *reinterpret_cast<u32x4*>((bf16_t*)o1s + (wid * 8 + g * 4 + (cb >> 1)) * 512 + lane * 8) = w; } }
	global_store_dwordx4 v[196:197], v[28:31], off
	v_pk_mul_f32 v[38:39], v[74:75], v[38:39]
	v_pk_mul_f32 v[36:37], v[72:73], v[36:37]
	v_pk_mul_f32 v[30:31], v[74:75], v[46:47]
	v_pk_mul_f32 v[28:29], v[72:73], v[44:45]
	v_pk_mul_f32 v[14:15], v[74:75], v[14:15]
	v_cvt_pk_bf16_f32 v28, v28, v29
	v_cvt_pk_bf16_f32 v29, v30, v31
	v_cvt_pk_bf16_f32 v30, v36, v37
	v_cvt_pk_bf16_f32 v31, v38, v39
	global_store_dwordx4 v[196:197], v[28:31], off offset:1024
	v_pk_mul_f32 v[36:37], v[74:75], v[26:27]
	v_pk_mul_f32 v[26:27], v[72:73], v[24:25]
	v_pk_mul_f32 v[28:29], v[74:75], v[66:67]
	v_pk_mul_f32 v[30:31], v[72:73], v[64:65]
	v_cvt_pk_bf16_f32 v25, v28, v29
	v_cvt_pk_bf16_f32 v24, v30, v31
	v_cvt_pk_bf16_f32 v26, v26, v27
	v_cvt_pk_bf16_f32 v27, v36, v37
	v_pk_mul_f32 v[12:13], v[72:73], v[12:13]
	global_store_dwordx4 v[196:197], v[24:27], off offset:2048
	v_mfma_f32_16x16x32_bf16 v[0:3], v[88:91], v[92:95], v[0:3]
	s_nop 0
	v_mul_f32_e64 v24, v74, v6
	v_mul_f32_e64 v25, v75, v7
	v_pk_mul_f32 v[6:7], v[72:73], v[4:5]
	v_cvt_pk_bf16_f32 v4, v12, v13
	v_cvt_pk_bf16_f32 v5, v14, v15
	v_rcp_f32_e32 v12, v68
	v_rcp_f32_e32 v13, v69
	v_rcp_f32_e32 v14, v70
	v_rcp_f32_e32 v15, v71
	v_cvt_pk_bf16_f32 v6, v6, v7
	v_cvt_pk_bf16_f32 v7, v24, v25
	global_store_dwordx4 v[196:197], v[4:7], off offset:3072
	v_pk_mul_f32 v[24:25], v[14:15], v[50:51]
	v_pk_mul_f32 v[26:27], v[12:13], v[48:49]
	v_pk_mul_f32 v[6:7], v[14:15], v[58:59]
	v_pk_mul_f32 v[4:5], v[12:13], v[56:57]
	s_nop 0
	v_cvt_pk_bf16_f32 v4, v4, v5
	v_cvt_pk_bf16_f32 v5, v6, v7
	v_cvt_pk_bf16_f32 v6, v26, v27
	v_cvt_pk_bf16_f32 v7, v24, v25
	global_store_dwordx4 v[198:199], v[4:7], off
	v_pk_mul_f32 v[24:25], v[14:15], v[34:35]
	v_pk_mul_f32 v[26:27], v[12:13], v[32:33]
	v_pk_mul_f32 v[6:7], v[14:15], v[42:43]
	v_pk_mul_f32 v[4:5], v[12:13], v[40:41]
	s_nop 0
	v_cvt_pk_bf16_f32 v4, v4, v5
	v_cvt_pk_bf16_f32 v5, v6, v7
	v_cvt_pk_bf16_f32 v6, v26, v27
	v_cvt_pk_bf16_f32 v7, v24, v25
	global_store_dwordx4 v[200:201], v[4:7], off
	s_nop 1
	v_pk_mul_f32 v[6:7], v[14:15], v[18:19]
	v_pk_mul_f32 v[4:5], v[12:13], v[16:17]
	v_pk_mul_f32 v[16:17], v[14:15], v[22:23]
	v_pk_mul_f32 v[18:19], v[12:13], v[20:21]
	v_cvt_pk_bf16_f32 v4, v4, v5
	v_cvt_pk_bf16_f32 v5, v6, v7
	v_cvt_pk_bf16_f32 v6, v18, v19
	v_cvt_pk_bf16_f32 v7, v16, v17
	global_store_dwordx4 v[202:203], v[4:7], off
	v_mov_b32_e32 v17, 0x2000
	s_nop 0
	v_pk_mul_f32 v[4:5], v[14:15], v[10:11]
	v_pk_mul_f32 v[6:7], v[12:13], v[8:9]
	v_pk_mul_f32 v[8:9], v[14:15], v[2:3]
	v_pk_mul_f32 v[2:3], v[12:13], v[0:1]
	v_cvt_pk_bf16_f32 v0, v6, v7
	v_cvt_pk_bf16_f32 v1, v4, v5
	v_cvt_pk_bf16_f32 v2, v2, v3
	v_cvt_pk_bf16_f32 v3, v8, v9
	v_mov_b32_e32 v8, v210
	global_store_dwordx4 v[204:205], v[0:3], off
	s_nop 0
	v_ashrrev_i32_e32 v9, 6, v8
	v_and_b32_e32 v0, 0x3fffffc0, v8
	v_lshlrev_b32_e32 v12, 3, v8
	v_and_b32_e32 v13, 7, v8
	v_lshl_add_u32 v225, v0, 2, s16
	v_and_b32_e32 v0, 64, v12
	v_lshlrev_b32_e32 v1, 3, v9
	v_or_b32_e32 v2, s74, v13
	v_and_b32_e32 v192, 48, v8
	v_add3_u32 v14, v2, v1, v0
	v_lshl_add_u64 v[4:5], s[0:1], 0, v[192:193]
	v_readlane_b32 s0, v255, 10
	v_and_b32_e32 v227, 63, v8
	v_lshlrev_b32_e32 v11, 4, v227
	v_lshl_add_u32 v15, v9, 12, s0
	v_mad_i64_i32 v[6:7], s[0:1], v14, s85, v[4:5]
	global_load_dwordx4 v[0:3], v[6:7], off
	global_load_dwordx4 v[96:99], v[6:7], off offset:64
	v_add_u32_e32 v108, 0x80, v14
	v_mad_i64_i32 v[4:5], s[0:1], v108, s85, v[4:5]
	global_load_dwordx4 v[100:103], v[4:5], off
	global_load_dwordx4 v[104:107], v[4:5], off offset:64
	v_add_u32_e32 v228, v15, v11
	v_bfe_u32 v10, v8, 4, 2
	v_lshrrev_b32_e32 v15, 6, v8
	v_and_b32_e32 v15, 4, v15
	v_lshl_add_u32 v17, v8, 4, v17
	v_lshrrev_b32_e32 v17, 8, v17
	v_and_b32_e32 v226, 15, v8
	s_waitcnt vmcnt(0)
	ds_write_b128 v228, v[0:3]
	ds_write_b128 v228, v[96:99] offset:1024
	ds_write_b128 v228, v[100:103] offset:2048
	ds_write_b128 v228, v[104:107] offset:3072
	v_or_b32_e32 v6, 4, v10
	s_movk_i32 s0, 0x1800
	v_lshrrev_b32_e32 v14, 5, v8
	v_and_b32_e32 v14, 6, v14
	v_bfe_u32 v2, v8, 2, 2
	v_bfe_u32 v1, v8, 1, 1
	v_lshlrev_b32_e32 v3, 1, v2
	v_bitop3_b32 v5, v3, v10, v1 bitop3:0x36
	v_bitop3_b32 v1, v3, v6, v1 bitop3:0x36
	v_bfe_u32 v6, v227, 4, 1
	v_lshlrev_b32_e32 v7, 8, v6
	v_lshlrev_b32_e32 v48, 5, v6
	v_lshrrev_b32_e32 v6, 3, v8
	v_and_b32_e32 v3, 0x200, v11
	v_mul_lo_u32 v6, v6, s0
	v_readlane_b32 s0, v255, 54
	v_add3_u32 v3, 0, v3, v7
	v_lshrrev_b32_e32 v7, 4, v8
	v_bfe_u32 v11, v8, 4, 1
	v_add_lshl_u32 v6, s0, v6, 1
	s_mov_b32 s0, 0x1fffe0
	v_bitop3_b32 v11, v11, v13, v14 bitop3:0x36
	v_bfe_u32 v13, v8, 1, 27
	v_and_or_b32 v16, v7, s0, v15
	v_readlane_b32 s0, v255, 50
	v_xor_b32_e32 v7, v13, v7
	v_lshrrev_b32_e32 v0, 1, v8
	v_and_or_b32 v12, v12, 8, s0
	s_mov_b32 s0, 0xffffe0
	v_and_b32_e32 v14, 24, v13
	v_lshlrev_b32_e32 v7, 4, v7
	v_and_or_b32 v15, v17, s0, v15
	v_lshlrev_b32_e32 v4, 10, v2
	v_lshlrev_b32_e32 v10, 6, v2
	v_or3_b32 v16, v16, v2, v14
	v_and_b32_e32 v0, 0x60, v0
	v_and_b32_e32 v7, 16, v7
	v_or3_b32 v2, v15, v2, v14
	v_and_b32_e32 v13, 0x60, v13
	v_readfirstlane_b32 s0, v9
	v_mul_u32_u24_e32 v16, 0x1800, v16
	v_or3_b32 v0, v0, v7, v12
	v_mul_i32_i24_e32 v2, 0x1800, v2
	v_or3_b32 v7, v13, v7, v12
	v_and_b32_e32 v8, 3, v8
	s_lshl_b32 s0, s0, 10
	v_lshlrev_b32_e32 v231, 4, v1
	v_lshlrev_b32_e32 v1, 3, v8
	v_lshl_or_b32 v232, v11, 4, v6
	v_add_lshl_u32 v233, v0, v16, 1
	v_add_lshl_u32 v234, v7, v2, 1
	s_add_i32 s12, s15, s0
	v_add3_u32 v49, v3, v10, v1
	v_mov_b32_e32 v0, v233
	v_mov_b32_e32 v1, v232
	v_mov_b32_e32 v2, v234
	s_mov_b32 m0, s12
	s_add_i32 s13, s0, 0
	v_readlane_b32 s0, v253, 33
	global_load_lds_dwordx4 v1, s[86:87]
	s_mov_b32 m0, s13
	v_mov_b32_e32 v1, v232
	global_load_lds_dwordx4 v0, s[86:87]
	s_add_i32 m0, s13, 0x2000
	v_mov_b32_e32 v0, v233
	global_load_lds_dwordx4 v2, s[86:87]
	v_mov_b32_e32 v2, v234
	s_add_i32 m0, s13, 0x12000
	v_readlane_b32 s1, v253, 34
	v_lshlrev_b32_e32 v9, 7, v8
	v_add3_u32 v229, s15, v4, v9
	v_lshlrev_b32_e32 v230, 4, v5
	v_add_u32_e32 v50, v229, v230
	s_nop 0
	global_load_lds_dwordx4 v1, s[0:1]
	s_add_i32 m0, s13, 0x4000
	v_mov_b32_e32 v1, v234
	global_load_lds_dwordx4 v0, s[0:1]
	s_add_i32 m0, s13, 0x6000
	v_mov_b32_e32 v0, v232
	global_load_lds_dwordx4 v2, s[0:1]
	v_readlane_b32 s0, v253, 35
	v_mov_b32_e32 v2, v233
	s_add_i32 m0, s13, 0x14000
	v_readlane_b32 s1, v253, 36
	v_add_u32_e32 v51, v229, v231
	v_add_u32_e32 v223, v49, v48
	v_xad_u32 v224, v48, 32, v49
	s_nop 1
	global_load_lds_dwordx4 v0, s[0:1]
	s_add_i32 m0, s13, 0x8000
	s_nop 0
	global_load_lds_dwordx4 v2, s[0:1]
	s_add_i32 m0, s13, 0xa000
	s_nop 0
	global_load_lds_dwordx4 v1, s[0:1]
	s_waitcnt vmcnt(3)
	s_waitcnt lgkmcnt(0)
	s_barrier
; #define VWAIT(n) asm volatile("s_waitcnt vmcnt(" #n ")" ::: "memory")
; #define LBAR() do { asm volatile("s_waitcnt lgkmcnt(0)" ::: "memory"); __builtin_amdgcn_s_barrier(); } while (0)
; #define VWAIT(n) asm volatile("s_waitcnt vmcnt(" #n ")" ::: "memory")
; #define LBAR() do { asm volatile("s_waitcnt lgkmcnt(0)" ::: "memory"); __builtin_amdgcn_s_barrier(); } while (0)
; #define ROWMAXF16(S, pm) do { _Pragma("unroll") for (int g = 0; g < 2; ++g) { float m_ = S[g][0][0]; \
;       _Pragma("unroll") for (int kb = 0; kb < 4; ++kb) _Pragma("unroll") for (int j = 0; j < 4; ++j) m_ = fmaxf(m_, S[g][kb][j]); pm[g] = m_; } } while (0)
; #define EXP16(S) do { _Pragma("unroll") for (int g = 0; g < 2; ++g) _Pragma("unroll") for (int kb = 0; kb < 4; ++kb) _Pragma("unroll") for (int j = 0; j < 4; ++j) S[g][kb][j] = __builtin_amdgcn_exp2f(S[g][kb][j]); } while (0)
; DEV void diff16_pass(const bf16_t* __restrict__ proj, int qcol, int kcol, int vcol, int q0, f32x4 (&o)[2][8], f32x4 (&l_out)[2], unsigned char* lds) {
;     ...
;   float m_reg[2] = {0.f, 0.f};
;   f32x4 ol[2] = {(f32x4){0.f, 0.f, 0.f, 0.f}, (f32x4){0.f, 0.f, 0.f, 0.f}};
;   const bf16x8 ones = {0x3F80, 0x3F80, 0x3F80, 0x3F80, 0x3F80, 0x3F80, 0x3F80, 0x3F80};
;   f32x4 negm[2] = {(f32x4){0.f, 0.f, 0.f, 0.f}, (f32x4){0.f, 0.f, 0.f, 0.f}};
; #pragma unroll
;   for (int g = 0; g < 2; ++g)
; #pragma unroll
;     for (int cb = 0; cb < 8; ++cb) o[g][cb] = (f32x4){0.f, 0.f, 0.f, 0.f};
;   f32x4 SA[2][4], SB2[2][4]; float alA[2], alB[2]; bool rfA = false, rfB = false; bf16x8 pa[2][2];
;   DMA(0); DMA(1); DMA(2); VWAIT(3); LBAR();
;   { QKT16(SA, 0); float pm_[2]; ROWMAXF16(SA, pm_); RESCALE16(SA, pm_, alA, rfA, true); alA[0] = 1.f; alA[1] = 1.f; rfA = false; EXP16(SA); }
	ds_read_b128 v[24:27], v228
	ds_read_b128 v[28:31], v228 offset:1024
	ds_read_b128 v[32:35], v228 offset:2048
	ds_read_b128 v[36:39], v228 offset:3072
	ds_read_b128 v[0:3], v50
	ds_read_b128 v[4:7], v51
	s_waitcnt lgkmcnt(0)
	v_mfma_f32_16x16x32_bf16 v[8:11], v[0:3], v[24:27], 0
	v_mfma_f32_16x16x32_bf16 v[12:15], v[0:3], v[32:35], 0
	v_mfma_f32_16x16x32_bf16 v[0:3], v[4:7], v[28:31], v[8:11]
	v_mfma_f32_16x16x32_bf16 v[4:7], v[4:7], v[36:39], v[12:15]
	s_nop 4
	ds_read_b128 v[8:11], v50 offset:512
	ds_read_b128 v[12:15], v51 offset:512
	s_waitcnt lgkmcnt(0)
	v_mfma_f32_16x16x32_bf16 v[16:19], v[8:11], v[24:27], 0
	v_mfma_f32_16x16x32_bf16 v[20:23], v[8:11], v[32:35], 0
	v_mfma_f32_16x16x32_bf16 v[8:11], v[12:15], v[28:31], v[16:19]
	v_mfma_f32_16x16x32_bf16 v[16:19], v[12:15], v[36:39], v[20:23]
	ds_read_b128 v[12:15], v50 offset:4096
	s_nop 4
	ds_read_b128 v[20:23], v51 offset:4096
	s_waitcnt lgkmcnt(0)
	v_mfma_f32_16x16x32_bf16 v[40:43], v[12:15], v[24:27], 0
	v_mfma_f32_16x16x32_bf16 v[44:47], v[12:15], v[32:35], 0
	v_mfma_f32_16x16x32_bf16 v[12:15], v[20:23], v[28:31], v[40:43]
	v_mfma_f32_16x16x32_bf16 v[20:23], v[20:23], v[36:39], v[44:47]
	s_nop 4
	ds_read_b128 v[40:43], v50 offset:4608
	ds_read_b128 v[44:47], v51 offset:4608
	s_waitcnt lgkmcnt(0)
	v_mfma_f32_16x16x32_bf16 v[24:27], v[40:43], v[24:27], 0
	v_mfma_f32_16x16x32_bf16 v[32:35], v[40:43], v[32:35], 0
	v_mfma_f32_16x16x32_bf16 v[24:27], v[44:47], v[28:31], v[24:27]
	v_mfma_f32_16x16x32_bf16 v[28:31], v[44:47], v[36:39], v[32:35]
	s_nop 5
	v_max_f32_e32 v32, v1, v1
	v_max_f32_e32 v33, v0, v0
	v_max_f32_e32 v32, v33, v32
	v_max_f32_e32 v33, v5, v5
	v_max_f32_e32 v34, v4, v4
	v_max_f32_e32 v33, v34, v33
	v_max3_f32 v32, v32, v2, v3
	v_max3_f32 v33, v33, v6, v7
	v_max3_f32 v32, v32, v8, v9
	v_max3_f32 v33, v33, v16, v17
	v_max3_f32 v32, v32, v10, v11
	v_max3_f32 v33, v33, v18, v19
	v_max3_f32 v32, v32, v12, v13
	v_max3_f32 v33, v33, v20, v21
	v_max3_f32 v32, v32, v14, v15
	v_max3_f32 v33, v33, v22, v23
	v_max3_f32 v32, v32, v24, v25
	v_max3_f32 v33, v33, v28, v29
	v_max3_f32 v32, v32, v26, v27
	v_max3_f32 v34, v33, v30, v31
	ds_bpermute_b32 v33, v217, v32
	ds_bpermute_b32 v35, v217, v34
	s_waitcnt lgkmcnt(0)
	v_max_f32_e32 v33, v33, v33
	v_max_f32_e32 v35, v35, v35
	v_max_f32_e32 v32, v32, v33
	v_max_f32_e32 v34, v34, v35
	ds_bpermute_b32 v33, v216, v32
	ds_bpermute_b32 v35, v216, v34
	s_cbranch_vccnz .LBB0_418
	s_waitcnt lgkmcnt(0)
	v_max_f32_e32 v35, v35, v35
	v_max_f32_e32 v34, v34, v34
	v_max_f32_e32 v35, v34, v35
	v_sub_f32_e32 v5, v5, v35
	v_sub_f32_e32 v4, v4, v35
	v_exp_f32_e32 v137, v4
	v_exp_f32_e32 v148, v5
	v_max_f32_e32 v4, v33, v33
	v_max_f32_e32 v5, v32, v32
	v_sub_f32_e32 v7, v7, v35
	v_sub_f32_e32 v6, v6, v35
	v_max_f32_e32 v34, v5, v4
	v_exp_f32_e32 v149, v6
	v_exp_f32_e32 v151, v7
	v_sub_f32_e32 v4, v27, v34
	v_sub_f32_e32 v5, v26, v34
	v_sub_f32_e32 v6, v25, v34
	v_sub_f32_e32 v7, v24, v34
	v_exp_f32_e32 v152, v7
	v_exp_f32_e32 v154, v6
	v_exp_f32_e32 v155, v5
	v_exp_f32_e32 v157, v4
	v_sub_f32_e32 v4, v15, v34
	v_sub_f32_e32 v5, v14, v34
	v_sub_f32_e32 v6, v13, v34
	v_sub_f32_e32 v7, v12, v34
	v_sub_f32_e32 v31, v31, v35
	v_sub_f32_e32 v30, v30, v35
	v_sub_f32_e32 v29, v29, v35
	v_sub_f32_e32 v28, v28, v35
	v_sub_f32_e32 v23, v23, v35
	v_sub_f32_e32 v22, v22, v35
	v_sub_f32_e32 v21, v21, v35
	v_sub_f32_e32 v20, v20, v35
	v_sub_f32_e32 v19, v19, v35
	v_sub_f32_e32 v18, v18, v35
	v_sub_f32_e32 v17, v17, v35
	v_sub_f32_e32 v16, v16, v35
	v_exp_f32_e32 v153, v7
	v_exp_f32_e32 v156, v6
	v_exp_f32_e32 v158, v5
	v_exp_f32_e32 v159, v4
	v_sub_f32_e32 v4, v11, v34
	v_sub_f32_e32 v5, v10, v34
	v_sub_f32_e32 v6, v9, v34
	v_sub_f32_e32 v7, v8, v34
	v_sub_f32_e32 v3, v3, v34
	v_sub_f32_e32 v2, v2, v34
	v_sub_f32_e32 v1, v1, v34
	v_sub_f32_e32 v0, v0, v34
	v_exp_f32_e32 v128, v28
	v_exp_f32_e32 v130, v29
	v_exp_f32_e32 v131, v30
	v_exp_f32_e32 v133, v31
	v_exp_f32_e32 v129, v20
	v_exp_f32_e32 v134, v21
	v_exp_f32_e32 v135, v22
	v_exp_f32_e32 v138, v23
	v_exp_f32_e32 v132, v16
	v_exp_f32_e32 v136, v17
	v_exp_f32_e32 v139, v18
	v_exp_f32_e32 v150, v19
	v_exp_f32_e32 v240, v7
	v_exp_f32_e32 v242, v6
	v_exp_f32_e32 v243, v5
	v_exp_f32_e32 v246, v4
	v_exp_f32_e32 v241, v0
	v_exp_f32_e32 v244, v1
	v_exp_f32_e32 v245, v2
	v_exp_f32_e32 v247, v3
	v_lshrrev_b32_e32 v36, 3, v226
	v_pk_add_f32 v[208:209], v[34:35], 0 op_sel_hi:[1,0]
	v_mov_b32_e32 v2, v193
	v_mov_b32_e32 v3, v193
	v_or_b32_e32 v235, s75, v36
	v_xor_b32_e32 v76, 0x80000000, v209
	v_pk_add_f32 v[72:73], v[208:209], 0 neg_lo:[1,1] neg_hi:[1,1]
	v_mov_b32_e32 v0, v193
	v_mov_b32_e32 v1, v193
	v_mov_b64_e32 v[10:11], v[2:3]
	v_mov_b64_e32 v[26:27], v[2:3]
	v_mov_b64_e32 v[18:19], v[2:3]
	v_mov_b64_e32 v[38:39], v[2:3]
	v_mov_b64_e32 v[42:43], v[2:3]
	v_mov_b64_e32 v[50:51], v[2:3]
	v_mov_b64_e32 v[66:67], v[2:3]
	v_mov_b64_e32 v[6:7], v[2:3]
	v_mov_b64_e32 v[14:15], v[2:3]
	v_mov_b64_e32 v[30:31], v[2:3]
	v_mov_b64_e32 v[22:23], v[2:3]
	v_mov_b64_e32 v[34:35], v[2:3]
	v_mov_b64_e32 v[46:47], v[2:3]
	v_mov_b64_e32 v[54:55], v[2:3]
	v_mov_b64_e32 v[62:63], v[2:3]
	v_mov_b64_e32 v[70:71], v[2:3]
	v_mov_b64_e32 v[58:59], v[2:3]
	v_or_b32_e32 v236, 2, v235
	v_cmp_gt_u32_e64 s[4:5], 16, v227
	v_lshl_add_u32 v237, v226, 2, v225
	s_mov_b32 s19, 1
	s_mov_b64 s[6:7], 0
	v_mov_b32_e32 v249, 1.0
	s_mov_b32 s15, 0x10000
	s_movk_i32 s16, 0x4000
	v_mov_b64_e32 v[8:9], v[0:1]
	v_mov_b64_e32 v[24:25], v[0:1]
	v_mov_b64_e32 v[16:17], v[0:1]
	v_mov_b64_e32 v[36:37], v[0:1]
	v_mov_b64_e32 v[40:41], v[0:1]
	v_mov_b64_e32 v[48:49], v[0:1]
	v_mov_b64_e32 v[64:65], v[0:1]
	v_mov_b64_e32 v[4:5], v[0:1]
	v_mov_b64_e32 v[12:13], v[0:1]
	v_mov_b64_e32 v[28:29], v[0:1]
	v_mov_b64_e32 v[20:21], v[0:1]
	v_mov_b64_e32 v[32:33], v[0:1]
	v_mov_b64_e32 v[44:45], v[0:1]
	v_mov_b64_e32 v[52:53], v[0:1]
	v_mov_b64_e32 v[60:61], v[0:1]
	v_mov_b32_e32 v248, 1.0
	v_mov_b64_e32 v[68:69], v[0:1]
	v_mov_b64_e32 v[56:57], v[0:1]
	v_mov_b32_e32 v73, v72
	v_mov_b32_e32 v74, v72
	v_mov_b32_e32 v75, v72
	v_mov_b32_e32 v77, v76
	v_mov_b32_e32 v78, v76
	v_mov_b32_e32 v79, v76
	s_branch .LBB0_396

.LBB0_396:
	s_and_b32 s18, s19, 3
	v_lshl_add_u32 v84, s18, 13, v229
	v_add_u32_e32 v86, v84, v230
	v_add_u32_e32 v87, v84, v231
	ds_read_b128 v[176:179], v228
	ds_read_b128 v[160:163], v86
	ds_read_b128 v[180:183], v228 offset:2048
	ds_read_b128 v[164:167], v87
	ds_read_b128 v[184:187], v228 offset:1024
	ds_read_b128 v[188:191], v228 offset:3072
	ds_read_b128 v[168:171], v86 offset:512
	ds_read_b128 v[172:175], v87 offset:512
	ds_read_b128 v[140:143], v86 offset:4096
	ds_read_b128 v[144:147], v87 offset:4096
	s_and_b32 s0, s15, 0xc000
	v_add_u32_e32 v212, s0, v223
	v_add_u32_e32 v213, s0, v224
	v_cvt_pk_bf16_f32 v120, v241, v244
	v_cvt_pk_bf16_f32 v121, v245, v247
	v_cvt_pk_bf16_f32 v122, v240, v242
	v_cvt_pk_bf16_f32 v123, v243, v246
	v_cvt_pk_bf16_f32 v112, v153, v156
	v_cvt_pk_bf16_f32 v113, v158, v159
	v_cvt_pk_bf16_f32 v114, v152, v154
	v_cvt_pk_bf16_f32 v115, v155, v157
	v_cvt_pk_bf16_f32 v124, v137, v148
	v_cvt_pk_bf16_f32 v125, v149, v151
	v_cvt_pk_bf16_f32 v126, v132, v136
	v_cvt_pk_bf16_f32 v127, v139, v150
	v_cvt_pk_bf16_f32 v116, v129, v134
	v_cvt_pk_bf16_f32 v117, v135, v138
	v_cvt_pk_bf16_f32 v118, v128, v130
	v_cvt_pk_bf16_f32 v119, v131, v133
	s_andn2_b64 vcc, exec, s[6:7]
	s_cbranch_vccz .Lh1b_resc
.Lh1b_resc_ret:
	s_add_i32 s17, s19, 2
	s_min_i32 s10, s17, 0xff
	s_mul_i32 s0, s10, 0xc0000
	s_add_u32 s0, s86, s0
	s_addc_u32 s1, s87, 0
	s_and_b32 s10, s10, 3
	s_lshl_b32 s11, s10, 13
	s_lshl_b32 s10, s10, 14
	s_add_i32 s10, s13, s10
	s_mov_b32 s82, s80
	s_mov_b32 s83, s80
	s_mov_b32 s81, s80
	v_mov_b64_e32 v[154:155], s[82:83]
	v_mov_b64_e32 v[152:153], s[80:81]
	ds_read_b128 v[240:243], v86 offset:4608
	ds_read_b128 v[244:247], v87 offset:4608
	v_mfma_f32_16x16x32_bf16 v[68:71], v[120:123], v[152:155], v[68:71]
	v_mfma_f32_16x16x32_bf16 v[56:59], v[124:127], v[152:155], v[56:59]
	v_mfma_f32_16x16x32_bf16 v[68:71], v[112:115], v[152:155], v[68:71]
	v_mfma_f32_16x16x32_bf16 v[56:59], v[116:119], v[152:155], v[56:59]
	s_waitcnt lgkmcnt(6)
	ds_read_b64_tr_b16 v[128:129], v212
	ds_read_b64_tr_b16 v[130:131], v212 offset:4096
	ds_read_b64_tr_b16 v[132:133], v212 offset:8192
	ds_read_b64_tr_b16 v[134:135], v212 offset:12288
	v_mfma_f32_16x16x32_bf16 v[84:87], v[160:163], v[176:179], v[72:75]
	v_mfma_f32_16x16x32_bf16 v[80:83], v[160:163], v[180:183], v[76:79]
	v_mfma_f32_16x16x32_bf16 v[84:87], v[164:167], v[184:187], v[84:87]
	v_mfma_f32_16x16x32_bf16 v[80:83], v[164:167], v[188:191], v[80:83]
	s_add_i32 m0, s12, s11
	s_nop 0
	global_load_lds_dwordx4 v232, s[0:1]
	s_waitcnt lgkmcnt(8)
	ds_read_b64_tr_b16 v[136:137], v213
	ds_read_b64_tr_b16 v[138:139], v213 offset:4096
	ds_read_b64_tr_b16 v[148:149], v213 offset:8192
	ds_read_b64_tr_b16 v[150:151], v213 offset:12288
	v_mfma_f32_16x16x32_bf16 v[96:99], v[168:171], v[176:179], v[72:75]
	v_mfma_f32_16x16x32_bf16 v[88:91], v[168:171], v[180:183], v[76:79]
	v_mfma_f32_16x16x32_bf16 v[96:99], v[172:175], v[184:187], v[96:99]
	v_mfma_f32_16x16x32_bf16 v[88:91], v[172:175], v[188:191], v[88:91]
	s_mov_b32 m0, s10
	s_nop 0
	global_load_lds_dwordx4 v233, s[0:1]
	s_waitcnt lgkmcnt(10)
	ds_read_b64_tr_b16 v[152:153], v212 offset:1024
	ds_read_b64_tr_b16 v[154:155], v212 offset:5120
	ds_read_b64_tr_b16 v[156:157], v212 offset:9216
	ds_read_b64_tr_b16 v[158:159], v212 offset:13312
	v_mfma_f32_16x16x32_bf16 v[100:103], v[140:143], v[176:179], v[72:75]
	v_mfma_f32_16x16x32_bf16 v[92:95], v[140:143], v[180:183], v[76:79]
	v_mfma_f32_16x16x32_bf16 v[100:103], v[144:147], v[184:187], v[100:103]
	v_mfma_f32_16x16x32_bf16 v[92:95], v[144:147], v[188:191], v[92:95]
	s_add_i32 m0, s10, 0x2000
	s_nop 0
	global_load_lds_dwordx4 v234, s[0:1]
	s_waitcnt lgkmcnt(12)
	v_mfma_f32_16x16x32_bf16 v[108:111], v[240:243], v[176:179], v[72:75]
	v_mfma_f32_16x16x32_bf16 v[104:107], v[240:243], v[180:183], v[76:79]
	v_mfma_f32_16x16x32_bf16 v[108:111], v[244:247], v[184:187], v[108:111]
	v_mfma_f32_16x16x32_bf16 v[104:107], v[244:247], v[188:191], v[104:107]
	s_cmp_le_i32 s19, s75
	s_cbranch_scc0 .LBB0_406

.LBB0_400:
	s_waitcnt lgkmcnt(8)
	ds_read_b64_tr_b16 v[240:241], v212 offset:2048
	ds_read_b64_tr_b16 v[242:243], v212 offset:6144
	ds_read_b64_tr_b16 v[244:245], v212 offset:10240
	ds_read_b64_tr_b16 v[246:247], v212 offset:14336
	v_mfma_f32_16x16x32_bf16 v[52:55], v[120:123], v[136:139], v[52:55]
	v_exp_f32_e32 v162, v84
	v_mfma_f32_16x16x32_bf16 v[48:51], v[124:127], v[136:139], v[48:51]
	v_exp_f32_e32 v163, v85
	v_mfma_f32_16x16x32_bf16 v[52:55], v[112:115], v[148:151], v[52:55]
	v_exp_f32_e32 v161, v86
	v_mfma_f32_16x16x32_bf16 v[48:51], v[116:119], v[148:151], v[48:51]
	v_exp_f32_e32 v160, v87
	v_exp_f32_e32 v167, v96
	s_waitcnt lgkmcnt(8)
	ds_read_b64_tr_b16 v[128:129], v213 offset:2048
	ds_read_b64_tr_b16 v[130:131], v213 offset:6144
	ds_read_b64_tr_b16 v[132:133], v213 offset:10240
	ds_read_b64_tr_b16 v[134:135], v213 offset:14336
	v_mfma_f32_16x16x32_bf16 v[44:47], v[120:123], v[152:155], v[44:47]
	v_exp_f32_e32 v166, v97
	v_mfma_f32_16x16x32_bf16 v[40:43], v[124:127], v[152:155], v[40:43]
	v_exp_f32_e32 v164, v98
	v_mfma_f32_16x16x32_bf16 v[44:47], v[112:115], v[156:159], v[44:47]
	v_exp_f32_e32 v165, v99
	v_mfma_f32_16x16x32_bf16 v[40:43], v[116:119], v[156:159], v[40:43]
	v_exp_f32_e32 v171, v100
	v_exp_f32_e32 v170, v101
	s_waitcnt lgkmcnt(8)
	ds_read_b64_tr_b16 v[136:137], v212 offset:3072
	ds_read_b64_tr_b16 v[138:139], v212 offset:7168
	ds_read_b64_tr_b16 v[148:149], v212 offset:11264
	ds_read_b64_tr_b16 v[150:151], v212 offset:15360
	v_mfma_f32_16x16x32_bf16 v[32:35], v[120:123], v[140:143], v[32:35]
	v_exp_f32_e32 v169, v102
	v_mfma_f32_16x16x32_bf16 v[36:39], v[124:127], v[140:143], v[36:39]
	v_exp_f32_e32 v168, v103
	v_mfma_f32_16x16x32_bf16 v[32:35], v[112:115], v[144:147], v[32:35]
	v_exp_f32_e32 v178, v108
	v_mfma_f32_16x16x32_bf16 v[36:39], v[116:119], v[144:147], v[36:39]
	v_exp_f32_e32 v179, v109
	v_exp_f32_e32 v177, v110
	s_waitcnt lgkmcnt(8)
	ds_read_b64_tr_b16 v[152:153], v213 offset:3072
	ds_read_b64_tr_b16 v[154:155], v213 offset:7168
	ds_read_b64_tr_b16 v[156:157], v213 offset:11264
	ds_read_b64_tr_b16 v[158:159], v213 offset:15360
	v_mfma_f32_16x16x32_bf16 v[20:23], v[120:123], v[240:243], v[20:23]
	v_exp_f32_e32 v176, v111
	v_mfma_f32_16x16x32_bf16 v[16:19], v[124:127], v[240:243], v[16:19]
	v_exp_f32_e32 v175, v80
	v_mfma_f32_16x16x32_bf16 v[20:23], v[112:115], v[244:247], v[20:23]
	v_exp_f32_e32 v174, v81
	v_mfma_f32_16x16x32_bf16 v[16:19], v[116:119], v[244:247], v[16:19]
	v_exp_f32_e32 v172, v82
	v_exp_f32_e32 v173, v83
	s_waitcnt lgkmcnt(8)
	v_mfma_f32_16x16x32_bf16 v[28:31], v[120:123], v[128:131], v[28:31]
	v_exp_f32_e32 v183, v88
	v_mfma_f32_16x16x32_bf16 v[24:27], v[124:127], v[128:131], v[24:27]
	v_exp_f32_e32 v182, v89
	v_mfma_f32_16x16x32_bf16 v[28:31], v[112:115], v[132:135], v[28:31]
	v_exp_f32_e32 v181, v90
	v_mfma_f32_16x16x32_bf16 v[24:27], v[116:119], v[132:135], v[24:27]
	v_exp_f32_e32 v180, v91
	s_waitcnt lgkmcnt(4)
	v_mfma_f32_16x16x32_bf16 v[12:15], v[120:123], v[136:139], v[12:15]
	v_exp_f32_e32 v186, v92
	v_mfma_f32_16x16x32_bf16 v[8:11], v[124:127], v[136:139], v[8:11]
	v_exp_f32_e32 v187, v93
	v_mfma_f32_16x16x32_bf16 v[12:15], v[112:115], v[148:151], v[12:15]
	v_exp_f32_e32 v185, v94
	v_mfma_f32_16x16x32_bf16 v[8:11], v[116:119], v[148:151], v[8:11]
	v_exp_f32_e32 v184, v95
	s_waitcnt lgkmcnt(0)
	v_mfma_f32_16x16x32_bf16 v[4:7], v[120:123], v[152:155], v[4:7]
	v_exp_f32_e32 v191, v104
	v_mfma_f32_16x16x32_bf16 v[0:3], v[124:127], v[152:155], v[0:3]
	v_exp_f32_e32 v190, v105
	v_mfma_f32_16x16x32_bf16 v[4:7], v[112:115], v[156:159], v[4:7]
	v_exp_f32_e32 v189, v106
	v_mfma_f32_16x16x32_bf16 v[0:3], v[116:119], v[156:159], v[0:3]
	v_exp_f32_e32 v188, v107
	s_waitcnt vmcnt(3)
	s_waitcnt lgkmcnt(0)
	s_add_i32 s0, s19, 1
	s_cmp_ge_i32 s0, s14
	s_mov_b64 s[0:1], -1
	s_barrier
	s_cbranch_scc1 .LBB0_395
	s_and_b32 s0, s16, 0x6000
	v_add_u32_e32 v84, s0, v229
	v_add_u32_e32 v86, v84, v230
	v_add_u32_e32 v87, v84, v231
	ds_read_b128 v[240:243], v228
	ds_read_b128 v[128:131], v86
	ds_read_b128 v[244:247], v228 offset:2048
	ds_read_b128 v[132:135], v87
	ds_read_b128 v[152:155], v228 offset:1024
	ds_read_b128 v[156:159], v228 offset:3072
	ds_read_b128 v[136:139], v86 offset:512
	ds_read_b128 v[148:151], v87 offset:512
	ds_read_b128 v[140:143], v86 offset:4096
	ds_read_b128 v[144:147], v87 offset:4096
	s_lshl_b32 s0, s18, 14
	v_add_u32_e32 v214, s0, v223
	v_add_u32_e32 v215, s0, v224
	v_cvt_pk_bf16_f32 v120, v162, v163
	v_cvt_pk_bf16_f32 v121, v161, v160
	v_cvt_pk_bf16_f32 v122, v167, v166
	v_cvt_pk_bf16_f32 v123, v164, v165
	v_cvt_pk_bf16_f32 v112, v171, v170
	v_cvt_pk_bf16_f32 v113, v169, v168
	v_cvt_pk_bf16_f32 v114, v178, v179
	v_cvt_pk_bf16_f32 v115, v177, v176
	v_cvt_pk_bf16_f32 v124, v175, v174
	v_cvt_pk_bf16_f32 v125, v172, v173
	v_cvt_pk_bf16_f32 v126, v183, v182
	v_cvt_pk_bf16_f32 v127, v181, v180
	v_cvt_pk_bf16_f32 v116, v186, v187
	v_cvt_pk_bf16_f32 v117, v185, v184
	v_cvt_pk_bf16_f32 v118, v191, v190
	v_cvt_pk_bf16_f32 v119, v189, v188
	s_andn2_b64 vcc, exec, s[10:11]
	s_cbranch_vccz .Lh2b_resc
.Lh2b_resc_ret:
	s_min_i32 s0, s19, 0xfc
	s_add_i32 s6, s0, 3
	s_mul_i32 s0, s6, 0xc0000
	s_add_u32 s0, s86, s0
	s_addc_u32 s1, s87, 0
	s_and_b32 s6, s6, 3
	s_lshl_b32 s7, s6, 13
	s_lshl_b32 s6, s6, 14
	s_add_i32 s6, s13, s6
	s_mov_b32 s82, s80
	s_mov_b32 s83, s80
	s_mov_b32 s81, s80
	v_mov_b64_e32 v[186:187], s[82:83]
	v_mov_b64_e32 v[184:185], s[80:81]
	ds_read_b128 v[160:163], v86 offset:4608
	ds_read_b128 v[164:167], v87 offset:4608
	v_mfma_f32_16x16x32_bf16 v[68:71], v[120:123], v[184:187], v[68:71]
	v_mfma_f32_16x16x32_bf16 v[56:59], v[124:127], v[184:187], v[56:59]
	v_mfma_f32_16x16x32_bf16 v[68:71], v[112:115], v[184:187], v[68:71]
	v_mfma_f32_16x16x32_bf16 v[56:59], v[116:119], v[184:187], v[56:59]
	s_waitcnt lgkmcnt(6)
	ds_read_b64_tr_b16 v[168:169], v214
	ds_read_b64_tr_b16 v[170:171], v214 offset:4096
	ds_read_b64_tr_b16 v[172:173], v214 offset:8192
	ds_read_b64_tr_b16 v[174:175], v214 offset:12288
	v_mfma_f32_16x16x32_bf16 v[84:87], v[128:131], v[240:243], v[72:75]
	v_mfma_f32_16x16x32_bf16 v[80:83], v[128:131], v[244:247], v[76:79]
	v_mfma_f32_16x16x32_bf16 v[84:87], v[132:135], v[152:155], v[84:87]
	v_mfma_f32_16x16x32_bf16 v[80:83], v[132:135], v[156:159], v[80:83]
	s_add_i32 m0, s12, s7
	s_nop 0
	global_load_lds_dwordx4 v232, s[0:1]
	s_waitcnt lgkmcnt(8)
	ds_read_b64_tr_b16 v[176:177], v215
	ds_read_b64_tr_b16 v[178:179], v215 offset:4096
	ds_read_b64_tr_b16 v[180:181], v215 offset:8192
	ds_read_b64_tr_b16 v[182:183], v215 offset:12288
	v_mfma_f32_16x16x32_bf16 v[96:99], v[136:139], v[240:243], v[72:75]
	v_mfma_f32_16x16x32_bf16 v[88:91], v[136:139], v[244:247], v[76:79]
	v_mfma_f32_16x16x32_bf16 v[96:99], v[148:151], v[152:155], v[96:99]
	v_mfma_f32_16x16x32_bf16 v[88:91], v[148:151], v[156:159], v[88:91]
	s_mov_b32 m0, s6
	s_nop 0
	global_load_lds_dwordx4 v233, s[0:1]
	s_waitcnt lgkmcnt(10)
	ds_read_b64_tr_b16 v[184:185], v214 offset:1024
	ds_read_b64_tr_b16 v[186:187], v214 offset:5120
	ds_read_b64_tr_b16 v[188:189], v214 offset:9216
	ds_read_b64_tr_b16 v[190:191], v214 offset:13312
	v_mfma_f32_16x16x32_bf16 v[100:103], v[140:143], v[240:243], v[72:75]
	v_mfma_f32_16x16x32_bf16 v[92:95], v[140:143], v[244:247], v[76:79]
	v_mfma_f32_16x16x32_bf16 v[100:103], v[144:147], v[152:155], v[100:103]
	v_mfma_f32_16x16x32_bf16 v[92:95], v[144:147], v[156:159], v[92:95]
	s_add_i32 m0, s6, 0x2000
	s_nop 0
	global_load_lds_dwordx4 v234, s[0:1]
	s_waitcnt lgkmcnt(12)
	v_mfma_f32_16x16x32_bf16 v[108:111], v[160:163], v[240:243], v[72:75]
	v_mfma_f32_16x16x32_bf16 v[104:107], v[160:163], v[244:247], v[76:79]
	v_mfma_f32_16x16x32_bf16 v[108:111], v[164:167], v[152:155], v[108:111]
	v_mfma_f32_16x16x32_bf16 v[104:107], v[164:167], v[156:159], v[104:107]
	s_cmp_lt_i32 s19, s75
	s_cbranch_scc0 .LBB0_411

; #define VWAIT(n) asm volatile("s_waitcnt vmcnt(" #n ")" ::: "memory")
; #define LBAR() do { asm volatile("s_waitcnt lgkmcnt(0)" ::: "memory"); __builtin_amdgcn_s_barrier(); } while (0)
; #define VWAIT(n) asm volatile("s_waitcnt vmcnt(" #n ")" ::: "memory")
; #define LBAR() do { asm volatile("s_waitcnt lgkmcnt(0)" ::: "memory"); __builtin_amdgcn_s_barrier(); } while (0)
; #define SUMPACK16(S, al) do { _Pragma("unroll") for (int g = 0; g < 2; ++g) { pa[g][0] = PKS(S, g, 0); pa[g][1] = PKS(S, g, 1); } } while (0)
; #define PVL() do { ol[0] = MF16(pa[0][0], ones, ol[0]); ol[1] = MF16(pa[1][0], ones, ol[1]); ol[0] = MF16(pa[0][1], ones, ol[0]); ol[1] = MF16(pa[1][1], ones, ol[1]); } while (0)
; DEV void diff16_pass(const bf16_t* __restrict__ proj, int qcol, int kcol, int vcol, int q0, f32x4 (&o)[2][8], f32x4 (&l_out)[2], unsigned char* lds) {
;     ...
;   { SUMPACK16(SB2, alB); DRESC16(alB, rfB); PVL(); const lds_cptr vE_ = vrdE + ((NT - 1) & 3) * D_VSLOT, vO_ = vrdO + ((NT - 1) & 3) * D_VSLOT;
;     PV16(0, vE_, vO_); PV16(1, vE_, vO_); PV16(2, vE_, vO_); PV16(3, vE_, vO_); PV16(4, vE_, vO_); PV16(5, vE_, vO_); PV16(6, vE_, vO_); PV16(7, vE_, vO_); }
;   VWAIT(0); LBAR();
.LBB0_420:
	v_cvt_pk_bf16_f32 v72, v162, v163
	v_cvt_pk_bf16_f32 v73, v161, v160
	v_cvt_pk_bf16_f32 v74, v167, v166
	v_cvt_pk_bf16_f32 v75, v164, v165
	v_cvt_pk_bf16_f32 v80, v175, v174
	v_cvt_pk_bf16_f32 v81, v172, v173
	v_cvt_pk_bf16_f32 v82, v183, v182
	v_cvt_pk_bf16_f32 v83, v181, v180
	s_mov_b32 s82, s80
	s_mov_b32 s83, s80
	s_mov_b32 s81, s80
	v_mov_b64_e32 v[94:95], s[82:83]
	v_cvt_pk_bf16_f32 v76, v171, v170
	v_cvt_pk_bf16_f32 v77, v169, v168
	v_cvt_pk_bf16_f32 v78, v178, v179
	v_cvt_pk_bf16_f32 v79, v177, v176
	v_cvt_pk_bf16_f32 v84, v186, v187
	v_cvt_pk_bf16_f32 v85, v185, v184
	v_cvt_pk_bf16_f32 v86, v191, v190
	v_cvt_pk_bf16_f32 v87, v189, v188
	v_mov_b64_e32 v[92:93], s[80:81]
	s_movk_i32 s0, 0x2200
	s_brev_b32 s4, 60
	v_mfma_f32_16x16x32_bf16 v[68:71], v[72:75], v[92:95], v[68:71]
	v_mfma_f32_16x16x32_bf16 v[56:59], v[80:83], v[92:95], v[56:59]
	v_mfma_f32_16x16x32_bf16 v[88:91], v[76:79], v[92:95], v[68:71]
	v_mfma_f32_16x16x32_bf16 v[68:71], v[84:87], v[92:95], v[56:59]
	s_nop 5
	ds_read_b64_tr_b16 v[56:57], v223 offset:49152
	ds_read_b64_tr_b16 v[58:59], v223 offset:53248
	ds_read_b64_tr_b16 v[92:93], v223 offset:57344
	ds_read_b64_tr_b16 v[94:95], v223 offset:61440
	s_waitcnt lgkmcnt(0)
	v_mfma_f32_16x16x32_bf16 v[60:63], v[72:75], v[56:59], v[60:63]
	v_mfma_f32_16x16x32_bf16 v[56:59], v[80:83], v[56:59], v[64:67]
	v_mfma_f32_16x16x32_bf16 v[60:63], v[76:79], v[92:95], v[60:63]
	v_mfma_f32_16x16x32_bf16 v[56:59], v[84:87], v[92:95], v[56:59]
	s_nop 0
	ds_read_b64_tr_b16 v[64:65], v224 offset:49152
	ds_read_b64_tr_b16 v[66:67], v224 offset:53248
	ds_read_b64_tr_b16 v[92:93], v224 offset:57344
	ds_read_b64_tr_b16 v[94:95], v224 offset:61440
	s_waitcnt lgkmcnt(0)
	v_mfma_f32_16x16x32_bf16 v[52:55], v[72:75], v[64:67], v[52:55]
	v_mfma_f32_16x16x32_bf16 v[48:51], v[80:83], v[64:67], v[48:51]
	v_mfma_f32_16x16x32_bf16 v[52:55], v[76:79], v[92:95], v[52:55]
	v_mfma_f32_16x16x32_bf16 v[48:51], v[84:87], v[92:95], v[48:51]
	ds_read_b64_tr_b16 v[64:65], v223 offset:50176
	ds_read_b64_tr_b16 v[66:67], v223 offset:54272
	ds_read_b64_tr_b16 v[92:93], v223 offset:58368
	ds_read_b64_tr_b16 v[94:95], v223 offset:62464
	s_waitcnt lgkmcnt(0)
	v_mfma_f32_16x16x32_bf16 v[44:47], v[72:75], v[64:67], v[44:47]
	v_mfma_f32_16x16x32_bf16 v[40:43], v[80:83], v[64:67], v[40:43]
	v_mfma_f32_16x16x32_bf16 v[44:47], v[76:79], v[92:95], v[44:47]
	v_mfma_f32_16x16x32_bf16 v[40:43], v[84:87], v[92:95], v[40:43]
	ds_read_b64_tr_b16 v[64:65], v224 offset:50176
	ds_read_b64_tr_b16 v[66:67], v224 offset:54272
	ds_read_b64_tr_b16 v[92:93], v224 offset:58368
	ds_read_b64_tr_b16 v[94:95], v224 offset:62464
	s_waitcnt lgkmcnt(0)
	v_mfma_f32_16x16x32_bf16 v[32:35], v[72:75], v[64:67], v[32:35]
	v_mfma_f32_16x16x32_bf16 v[64:67], v[80:83], v[64:67], v[36:39]
	v_mfma_f32_16x16x32_bf16 v[36:39], v[76:79], v[92:95], v[32:35]
	v_mfma_f32_16x16x32_bf16 v[32:35], v[84:87], v[92:95], v[64:67]
	s_nop 5
	ds_read_b64_tr_b16 v[64:65], v223 offset:51200
	ds_read_b64_tr_b16 v[66:67], v223 offset:55296
	ds_read_b64_tr_b16 v[92:93], v223 offset:59392
	ds_read_b64_tr_b16 v[94:95], v223 offset:63488
	s_waitcnt lgkmcnt(0)
	v_mfma_f32_16x16x32_bf16 v[20:23], v[72:75], v[64:67], v[20:23]
	v_mfma_f32_16x16x32_bf16 v[16:19], v[80:83], v[64:67], v[16:19]
	v_mfma_f32_16x16x32_bf16 v[64:67], v[76:79], v[92:95], v[20:23]
	v_mfma_f32_16x16x32_bf16 v[16:19], v[84:87], v[92:95], v[16:19]
	s_nop 4
	ds_read_b64_tr_b16 v[20:21], v224 offset:51200
	ds_read_b64_tr_b16 v[22:23], v224 offset:55296
	ds_read_b64_tr_b16 v[92:93], v224 offset:59392
	ds_read_b64_tr_b16 v[94:95], v224 offset:63488
	s_waitcnt lgkmcnt(0)
	v_mfma_f32_16x16x32_bf16 v[28:31], v[72:75], v[20:23], v[28:31]
	v_mfma_f32_16x16x32_bf16 v[20:23], v[80:83], v[20:23], v[24:27]
	v_mfma_f32_16x16x32_bf16 v[24:27], v[76:79], v[92:95], v[28:31]
	v_mfma_f32_16x16x32_bf16 v[20:23], v[84:87], v[92:95], v[20:23]
	s_nop 4
	ds_read_b64_tr_b16 v[28:29], v223 offset:52224
	ds_read_b64_tr_b16 v[30:31], v223 offset:56320
	ds_read_b64_tr_b16 v[92:93], v223 offset:60416
	ds_read_b64_tr_b16 v[94:95], v223 offset:64512
	s_waitcnt lgkmcnt(0)
	v_mfma_f32_16x16x32_bf16 v[12:15], v[72:75], v[28:31], v[12:15]
	v_mfma_f32_16x16x32_bf16 v[8:11], v[80:83], v[28:31], v[8:11]
	v_mfma_f32_16x16x32_bf16 v[12:15], v[76:79], v[92:95], v[12:15]
	v_mfma_f32_16x16x32_bf16 v[8:11], v[84:87], v[92:95], v[8:11]
	ds_read_b64_tr_b16 v[28:29], v224 offset:52224
	ds_read_b64_tr_b16 v[30:31], v224 offset:56320
	ds_read_b64_tr_b16 v[92:93], v224 offset:60416
	ds_read_b64_tr_b16 v[94:95], v224 offset:64512
	s_waitcnt vmcnt(0)
	s_waitcnt lgkmcnt(0)
	s_waitcnt lgkmcnt(0)
	v_mfma_f32_16x16x32_bf16 v[4:7], v[72:75], v[28:31], v[4:7]
	s_barrier
; DEV void attn_store16(f32x4 (&o)[2][8], const float* __restrict__ gain, float oscale, bf16_t* __restrict__ mix, int q0, int colbase) {
;     ...
;   float gn[8];
; #pragma unroll
;   for (int cb = 0; cb < 8; ++cb) gn[cb] = gain[16 * cb + fr] * oscale;
; DEV void attn_phase(const Params& p, int layer) {
;     ...
;         for (int g = 0; g < 2; ++g) { const f32x4 l4 = ld[g];
;           const f32x4 il = {__builtin_amdgcn_rcpf(l4[0]) * lam, __builtin_amdgcn_rcpf(l4[1]) * lam, __builtin_amdgcn_rcpf(l4[2]) * lam, __builtin_amdgcn_rcpf(l4[3]) * lam};
; #pragma unroll
;           for (int cb = 0; cb < 8; cb += 2) { const u32x4 w = *reinterpret_cast<const u32x4*>((const bf16_t*)o1s + (wid * 8 + g * 4 + (cb >> 1)) * 512 + lane * 8);
;             const f32x4 a4 = {__uint_as_float(w[0] << 16), __uint_as_float(w[0] & 0xffff0000u), __uint_as_float(w[1] << 16), __uint_as_float(w[1] & 0xffff0000u)};
;             const f32x4 b4 = {__uint_as_float(w[2] << 16), __uint_as_float(w[2] & 0xffff0000u), __uint_as_float(w[3] << 16), __uint_as_float(w[3] & 0xffff0000u)};
;             od[g][cb] = a4 - od[g][cb] * il; od[g][cb + 1] = b4 - od[g][cb + 1] * il; } }
	v_mfma_f32_16x16x32_bf16 v[0:3], v[80:83], v[28:31], v[0:3]
	v_rcp_f32_e32 v28, v88
	v_rcp_f32_e32 v29, v89
	v_rcp_f32_e32 v30, v90
	v_rcp_f32_e32 v31, v91
	v_mfma_f32_16x16x32_bf16 v[4:7], v[76:79], v[92:95], v[4:7]
	v_mul_f32_e64 v78, v194, v28
	v_mul_f32_e64 v79, v195, v29
	v_pk_mul_f32 v[82:83], v[206:207], v[30:31]
	global_load_dwordx4 v[104:107], v[196:197], off
	global_load_dwordx4 v[108:111], v[196:197], off offset:1024
	global_load_dwordx4 v[112:115], v[196:197], off offset:2048
	global_load_dwordx4 v[116:119], v[196:197], off offset:3072
	global_load_dwordx4 v[120:123], v[198:199], off
	global_load_dwordx4 v[124:127], v[200:201], off
	global_load_dwordx4 v[128:131], v[202:203], off
	global_load_dwordx4 v[132:135], v[204:205], off
	v_mfma_f32_16x16x32_bf16 v[0:3], v[84:87], v[92:95], v[0:3]
	s_waitcnt vmcnt(0)
	v_lshlrev_b32_e32 v72, 16, v104
	v_and_b32_e32 v73, 0xffff0000, v104
	v_lshlrev_b32_e32 v28, 16, v105
	v_and_b32_e32 v29, 0xffff0000, v105
	v_lshlrev_b32_e32 v74, 16, v106
	v_and_b32_e32 v75, 0xffff0000, v106
	v_lshlrev_b32_e32 v76, 16, v107
	v_and_b32_e32 v77, 0xffff0000, v107
	v_pk_fma_f32 v[30:31], v[82:83], v[62:63], v[28:29] neg_lo:[1,0,0] neg_hi:[1,0,0]
	v_pk_fma_f32 v[28:29], v[82:83], v[54:55], v[76:77] neg_lo:[1,0,0] neg_hi:[1,0,0]
	v_pk_fma_f32 v[62:63], v[78:79], v[52:53], v[74:75] neg_lo:[1,0,0] neg_hi:[1,0,0]
	v_pk_fma_f32 v[72:73], v[78:79], v[60:61], v[72:73] neg_lo:[1,0,0] neg_hi:[1,0,0]
	v_pk_mul_f32 v[88:89], v[62:63], v[62:63]
	v_lshlrev_b32_e32 v60, 16, v108
	v_and_b32_e32 v61, 0xffff0000, v108
	v_lshlrev_b32_e32 v52, 16, v109
	v_and_b32_e32 v53, 0xffff0000, v109
	v_lshlrev_b32_e32 v74, 16, v110
	v_and_b32_e32 v75, 0xffff0000, v110
	v_lshlrev_b32_e32 v54, 16, v111
	v_and_b32_e32 v55, 0xffff0000, v111
	v_pk_fma_f32 v[46:47], v[82:83], v[46:47], v[52:53] neg_lo:[1,0,0] neg_hi:[1,0,0]
	v_pk_fma_f32 v[38:39], v[82:83], v[38:39], v[54:55] neg_lo:[1,0,0] neg_hi:[1,0,0]
	v_pk_fma_f32 v[76:77], v[78:79], v[44:45], v[60:61] neg_lo:[1,0,0] neg_hi:[1,0,0]
	v_pk_fma_f32 v[74:75], v[78:79], v[36:37], v[74:75] neg_lo:[1,0,0] neg_hi:[1,0,0]
	v_pk_fma_f32 v[88:89], v[72:73], v[72:73], v[88:89]
	v_lshlrev_b32_e32 v36, 16, v112
	v_and_b32_e32 v37, 0xffff0000, v112
	v_lshlrev_b32_e32 v44, 16, v113
	v_and_b32_e32 v45, 0xffff0000, v113
	v_lshlrev_b32_e32 v60, 16, v114
	v_and_b32_e32 v61, 0xffff0000, v114
	v_lshlrev_b32_e32 v54, 16, v115
	v_and_b32_e32 v55, 0xffff0000, v115
	v_pk_fma_f32 v[52:53], v[82:83], v[66:67], v[44:45] neg_lo:[1,0,0] neg_hi:[1,0,0]
	v_pk_fma_f32 v[66:67], v[78:79], v[64:65], v[36:37] neg_lo:[1,0,0] neg_hi:[1,0,0]
	v_pk_fma_f32 v[44:45], v[82:83], v[26:27], v[54:55] neg_lo:[1,0,0] neg_hi:[1,0,0]
	v_pk_fma_f32 v[64:65], v[78:79], v[24:25], v[60:61] neg_lo:[1,0,0] neg_hi:[1,0,0]
	v_mov_b32_e32 v90, v65
	v_mov_b32_e32 v91, v67
	v_pk_mul_f32 v[90:91], v[90:91], v[90:91]
	v_lshlrev_b32_e32 v36, 16, v116
	v_and_b32_e32 v37, 0xffff0000, v116
	v_lshlrev_b32_e32 v84, 16, v118
	v_and_b32_e32 v85, 0xffff0000, v118
	v_lshlrev_b32_e32 v26, 16, v119
	v_and_b32_e32 v27, 0xffff0000, v119
	v_pk_fma_f32 v[80:81], v[78:79], v[12:13], v[36:37] neg_lo:[1,0,0] neg_hi:[1,0,0]
	v_pk_fma_f32 v[54:55], v[82:83], v[6:7], v[26:27] neg_lo:[1,0,0] neg_hi:[1,0,0]
	v_pk_fma_f32 v[78:79], v[78:79], v[4:5], v[84:85] neg_lo:[1,0,0] neg_hi:[1,0,0]
	v_rcp_f32_e32 v4, v68
	v_rcp_f32_e32 v5, v69
	v_rcp_f32_e32 v6, v70
	v_rcp_f32_e32 v7, v71
	v_lshlrev_b32_e32 v24, 16, v117
	v_pk_mul_f32 v[68:69], v[194:195], v[4:5]
	v_and_b32_e32 v25, 0xffff0000, v117
	v_pk_mul_f32 v[70:71], v[206:207], v[6:7]
	v_pk_fma_f32 v[60:61], v[82:83], v[14:15], v[24:25] neg_lo:[1,0,0] neg_hi:[1,0,0]
	v_mov_b32_e32 v92, v79
	v_mov_b32_e32 v93, v81
	v_pk_mul_f32 v[92:93], v[92:93], v[92:93]
	v_lshlrev_b32_e32 v12, 16, v120
	v_and_b32_e32 v13, 0xffff0000, v120
	v_lshlrev_b32_e32 v4, 16, v121
	v_and_b32_e32 v5, 0xffff0000, v121
	v_lshlrev_b32_e32 v14, 16, v122
	v_and_b32_e32 v15, 0xffff0000, v122
	v_lshlrev_b32_e32 v24, 16, v123
	v_and_b32_e32 v25, 0xffff0000, v123
	v_pk_fma_f32 v[6:7], v[70:71], v[58:59], v[4:5] neg_lo:[1,0,0] neg_hi:[1,0,0]
	v_pk_fma_f32 v[26:27], v[68:69], v[56:57], v[12:13] neg_lo:[1,0,0] neg_hi:[1,0,0]
	v_pk_fma_f32 v[4:5], v[70:71], v[50:51], v[24:25] neg_lo:[1,0,0] neg_hi:[1,0,0]
	v_pk_fma_f32 v[24:25], v[68:69], v[48:49], v[14:15] neg_lo:[1,0,0] neg_hi:[1,0,0]
	v_lshlrev_b32_e32 v36, 16, v124
	v_and_b32_e32 v37, 0xffff0000, v124
	v_lshlrev_b32_e32 v12, 16, v125
	v_and_b32_e32 v13, 0xffff0000, v125
	v_lshlrev_b32_e32 v48, 16, v126
	v_and_b32_e32 v49, 0xffff0000, v126
	v_lshlrev_b32_e32 v50, 16, v127
	v_and_b32_e32 v51, 0xffff0000, v127
	v_pk_fma_f32 v[14:15], v[70:71], v[42:43], v[12:13] neg_lo:[1,0,0] neg_hi:[1,0,0]
	v_pk_fma_f32 v[36:37], v[68:69], v[40:41], v[36:37] neg_lo:[1,0,0] neg_hi:[1,0,0]
	v_pk_fma_f32 v[12:13], v[70:71], v[34:35], v[50:51] neg_lo:[1,0,0] neg_hi:[1,0,0]
	v_pk_fma_f32 v[32:33], v[68:69], v[32:33], v[48:49] neg_lo:[1,0,0] neg_hi:[1,0,0]
	v_lshlrev_b32_e32 v34, 16, v128
	v_and_b32_e32 v35, 0xffff0000, v128
	v_lshlrev_b32_e32 v40, 16, v129
	v_and_b32_e32 v41, 0xffff0000, v129
	v_lshlrev_b32_e32 v48, 16, v130
	v_and_b32_e32 v49, 0xffff0000, v130
	v_lshlrev_b32_e32 v42, 16, v131
	v_and_b32_e32 v43, 0xffff0000, v131
	v_pk_fma_f32 v[18:19], v[70:71], v[18:19], v[40:41] neg_lo:[1,0,0] neg_hi:[1,0,0]
	v_pk_fma_f32 v[34:35], v[68:69], v[16:17], v[34:35] neg_lo:[1,0,0] neg_hi:[1,0,0]
	v_pk_fma_f32 v[16:17], v[70:71], v[22:23], v[42:43] neg_lo:[1,0,0] neg_hi:[1,0,0]
	v_pk_fma_f32 v[20:21], v[68:69], v[20:21], v[48:49] neg_lo:[1,0,0] neg_hi:[1,0,0]
	v_lshlrev_b32_e32 v22, 16, v132
	v_and_b32_e32 v23, 0xffff0000, v132
	v_lshlrev_b32_e32 v48, 16, v134
	v_and_b32_e32 v49, 0xffff0000, v134
	v_lshlrev_b32_e32 v42, 16, v135
	v_and_b32_e32 v43, 0xffff0000, v135
	v_pk_fma_f32 v[8:9], v[68:69], v[8:9], v[22:23] neg_lo:[1,0,0] neg_hi:[1,0,0]
	v_mov_b32_e32 v22, v210
	v_pk_fma_f32 v[2:3], v[70:71], v[2:3], v[42:43] neg_lo:[1,0,0] neg_hi:[1,0,0]
	v_lshlrev_b32_e32 v40, 16, v133
	v_ashrrev_i32_e32 v43, 6, v22
	v_and_b32_e32 v41, 0xffff0000, v133
	v_pk_fma_f32 v[0:1], v[68:69], v[0:1], v[48:49] neg_lo:[1,0,0] neg_hi:[1,0,0]
	v_and_b32_e32 v48, 15, v22
	v_mul_lo_u32 v23, v43, s0
	v_readlane_b32 s0, v255, 61
	v_pk_fma_f32 v[10:11], v[70:71], v[10:11], v[40:41] neg_lo:[1,0,0] neg_hi:[1,0,0]
	v_lshlrev_b32_e32 v40, 2, v48
	v_readlane_b32 s1, v255, 62
	v_bfe_u32 v42, v22, 4, 2
	v_add_u32_e32 v57, 0, v23
	v_lshlrev_b32_e32 v70, 1, v48
	v_mov_b32_e32 v22, v74
	v_mov_b32_e32 v23, v76
	global_load_dword v96, v40, s[0:1]
	global_load_dword v97, v40, s[0:1] offset:64
	global_load_dword v98, v40, s[0:1] offset:128
	global_load_dword v99, v40, s[0:1] offset:192
	global_load_dword v100, v40, s[0:1] offset:256
	global_load_dword v101, v40, s[0:1] offset:320
	global_load_dword v102, v40, s[0:1] offset:384
	global_load_dword v103, v40, s[0:1] offset:448
	v_pk_mul_f32 v[22:23], v[22:23], v[22:23]
	v_lshlrev_b32_e32 v192, 4, v48
	v_mov_b32_e32 v95, v22
	s_waitcnt vmcnt(0)
; DEV bf16_t f2bf(float f) { unsigned u = __float_as_uint(f); u += 0x7fffu + ((u >> 16) & 1u); return (bf16_t)(u >> 16); }
; DEV void attn_store16(f32x4 (&o)[2][8], const float* __restrict__ gain, float oscale, bf16_t* __restrict__ mix, int q0, int colbase) {
;     ...
;   float gn[8];
; #pragma unroll
;   for (int cb = 0; cb < 8; ++cb) gn[cb] = gain[16 * cb + fr] * oscale;
; #pragma unroll
;   for (int g = 0; g < 2; ++g)
; #pragma unroll
;     for (int j = 0; j < 4; ++j) {
;       float ss = 0.f;
; #pragma unroll
;       for (int cb = 0; cb < 8; ++cb) ss += o[g][cb][j] * o[g][cb][j];
;       ss += __shfl_xor(ss, 1); ss += __shfl_xor(ss, 2); ss += __shfl_xor(ss, 4); ss += __shfl_xor(ss, 8);
;       const float rn = rsqrtf(ss * (1.f / 128.f) + EPS);
;       const int sl = 16 * g + 4 * fq + j;
; #pragma unroll
;       for (int cb = 0; cb < 8; ++cb) *reinterpret_cast<bf16_t*>(sc + sl * 272 + (16 * cb + fr) * 2) = f2bf(o[g][cb][j] * rn * gn[cb]);
	v_mul_f32_e32 v49, v222, v96
	v_mul_f32_e32 v50, v222, v97
	v_mul_f32_e32 v51, v222, v98
	v_mul_f32_e32 v56, v222, v99
	v_mul_f32_e32 v58, v222, v100
	v_mul_f32_e32 v59, v222, v101
	v_mul_f32_e32 v68, v222, v102
	v_mov_b32_e32 v41, v66
	s_mov_b32 s0, 0x358637bd
	v_mul_f32_e32 v69, v222, v103
	v_mov_b32_e32 v40, v64
	v_pk_mul_f32 v[82:83], v[40:41], v[40:41]
	v_mov_b32_e32 v40, v78
	v_mov_b32_e32 v41, v80
	v_pk_mul_f32 v[84:85], v[40:41], v[40:41]
	v_mul_u32_u24_e32 v40, 0x440, v42
	v_add3_u32 v70, v57, v70, v40
	v_mov_b32_e32 v40, v75
	v_mov_b32_e32 v41, v77
	v_pk_mul_f32 v[86:87], v[40:41], v[40:41]
	v_pk_mul_f32 v[40:41], v[28:29], v[28:29]
	v_mov_b32_e32 v22, v87
	v_mov_b32_e32 v94, v86
	v_pk_add_f32 v[22:23], v[88:89], v[22:23] op_sel:[1,0] op_sel_hi:[0,1]
	v_pk_add_f32 v[22:23], v[94:95], v[22:23]
	v_mov_b32_e32 v86, v91
	v_mov_b32_e32 v87, v83
	v_pk_add_f32 v[22:23], v[86:87], v[22:23]
	v_mov_b32_e32 v91, v82
	v_pk_add_f32 v[22:23], v[90:91], v[22:23]
	v_mov_b32_e32 v82, v93
	v_mov_b32_e32 v83, v85
	v_pk_add_f32 v[22:23], v[82:83], v[22:23]
	v_mov_b32_e32 v93, v84
	v_pk_add_f32 v[22:23], v[92:93], v[22:23]
	ds_bpermute_b32 v83, v221, v23
	ds_bpermute_b32 v82, v221, v22
	v_pk_fma_f32 v[40:41], v[30:31], v[30:31], v[40:41]
	s_waitcnt lgkmcnt(0)
	v_pk_add_f32 v[22:23], v[22:23], v[82:83]
	ds_bpermute_b32 v83, v220, v23
	ds_bpermute_b32 v82, v220, v22
	s_waitcnt lgkmcnt(0)
	v_pk_add_f32 v[22:23], v[22:23], v[82:83]
	ds_bpermute_b32 v83, v219, v23
	ds_bpermute_b32 v82, v219, v22
	s_waitcnt lgkmcnt(0)
	v_pk_add_f32 v[22:23], v[22:23], v[82:83]
	ds_bpermute_b32 v83, v218, v23
	ds_bpermute_b32 v82, v218, v22
	s_waitcnt lgkmcnt(0)
	v_pk_add_f32 v[82:83], v[22:23], v[82:83]
	v_mov_b64_e32 v[22:23], s[0:1]
	v_pk_fma_f32 v[82:83], v[82:83], s[4:5], v[22:23] op_sel_hi:[1,0,0]
	s_nop 0
	v_mul_f32_e32 v71, 0x4b800000, v83
	v_cmp_gt_f32_e64 s[0:1], s33, v83
	v_cmp_gt_f32_e32 vcc, s33, v82
	s_nop 0
	v_cndmask_b32_e64 v71, v83, v71, s[0:1]
	v_rsq_f32_e32 v71, v71
	s_nop 0
	v_mul_f32_e32 v83, 0x45800000, v71
	v_cndmask_b32_e64 v71, v71, v83, s[0:1]
	v_mul_f32_e32 v72, v72, v71
	v_mul_f32_e32 v72, v49, v72
	v_bfe_u32 v83, v72, 16, 1
	v_mul_f32_e32 v62, v62, v71
	v_add3_u32 v72, v72, v83, s2
	v_mul_f32_e32 v62, v50, v62
	ds_write_b16_d16_hi v70, v72
	v_bfe_u32 v72, v62, 16, 1
	v_add3_u32 v62, v62, v72, s2
	ds_write_b16_d16_hi v70, v62 offset:32
	v_mul_f32_e32 v62, v76, v71
	v_mul_f32_e32 v62, v51, v62
	v_bfe_u32 v72, v62, 16, 1
	v_add3_u32 v62, v62, v72, s2
	ds_write_b16_d16_hi v70, v62 offset:64
	v_mul_f32_e32 v62, v74, v71
	v_mul_f32_e32 v62, v56, v62
	v_bfe_u32 v72, v62, 16, 1
	v_add3_u32 v62, v62, v72, s2
	ds_write_b16_d16_hi v70, v62 offset:96
	v_mul_f32_e32 v62, v66, v71
	v_mul_f32_e32 v62, v58, v62
	v_bfe_u32 v66, v62, 16, 1
	v_add3_u32 v62, v62, v66, s2
	ds_write_b16_d16_hi v70, v62 offset:128
	v_mul_f32_e32 v62, v64, v71
	v_mul_f32_e32 v62, v59, v62
	v_bfe_u32 v64, v62, 16, 1
	v_add3_u32 v62, v62, v64, s2
	ds_write_b16_d16_hi v70, v62 offset:160
	v_mul_f32_e32 v62, v80, v71
	v_mul_f32_e32 v62, v68, v62
	v_bfe_u32 v64, v62, 16, 1
	v_add3_u32 v62, v62, v64, s2
	ds_write_b16_d16_hi v70, v62 offset:192
	v_mul_f32_e32 v62, v78, v71
	v_mul_f32_e32 v62, v69, v62
	v_bfe_u32 v64, v62, 16, 1
	v_add3_u32 v62, v62, v64, s2
	ds_write_b16_d16_hi v70, v62 offset:224
	v_mul_f32_e32 v62, 0x4b800000, v82
	v_cndmask_b32_e32 v62, v82, v62, vcc
	v_rsq_f32_e32 v62, v62
	v_mov_b32_e32 v72, v39
	v_mov_b32_e32 v74, v45
	v_mov_b32_e32 v76, v55
	v_mul_f32_e32 v64, 0x45800000, v62
	v_cndmask_b32_e32 v62, v62, v64, vcc
	v_mul_f32_e32 v64, v73, v62
	v_mul_f32_e32 v64, v49, v64
	v_bfe_u32 v66, v64, 16, 1
	v_mul_f32_e32 v63, v63, v62
	v_add3_u32 v64, v64, v66, s2
	v_mul_f32_e32 v63, v50, v63
	ds_write_b16_d16_hi v70, v64 offset:272
	v_bfe_u32 v64, v63, 16, 1
	v_add3_u32 v63, v63, v64, s2
	ds_write_b16_d16_hi v70, v63 offset:304
	v_mul_f32_e32 v63, v77, v62
	v_mul_f32_e32 v63, v51, v63
	v_bfe_u32 v64, v63, 16, 1
	v_add3_u32 v63, v63, v64, s2
	ds_write_b16_d16_hi v70, v63 offset:336
	v_mul_f32_e32 v63, v75, v62
	v_mul_f32_e32 v63, v56, v63
	v_bfe_u32 v64, v63, 16, 1
	v_add3_u32 v63, v63, v64, s2
	ds_write_b16_d16_hi v70, v63 offset:368
	v_mul_f32_e32 v63, v67, v62
	v_mul_f32_e32 v63, v58, v63
	v_bfe_u32 v64, v63, 16, 1
	v_add3_u32 v63, v63, v64, s2
	ds_write_b16_d16_hi v70, v63 offset:400
	v_mul_f32_e32 v63, v65, v62
	v_mul_f32_e32 v63, v59, v63
	v_bfe_u32 v64, v63, 16, 1
	v_add3_u32 v63, v63, v64, s2
	ds_write_b16_d16_hi v70, v63 offset:432
	v_mul_f32_e32 v63, v81, v62
	v_mul_f32_e32 v63, v68, v63
	v_bfe_u32 v64, v63, 16, 1
	v_mul_f32_e32 v62, v79, v62
	v_add3_u32 v63, v63, v64, s2
	v_mul_f32_e32 v62, v69, v62
	ds_write_b16_d16_hi v70, v63 offset:464
	v_bfe_u32 v63, v62, 16, 1
	v_add3_u32 v62, v62, v63, s2
	ds_write_b16_d16_hi v70, v62 offset:496
	v_mov_b32_e32 v62, v38
	v_mov_b32_e32 v63, v46
	v_mov_b32_e32 v73, v47
	v_pk_mul_f32 v[62:63], v[62:63], v[62:63]
	v_pk_mul_f32 v[72:73], v[72:73], v[72:73]
	v_mov_b32_e32 v64, v44
	v_mov_b32_e32 v65, v52
	v_mov_b32_e32 v75, v53
	v_mov_b32_e32 v79, v62
	v_mov_b32_e32 v62, v73
	v_pk_mul_f32 v[64:65], v[64:65], v[64:65]
	v_pk_mul_f32 v[74:75], v[74:75], v[74:75]
	v_mov_b32_e32 v78, v72
	v_pk_add_f32 v[40:41], v[40:41], v[62:63] op_sel:[1,0] op_sel_hi:[0,1]
	v_mov_b32_e32 v66, v54
	v_mov_b32_e32 v67, v60
	v_mov_b32_e32 v77, v61
	v_pk_add_f32 v[40:41], v[78:79], v[40:41]
	v_mov_b32_e32 v62, v75
	v_mov_b32_e32 v63, v65
	v_pk_mul_f32 v[66:67], v[66:67], v[66:67]
	v_pk_mul_f32 v[76:77], v[76:77], v[76:77]
	v_pk_add_f32 v[40:41], v[62:63], v[40:41]
	v_mov_b32_e32 v75, v64
	v_pk_add_f32 v[40:41], v[74:75], v[40:41]
	v_mov_b32_e32 v62, v77
	v_mov_b32_e32 v63, v67
	v_pk_add_f32 v[40:41], v[62:63], v[40:41]
	v_mov_b32_e32 v77, v66
	v_pk_add_f32 v[40:41], v[76:77], v[40:41]
	ds_bpermute_b32 v63, v221, v41
	ds_bpermute_b32 v62, v221, v40
	s_waitcnt lgkmcnt(0)
; DEV bf16_t f2bf(float f) { unsigned u = __float_as_uint(f); u += 0x7fffu + ((u >> 16) & 1u); return (bf16_t)(u >> 16); }
; DEV void attn_store16(f32x4 (&o)[2][8], const float* __restrict__ gain, float oscale, bf16_t* __restrict__ mix, int q0, int colbase) {
;     ...
;     for (int j = 0; j < 4; ++j) {
;       float ss = 0.f;
; #pragma unroll
;       for (int cb = 0; cb < 8; ++cb) ss += o[g][cb][j] * o[g][cb][j];
;       ss += __shfl_xor(ss, 1); ss += __shfl_xor(ss, 2); ss += __shfl_xor(ss, 4); ss += __shfl_xor(ss, 8);
;       const float rn = rsqrtf(ss * (1.f / 128.f) + EPS);
;       const int sl = 16 * g + 4 * fq + j;
; #pragma unroll
;       for (int cb = 0; cb < 8; ++cb) *reinterpret_cast<bf16_t*>(sc + sl * 272 + (16 * cb + fr) * 2) = f2bf(o[g][cb][j] * rn * gn[cb]);
	v_pk_add_f32 v[40:41], v[40:41], v[62:63]
	ds_bpermute_b32 v63, v220, v41
	ds_bpermute_b32 v62, v220, v40
	s_waitcnt lgkmcnt(0)
	v_pk_add_f32 v[40:41], v[40:41], v[62:63]
	ds_bpermute_b32 v63, v219, v41
	ds_bpermute_b32 v62, v219, v40
	s_waitcnt lgkmcnt(0)
	v_pk_add_f32 v[40:41], v[40:41], v[62:63]
	ds_bpermute_b32 v63, v218, v41
	ds_bpermute_b32 v62, v218, v40
	s_waitcnt lgkmcnt(0)
	v_pk_add_f32 v[40:41], v[40:41], v[62:63]
	s_nop 0
	v_pk_fma_f32 v[40:41], v[40:41], s[4:5], v[22:23] op_sel_hi:[1,0,0]
	s_nop 0
	v_mul_f32_e32 v62, 0x4b800000, v41
	v_cmp_gt_f32_e64 s[0:1], s33, v41
	v_cmp_gt_f32_e32 vcc, s33, v40
	s_nop 0
	v_cndmask_b32_e64 v41, v41, v62, s[0:1]
	v_rsq_f32_e32 v41, v41
	s_nop 0
	v_mul_f32_e32 v62, 0x45800000, v41
	v_cndmask_b32_e64 v41, v41, v62, s[0:1]
	v_mul_f32_e32 v30, v30, v41
	v_mul_f32_e32 v30, v49, v30
	v_bfe_u32 v62, v30, 16, 1
	v_mul_f32_e32 v28, v28, v41
	v_add3_u32 v30, v30, v62, s2
	v_mul_f32_e32 v28, v50, v28
	ds_write_b16_d16_hi v70, v30 offset:544
	v_bfe_u32 v30, v28, 16, 1
	v_add3_u32 v28, v28, v30, s2
	ds_write_b16_d16_hi v70, v28 offset:576
	v_mul_f32_e32 v28, v46, v41
	v_mul_f32_e32 v28, v51, v28
	v_bfe_u32 v30, v28, 16, 1
	v_add3_u32 v28, v28, v30, s2
	ds_write_b16_d16_hi v70, v28 offset:608
	v_mul_f32_e32 v28, v38, v41
	v_mul_f32_e32 v28, v56, v28
	v_bfe_u32 v30, v28, 16, 1
	v_add3_u32 v28, v28, v30, s2
	ds_write_b16_d16_hi v70, v28 offset:640
	v_mul_f32_e32 v28, v52, v41
	v_mul_f32_e32 v28, v58, v28
	v_bfe_u32 v30, v28, 16, 1
	v_add3_u32 v28, v28, v30, s2
	ds_write_b16_d16_hi v70, v28 offset:672
	v_mul_f32_e32 v28, v44, v41
	v_mul_f32_e32 v28, v59, v28
	v_bfe_u32 v30, v28, 16, 1
	v_add3_u32 v28, v28, v30, s2
	ds_write_b16_d16_hi v70, v28 offset:704
	v_mul_f32_e32 v28, v60, v41
	v_mul_f32_e32 v28, v68, v28
	v_bfe_u32 v30, v28, 16, 1
	v_add3_u32 v28, v28, v30, s2
	ds_write_b16_d16_hi v70, v28 offset:736
	v_mul_f32_e32 v28, v54, v41
	v_mul_f32_e32 v28, v69, v28
	v_bfe_u32 v30, v28, 16, 1
	v_add3_u32 v28, v28, v30, s2
	ds_write_b16_d16_hi v70, v28 offset:768
	v_mul_f32_e32 v28, 0x4b800000, v40
	v_cndmask_b32_e32 v28, v40, v28, vcc
	v_rsq_f32_e32 v28, v28
	v_mov_b32_e32 v52, v21
	v_mov_b32_e32 v54, v1
	v_mul_f32_e32 v30, 0x45800000, v28
	v_cndmask_b32_e32 v28, v28, v30, vcc
	v_mul_f32_e32 v30, v31, v28
	v_mul_f32_e32 v30, v49, v30
	v_bfe_u32 v31, v30, 16, 1
	v_mul_f32_e32 v29, v29, v28
	v_add3_u32 v30, v30, v31, s2
	v_mul_f32_e32 v29, v50, v29
	ds_write_b16_d16_hi v70, v30 offset:816
	v_bfe_u32 v30, v29, 16, 1
	v_add3_u32 v29, v29, v30, s2
	ds_write_b16_d16_hi v70, v29 offset:848
	v_mul_f32_e32 v29, v47, v28
	v_mul_f32_e32 v29, v51, v29
	v_bfe_u32 v30, v29, 16, 1
	v_add3_u32 v29, v29, v30, s2
	ds_write_b16_d16_hi v70, v29 offset:880
	v_mul_f32_e32 v29, v39, v28
	v_mul_f32_e32 v29, v56, v29
	v_bfe_u32 v30, v29, 16, 1
	v_add3_u32 v29, v29, v30, s2
	ds_write_b16_d16_hi v70, v29 offset:912
	v_mul_f32_e32 v29, v53, v28
	v_mul_f32_e32 v29, v58, v29
	v_bfe_u32 v30, v29, 16, 1
	v_add3_u32 v29, v29, v30, s2
	ds_write_b16_d16_hi v70, v29 offset:944
	v_mul_f32_e32 v29, v45, v28
	v_mul_f32_e32 v29, v59, v29
	v_bfe_u32 v30, v29, 16, 1
	v_add3_u32 v29, v29, v30, s2
	ds_write_b16_d16_hi v70, v29 offset:976
	v_mul_f32_e32 v29, v61, v28
	v_mul_f32_e32 v29, v68, v29
	v_bfe_u32 v30, v29, 16, 1
	v_mul_f32_e32 v28, v55, v28
	v_add3_u32 v29, v29, v30, s2
	v_mul_f32_e32 v28, v69, v28
	ds_write_b16_d16_hi v70, v29 offset:1008
	v_bfe_u32 v29, v28, 16, 1
	v_add3_u32 v28, v28, v29, s2
	ds_write_b16_d16_hi v70, v28 offset:1040
	v_mov_b32_e32 v28, v32
	v_mov_b32_e32 v29, v36
	v_pk_mul_f32 v[30:31], v[28:29], v[28:29]
	v_mov_b32_e32 v28, v20
	v_mov_b32_e32 v29, v34
	v_pk_mul_f32 v[38:39], v[28:29], v[28:29]
	v_mov_b32_e32 v28, v0
	v_mov_b32_e32 v29, v8
	v_pk_mul_f32 v[40:41], v[28:29], v[28:29]
	v_mov_b32_e32 v28, v33
	v_mov_b32_e32 v29, v37
	v_pk_mul_f32 v[44:45], v[28:29], v[28:29]
	v_pk_mul_f32 v[46:47], v[24:25], v[24:25]
	v_mov_b32_e32 v53, v35
	v_pk_fma_f32 v[46:47], v[26:27], v[26:27], v[46:47]
	v_mov_b32_e32 v61, v30
	v_mov_b32_e32 v30, v45
	v_pk_mul_f32 v[52:53], v[52:53], v[52:53]
	v_mov_b32_e32 v60, v44
	v_pk_add_f32 v[30:31], v[46:47], v[30:31] op_sel:[1,0] op_sel_hi:[0,1]
	v_mov_b32_e32 v55, v9
	v_pk_add_f32 v[30:31], v[60:61], v[30:31]
	v_mov_b32_e32 v44, v53
	v_mov_b32_e32 v45, v39
	v_pk_mul_f32 v[54:55], v[54:55], v[54:55]
	v_pk_add_f32 v[30:31], v[44:45], v[30:31]
	v_mov_b32_e32 v53, v38
	v_pk_add_f32 v[30:31], v[52:53], v[30:31]
	v_mov_b32_e32 v38, v55
	v_mov_b32_e32 v39, v41
	v_pk_add_f32 v[30:31], v[38:39], v[30:31]
	v_mov_b32_e32 v55, v40
	v_pk_add_f32 v[30:31], v[54:55], v[30:31]
	ds_bpermute_b32 v39, v221, v31
	ds_bpermute_b32 v38, v221, v30
	v_pk_mul_f32 v[28:29], v[4:5], v[4:5]
	s_waitcnt lgkmcnt(0)
	v_pk_add_f32 v[30:31], v[30:31], v[38:39]
	ds_bpermute_b32 v39, v220, v31
	ds_bpermute_b32 v38, v220, v30
	v_pk_fma_f32 v[28:29], v[6:7], v[6:7], v[28:29]
	s_waitcnt lgkmcnt(0)
	v_pk_add_f32 v[30:31], v[30:31], v[38:39]
	ds_bpermute_b32 v39, v219, v31
	ds_bpermute_b32 v38, v219, v30
	s_waitcnt lgkmcnt(0)
	v_pk_add_f32 v[30:31], v[30:31], v[38:39]
	ds_bpermute_b32 v39, v218, v31
	ds_bpermute_b32 v38, v218, v30
	s_waitcnt lgkmcnt(0)
; DEV bf16_t f2bf(float f) { unsigned u = __float_as_uint(f); u += 0x7fffu + ((u >> 16) & 1u); return (bf16_t)(u >> 16); }
; DEV void attn_store16(f32x4 (&o)[2][8], const float* __restrict__ gain, float oscale, bf16_t* __restrict__ mix, int q0, int colbase) {
;     ...
;     for (int j = 0; j < 4; ++j) {
;       float ss = 0.f;
; #pragma unroll
;       for (int cb = 0; cb < 8; ++cb) ss += o[g][cb][j] * o[g][cb][j];
;       ss += __shfl_xor(ss, 1); ss += __shfl_xor(ss, 2); ss += __shfl_xor(ss, 4); ss += __shfl_xor(ss, 8);
;       const float rn = rsqrtf(ss * (1.f / 128.f) + EPS);
;       const int sl = 16 * g + 4 * fq + j;
; #pragma unroll
;       for (int cb = 0; cb < 8; ++cb) *reinterpret_cast<bf16_t*>(sc + sl * 272 + (16 * cb + fr) * 2) = f2bf(o[g][cb][j] * rn * gn[cb]);
	v_pk_add_f32 v[30:31], v[30:31], v[38:39]
	s_nop 0
	v_pk_fma_f32 v[30:31], v[30:31], s[4:5], v[22:23] op_sel_hi:[1,0,0]
	s_nop 0
	v_mul_f32_e32 v38, 0x4b800000, v31
	v_cmp_gt_f32_e64 s[0:1], s33, v31
	v_cmp_gt_f32_e32 vcc, s33, v30
	s_nop 0
	v_cndmask_b32_e64 v31, v31, v38, s[0:1]
	v_rsq_f32_e32 v31, v31
	s_nop 0
	v_mul_f32_e32 v38, 0x45800000, v31
	v_cndmask_b32_e64 v31, v31, v38, s[0:1]
	v_mul_f32_e32 v26, v26, v31
	v_mul_f32_e32 v26, v49, v26
	v_bfe_u32 v38, v26, 16, 1
	v_mul_f32_e32 v24, v24, v31
	v_add3_u32 v26, v26, v38, s2
	v_mul_f32_e32 v24, v50, v24
	ds_write_b16_d16_hi v70, v26 offset:4352
	v_bfe_u32 v26, v24, 16, 1
	v_add3_u32 v24, v24, v26, s2
	ds_write_b16_d16_hi v70, v24 offset:4384
	v_mul_f32_e32 v24, v36, v31
	v_mul_f32_e32 v24, v51, v24
	v_bfe_u32 v26, v24, 16, 1
	v_add3_u32 v24, v24, v26, s2
	ds_write_b16_d16_hi v70, v24 offset:4416
	v_mul_f32_e32 v24, v32, v31
	v_mul_f32_e32 v24, v56, v24
	v_bfe_u32 v26, v24, 16, 1
	v_add3_u32 v24, v24, v26, s2
	ds_write_b16_d16_hi v70, v24 offset:4448
	v_mul_f32_e32 v24, v34, v31
	v_mul_f32_e32 v24, v58, v24
	v_bfe_u32 v26, v24, 16, 1
	v_mul_f32_e32 v20, v20, v31
	v_add3_u32 v24, v24, v26, s2
	v_mul_f32_e32 v20, v59, v20
	ds_write_b16_d16_hi v70, v24 offset:4480
	v_bfe_u32 v24, v20, 16, 1
	v_mul_f32_e32 v8, v8, v31
	v_add3_u32 v20, v20, v24, s2
	v_mul_f32_e32 v8, v68, v8
	ds_write_b16_d16_hi v70, v20 offset:4512
	v_bfe_u32 v20, v8, 16, 1
	v_mul_f32_e32 v0, v0, v31
	v_add3_u32 v8, v8, v20, s2
	v_mul_f32_e32 v0, v69, v0
	ds_write_b16_d16_hi v70, v8 offset:4544
	v_bfe_u32 v8, v0, 16, 1
	v_add3_u32 v0, v0, v8, s2
	ds_write_b16_d16_hi v70, v0 offset:4576
	v_mul_f32_e32 v0, 0x4b800000, v30
	v_cndmask_b32_e32 v0, v30, v0, vcc
	v_rsq_f32_e32 v0, v0
	v_mov_b32_e32 v24, v13
	v_mov_b32_e32 v26, v17
	v_mov_b32_e32 v30, v3
	v_mul_f32_e32 v8, 0x45800000, v0
	v_cndmask_b32_e32 v0, v0, v8, vcc
	v_mul_f32_e32 v8, v27, v0
	v_mul_f32_e32 v8, v49, v8
	v_bfe_u32 v20, v8, 16, 1
	v_add3_u32 v8, v8, v20, s2
	ds_write_b16_d16_hi v70, v8 offset:4624
	v_mul_f32_e32 v8, v25, v0
	v_mul_f32_e32 v8, v50, v8
	v_bfe_u32 v20, v8, 16, 1
	v_add3_u32 v8, v8, v20, s2
	ds_write_b16_d16_hi v70, v8 offset:4656
	v_mul_f32_e32 v8, v37, v0
	v_mul_f32_e32 v8, v51, v8
	v_bfe_u32 v20, v8, 16, 1
	v_add3_u32 v8, v8, v20, s2
	ds_write_b16_d16_hi v70, v8 offset:4688
	v_mul_f32_e32 v8, v33, v0
	v_mul_f32_e32 v8, v56, v8
	v_bfe_u32 v20, v8, 16, 1
	v_add3_u32 v8, v8, v20, s2
	ds_write_b16_d16_hi v70, v8 offset:4720
	v_mul_f32_e32 v8, v35, v0
	v_mul_f32_e32 v8, v58, v8
	v_bfe_u32 v20, v8, 16, 1
	v_add3_u32 v8, v8, v20, s2
	ds_write_b16_d16_hi v70, v8 offset:4752
	v_mul_f32_e32 v8, v21, v0
	v_mul_f32_e32 v8, v59, v8
	v_bfe_u32 v20, v8, 16, 1
	v_add3_u32 v8, v8, v20, s2
	ds_write_b16_d16_hi v70, v8 offset:4784
	v_mul_f32_e32 v8, v9, v0
	v_mul_f32_e32 v0, v1, v0
	v_mul_f32_e32 v0, v69, v0
	v_bfe_u32 v1, v0, 16, 1
	v_mul_f32_e32 v8, v68, v8
	v_add3_u32 v0, v0, v1, s2
	v_bfe_u32 v9, v8, 16, 1
	ds_write_b16_d16_hi v70, v0 offset:4848
	v_mov_b32_e32 v0, v12
	v_mov_b32_e32 v1, v14
	v_mov_b32_e32 v25, v15
	v_add3_u32 v8, v8, v9, s2
	v_pk_mul_f32 v[0:1], v[0:1], v[0:1]
	v_pk_mul_f32 v[24:25], v[24:25], v[24:25]
	ds_write_b16_d16_hi v70, v8 offset:4816
	v_mov_b32_e32 v8, v16
	v_mov_b32_e32 v9, v18
	v_mov_b32_e32 v27, v19
	v_mov_b32_e32 v33, v0
	v_mov_b32_e32 v0, v25
	v_pk_mul_f32 v[8:9], v[8:9], v[8:9]
	v_pk_mul_f32 v[26:27], v[26:27], v[26:27]
	v_mov_b32_e32 v32, v24
	v_pk_add_f32 v[0:1], v[28:29], v[0:1] op_sel:[1,0] op_sel_hi:[0,1]
	v_mov_b32_e32 v20, v2
	v_mov_b32_e32 v21, v10
	v_mov_b32_e32 v31, v11
	v_pk_add_f32 v[0:1], v[32:33], v[0:1]
	v_mov_b32_e32 v24, v27
	v_mov_b32_e32 v25, v9
	v_pk_mul_f32 v[20:21], v[20:21], v[20:21]
	v_pk_mul_f32 v[30:31], v[30:31], v[30:31]
	v_pk_add_f32 v[0:1], v[24:25], v[0:1]
	v_mov_b32_e32 v27, v8
	v_pk_add_f32 v[0:1], v[26:27], v[0:1]
	v_mov_b32_e32 v8, v31
	v_mov_b32_e32 v9, v21
	v_pk_add_f32 v[0:1], v[8:9], v[0:1]
	v_mov_b32_e32 v31, v20
	v_pk_add_f32 v[0:1], v[30:31], v[0:1]
	ds_bpermute_b32 v9, v221, v1
	ds_bpermute_b32 v8, v221, v0
	s_waitcnt lgkmcnt(0)
	v_pk_add_f32 v[0:1], v[0:1], v[8:9]
	ds_bpermute_b32 v9, v220, v1
	ds_bpermute_b32 v8, v220, v0
	s_waitcnt lgkmcnt(0)
	v_pk_add_f32 v[0:1], v[0:1], v[8:9]
	ds_bpermute_b32 v9, v219, v1
	ds_bpermute_b32 v8, v219, v0
	s_waitcnt lgkmcnt(0)
	v_pk_add_f32 v[0:1], v[0:1], v[8:9]
	ds_bpermute_b32 v9, v218, v1
	ds_bpermute_b32 v8, v218, v0
	s_waitcnt lgkmcnt(0)
; DEV bf16_t f2bf(float f) { unsigned u = __float_as_uint(f); u += 0x7fffu + ((u >> 16) & 1u); return (bf16_t)(u >> 16); }
; DEV void attn_store16(f32x4 (&o)[2][8], const float* __restrict__ gain, float oscale, bf16_t* __restrict__ mix, int q0, int colbase) {
;     ...
;     for (int j = 0; j < 4; ++j) {
;       float ss = 0.f;
; #pragma unroll
;       for (int cb = 0; cb < 8; ++cb) ss += o[g][cb][j] * o[g][cb][j];
;       ss += __shfl_xor(ss, 1); ss += __shfl_xor(ss, 2); ss += __shfl_xor(ss, 4); ss += __shfl_xor(ss, 8);
;       const float rn = rsqrtf(ss * (1.f / 128.f) + EPS);
;       const int sl = 16 * g + 4 * fq + j;
; #pragma unroll
;       for (int cb = 0; cb < 8; ++cb) *reinterpret_cast<bf16_t*>(sc + sl * 272 + (16 * cb + fr) * 2) = f2bf(o[g][cb][j] * rn * gn[cb]);
;     }
; #pragma unroll
;   for (int i = 0; i < 8; ++i) { const int rs = 4 * i + (lane >> 4);
;     const u32x4 w = *reinterpret_cast<const u32x4*>(sc + rs * 272 + (lane & 15) * 16);
;     const size_t row = (size_t)(q0 + 64 * (rs >> 3) + 8 * wid + (rs & 7));
;     *reinterpret_cast<u32x4*>(mix + row * DM + colbase + (lane & 15) * 8) = w; }
;   __syncthreads();
	v_pk_add_f32 v[0:1], v[0:1], v[8:9]
	s_nop 0
	v_pk_fma_f32 v[0:1], v[0:1], s[4:5], v[22:23] op_sel_hi:[1,0,0]
	s_nop 0
	v_mul_f32_e32 v8, 0x4b800000, v1
	v_cmp_gt_f32_e64 s[0:1], s33, v1
	v_cmp_gt_f32_e32 vcc, s33, v0
	s_nop 0
	v_cndmask_b32_e64 v1, v1, v8, s[0:1]
	v_rsq_f32_e32 v1, v1
	s_nop 0
	v_mul_f32_e32 v8, 0x45800000, v1
	v_cndmask_b32_e64 v1, v1, v8, s[0:1]
	v_mul_f32_e32 v6, v6, v1
	v_mul_f32_e32 v6, v49, v6
	v_bfe_u32 v8, v6, 16, 1
	v_mul_f32_e32 v4, v4, v1
	v_add3_u32 v6, v6, v8, s2
	v_mul_f32_e32 v4, v50, v4
	ds_write_b16_d16_hi v70, v6 offset:4896
	v_bfe_u32 v6, v4, 16, 1
	v_add3_u32 v4, v4, v6, s2
	ds_write_b16_d16_hi v70, v4 offset:4928
	v_mul_f32_e32 v4, v14, v1
	v_mul_f32_e32 v4, v51, v4
	v_bfe_u32 v6, v4, 16, 1
	v_add3_u32 v4, v4, v6, s2
	ds_write_b16_d16_hi v70, v4 offset:4960
	v_mul_f32_e32 v4, v12, v1
	v_mul_f32_e32 v4, v56, v4
	v_bfe_u32 v6, v4, 16, 1
	v_add3_u32 v4, v4, v6, s2
	ds_write_b16_d16_hi v70, v4 offset:4992
	v_mul_f32_e32 v4, v18, v1
	v_mul_f32_e32 v4, v58, v4
	v_bfe_u32 v6, v4, 16, 1
	v_add3_u32 v4, v4, v6, s2
	ds_write_b16_d16_hi v70, v4 offset:5024
	v_mul_f32_e32 v4, v16, v1
	v_mul_f32_e32 v4, v59, v4
	v_bfe_u32 v6, v4, 16, 1
	v_add3_u32 v4, v4, v6, s2
	ds_write_b16_d16_hi v70, v4 offset:5056
	v_mul_f32_e32 v4, v10, v1
	v_mul_f32_e32 v1, v2, v1
	v_mul_f32_e32 v1, v69, v1
	v_bfe_u32 v2, v1, 16, 1
	v_add3_u32 v1, v1, v2, s2
	ds_write_b16_d16_hi v70, v1 offset:5120
	v_mul_f32_e32 v1, 0x4b800000, v0
	v_cndmask_b32_e32 v0, v0, v1, vcc
	v_rsq_f32_e32 v0, v0
	v_mul_f32_e32 v4, v68, v4
	v_bfe_u32 v6, v4, 16, 1
	v_add3_u32 v4, v4, v6, s2
	v_mul_f32_e32 v1, 0x45800000, v0
	v_cndmask_b32_e32 v0, v0, v1, vcc
	v_mul_f32_e32 v1, v7, v0
	v_mul_f32_e32 v1, v49, v1
	v_bfe_u32 v2, v1, 16, 1
	v_add3_u32 v1, v1, v2, s2
	ds_write_b16_d16_hi v70, v1 offset:5168
	v_mul_f32_e32 v1, v5, v0
	v_mul_f32_e32 v1, v50, v1
	v_bfe_u32 v2, v1, 16, 1
	v_add3_u32 v1, v1, v2, s2
	ds_write_b16_d16_hi v70, v1 offset:5200
	v_mul_f32_e32 v1, v15, v0
	v_mul_f32_e32 v1, v51, v1
	v_bfe_u32 v2, v1, 16, 1
	v_add3_u32 v1, v1, v2, s2
	ds_write_b16_d16_hi v70, v1 offset:5232
	v_mul_f32_e32 v1, v13, v0
	v_mul_f32_e32 v1, v56, v1
	v_bfe_u32 v2, v1, 16, 1
	v_add3_u32 v1, v1, v2, s2
	ds_write_b16_d16_hi v70, v1 offset:5264
	v_mul_f32_e32 v1, v19, v0
	v_mul_f32_e32 v1, v58, v1
	v_bfe_u32 v2, v1, 16, 1
	v_add3_u32 v1, v1, v2, s2
	ds_write_b16_d16_hi v70, v1 offset:5296
	v_mul_f32_e32 v1, v17, v0
	v_mul_f32_e32 v1, v59, v1
	v_bfe_u32 v2, v1, 16, 1
	v_add3_u32 v1, v1, v2, s2
	ds_write_b16_d16_hi v70, v1 offset:5328
	v_mul_f32_e32 v1, v11, v0
	v_mul_f32_e32 v1, v68, v1
	v_bfe_u32 v2, v1, 16, 1
	v_mul_f32_e32 v0, v3, v0
	v_add3_u32 v1, v1, v2, s2
	v_mul_f32_e32 v0, v69, v0
	ds_write_b16_d16_hi v70, v1 offset:5360
	v_bfe_u32 v1, v0, 16, 1
	v_add3_u32 v0, v0, v1, s2
	ds_write_b16_d16_hi v70, v0 offset:5392
	v_mul_u32_u24_e32 v0, 0x110, v42
	ds_write_b16_d16_hi v70, v4 offset:5088
	v_add3_u32 v9, v57, v192, v0
	v_lshl_add_u32 v8, v43, 3, s74
	ds_read_b128 v[0:3], v9
	v_readlane_b32 s0, v255, 47
	v_or_b32_e32 v6, v8, v42
	v_readlane_b32 s1, v255, 48
	v_ashrrev_i32_e32 v7, 31, v6
	v_lshlrev_b64 v[6:7], 12, v[6:7]
	v_lshl_add_u64 v[4:5], s[0:1], 0, v[192:193]
	v_lshl_add_u64 v[6:7], v[4:5], 0, v[6:7]
	s_waitcnt lgkmcnt(0)
	global_store_dwordx4 v[6:7], v[0:3], off offset:2048
	v_or_b32_e32 v10, 4, v42
	ds_read_b128 v[0:3], v9 offset:1088
	v_or_b32_e32 v6, v8, v10
	v_ashrrev_i32_e32 v7, 31, v6
	v_lshlrev_b64 v[6:7], 12, v[6:7]
	v_lshl_add_u64 v[6:7], v[4:5], 0, v[6:7]
	s_waitcnt lgkmcnt(0)
	global_store_dwordx4 v[6:7], v[0:3], off offset:2048
	ds_read_b128 v[0:3], v9 offset:2176
	v_add_u32_e32 v11, 64, v8
	v_or_b32_e32 v6, v11, v42
	v_ashrrev_i32_e32 v7, 31, v6
	v_lshlrev_b64 v[6:7], 12, v[6:7]
	v_lshl_add_u64 v[6:7], v[4:5], 0, v[6:7]
	s_waitcnt lgkmcnt(0)
	global_store_dwordx4 v[6:7], v[0:3], off offset:2048
	ds_read_b128 v[0:3], v9 offset:3264
	v_or_b32_e32 v6, v11, v10
	v_ashrrev_i32_e32 v7, 31, v6
	v_lshlrev_b64 v[6:7], 12, v[6:7]
	v_lshl_add_u64 v[6:7], v[4:5], 0, v[6:7]
	s_waitcnt lgkmcnt(0)
	global_store_dwordx4 v[6:7], v[0:3], off offset:2048
	ds_read_b128 v[0:3], v9 offset:4352
	v_add_u32_e32 v11, 0x80, v8
	v_or_b32_e32 v6, v11, v42
	v_ashrrev_i32_e32 v7, 31, v6
	v_lshlrev_b64 v[6:7], 12, v[6:7]
	v_lshl_add_u64 v[6:7], v[4:5], 0, v[6:7]
	s_waitcnt lgkmcnt(0)
	global_store_dwordx4 v[6:7], v[0:3], off offset:2048
	ds_read_b128 v[0:3], v9 offset:5440
	v_or_b32_e32 v6, v11, v10
	v_ashrrev_i32_e32 v7, 31, v6
	v_lshlrev_b64 v[6:7], 12, v[6:7]
	v_lshl_add_u64 v[6:7], v[4:5], 0, v[6:7]
	s_waitcnt lgkmcnt(0)
	global_store_dwordx4 v[6:7], v[0:3], off offset:2048
	ds_read_b128 v[0:3], v9 offset:6528
	v_add_u32_e32 v8, 0xc0, v8
	v_or_b32_e32 v6, v8, v42
	v_ashrrev_i32_e32 v7, 31, v6
	v_lshlrev_b64 v[6:7], 12, v[6:7]
	v_lshl_add_u64 v[6:7], v[4:5], 0, v[6:7]
	s_waitcnt lgkmcnt(0)
	global_store_dwordx4 v[6:7], v[0:3], off offset:2048
	ds_read_b128 v[0:3], v9 offset:7616
	v_or_b32_e32 v6, v8, v10
	v_ashrrev_i32_e32 v7, 31, v6
	v_lshlrev_b64 v[6:7], 12, v[6:7]
	v_lshl_add_u64 v[4:5], v[4:5], 0, v[6:7]
	s_mov_b64 s[0:1], 0
	s_and_b64 vcc, exec, s[8:9]
	s_waitcnt lgkmcnt(0)
	global_store_dwordx4 v[4:5], v[0:3], off offset:2048
	s_barrier
	s_cbranch_vccz .LBB0_351
	s_branch .LBB0_349
